# first K-iteration after an epilogue waits vmcnt(S+2)/(S+8) instead of vmcnt(8); header vmcnt(0) removed
# speedup vs baseline: 1.0025x; 1.0025x over previous
.LBB0_130:
	s_mov_b64 s[64:65], 0x80
	s_and_b32 s90, s7, 3
	s_add_i32 m0, s77, 0x18000
	v_lshl_add_u64 v[8:9], v[8:9], 0, s[64:65]
	s_lshl_b32 s91, s8, 6
	s_lshl_b32 s1, s8, 13
	s_lshl_b32 s7, s90, 12
	s_waitcnt vmcnt(2)
	s_barrier
	global_load_lds_dwordx4 v[8:9], off
	v_lshl_add_u64 v[4:5], v[4:5], 0, s[64:65]
	s_add_i32 m0, s77, 0x1a000
	s_add_i32 s92, s77, 0x8000
	s_add_i32 s93, s77, 0xa000
	global_load_lds_dwordx4 v[4:5], off
	v_lshl_add_u64 v[2:3], v[2:3], 0, s[64:65]
	s_mov_b32 m0, s92
	s_add_u32 s8, s2, 0x40080
	global_load_lds_dwordx4 v[2:3], off
	v_lshl_add_u64 v[2:3], v[6:7], 0, s[64:65]
	s_mov_b32 m0, s93
	s_addc_u32 s9, s3, 0
	global_load_lds_dwordx4 v[2:3], off
	s_add_i32 m0, s77, 0x1c000
	v_lshl_add_u64 v[2:3], s[8:9], 0, v[166:167]
	global_load_lds_dwordx4 v[2:3], off
	v_lshl_add_u64 v[2:3], s[8:9], 0, v[174:175]
	s_add_i32 m0, s77, 0x1e000
	v_bfe_u32 v17, v0, 4, 2
	global_load_lds_dwordx4 v[2:3], off
	v_and_b32_e32 v169, 15, v0
	v_lshlrev_b32_e32 v18, 4, v17
	v_lshlrev_b32_e32 v19, 2, v0
	v_lshl_or_b32 v18, v169, 6, v18
	v_and_b32_e32 v19, 32, v19
	v_bitop3_b32 v171, v18, s7, v19 bitop3:0xde
	s_cmpk_lt_u32 s6, 0x100
	v_cmp_eq_u32_e64 s[6:7], 0, v169
	v_lshrrev_b32_e32 v3, 1, v0
	v_lshlrev_b32_e32 v2, 1, v0
	v_writelane_b32 v251, s6, 50
	v_and_b32_e32 v3, 4, v3
	v_and_b32_e32 v5, 7, v0
	v_writelane_b32 v251, s7, 51
	v_cmp_eq_u32_e64 s[6:7], 1, v169
	v_lshlrev_b32_e32 v0, 5, v17
	v_and_or_b32 v208, v2, 8, v3
	v_writelane_b32 v251, s6, 52
	v_lshlrev_b32_e32 v2, 2, v19
	v_mov_b32_e32 v3, v1
	v_writelane_b32 v251, s7, 53
	v_cmp_eq_u32_e64 s[6:7], 2, v169
	s_waitcnt vmcnt(6)
	s_mov_b32 s99, 0x7fff0000
	v_lshlrev_b32_e32 v16, 3, v17
	v_bitop3_b32 v4, v18, s1, v19 bitop3:0xde
	v_writelane_b32 v251, s6, 54
	s_cselect_b64 s[66:67], -1, 0
	s_add_i32 s61, 0, 0x10000
	v_writelane_b32 v251, s7, 55
	v_cmp_eq_u32_e64 s[6:7], 3, v169
	s_add_i32 s40, 0, 0x14000
	s_mov_b32 s82, 0x18000
	v_writelane_b32 v251, s6, 56
	s_mov_b32 s60, 0x1c000
	v_cmp_eq_u32_e64 s[50:51], 8, v169
	v_writelane_b32 v251, s7, 57
	v_cmp_eq_u32_e64 s[6:7], 4, v169
	v_cmp_eq_u32_e64 s[52:53], 9, v169
	v_cmp_eq_u32_e64 s[54:55], 10, v169
	v_writelane_b32 v251, s6, 58
	v_cmp_eq_u32_e64 s[26:27], 11, v169
	v_cmp_eq_u32_e64 s[28:29], 12, v169
	v_writelane_b32 v251, s7, 59
	v_cmp_eq_u32_e64 s[6:7], 5, v169
	v_cmp_eq_u32_e64 s[30:31], 13, v169
	v_cmp_eq_u32_e64 s[34:35], 14, v169
	v_writelane_b32 v251, s6, 60
	v_cmp_eq_u32_e64 s[36:37], 15, v169
	v_mov_b32_e32 v185, v1
	v_writelane_b32 v251, s7, 61
	v_cmp_eq_u32_e64 s[6:7], 6, v169
	v_mov_b32_e32 v187, v1
	v_mov_b64_e32 v[188:189], 0x600
	v_writelane_b32 v251, s6, 62
	v_mov_b64_e32 v[190:191], 0x5ff
	v_add_u32_e32 v209, s61, v171
	v_writelane_b32 v251, s7, 63
	v_cmp_eq_u32_e64 s[6:7], 7, v169
	v_add_u32_e32 v210, s40, v171
	v_add_u32_e32 v211, 0, v4
	v_writelane_b32 v250, s6, 0
	s_movk_i32 s41, 0x1fc3
	s_mov_b32 s8, 0x88000
	v_writelane_b32 v250, s7, 1
	v_readlane_b32 s6, v251, 41
	v_readlane_b32 s7, v251, 42
	v_writelane_b32 v250, s70, 2
	s_mov_b32 s9, 0x8c000
	v_lshl_add_u64 v[176:177], s[6:7], 0, v[0:1]
	v_readlane_b32 s6, v251, 43
	v_readlane_b32 s7, v251, 44
	v_lshl_add_u64 v[2:3], s[70:71], 0, v[2:3]
	v_lshl_add_u64 v[2:3], v[2:3], 0, v[0:1]
	v_lshl_add_u64 v[178:179], s[6:7], 0, v[0:1]
	v_lshlrev_b32_e32 v0, 2, v5
	v_lshl_add_u64 v[180:181], v[2:3], 0, v[0:1]
	v_lshlrev_b32_e32 v0, 17, v17
	v_lshl_add_u64 v[182:183], s[96:97], 0, v[0:1]
	v_lshlrev_b32_e32 v0, 14, v10
	v_and_b32_e32 v0, 0xffff8000, v0
	v_lshl_add_u32 v0, v11, 11, v0
	v_and_b32_e32 v2, 1, v10
	v_lshl_or_b32 v0, v2, 6, v0
	v_lshl_add_u32 v184, v12, 1, v0
	v_lshlrev_b32_e32 v0, 14, v13
	v_and_b32_e32 v0, 0xffff8000, v0
	v_lshl_add_u32 v0, v14, 11, v0
	v_and_b32_e32 v2, 1, v13
	v_lshl_or_b32 v0, v2, 6, v0
	v_lshl_add_u32 v186, v15, 1, v0
	v_mbcnt_lo_u32_b32 v0, -1, 0
	s_mov_b32 s6, 0x80000
	s_mov_b32 s7, 0x84000
	s_mov_b32 s10, 0x90000
	s_mov_b32 s11, 0x94000
	s_mov_b32 s42, 0x98000
	s_mov_b32 s43, 0x9c000
	v_lshlrev_b32_e32 v192, 1, v16
	v_mov_b32_e32 v212, 0x3e38aa3b
	v_mov_b32_e32 v213, 0x1000
	v_mov_b32_e32 v214, 0x1800
	v_mbcnt_hi_u32_b32 v216, -1, v0
	s_barrier
	v_writelane_b32 v250, s71, 3
	s_branch .LBB0_133

.LBB0_136:
	ds_read_b128 v[132:135], v209
	ds_read_b128 v[136:139], v209 offset:1024
	ds_read_b128 v[140:143], v209 offset:2048
	ds_read_b128 v[144:147], v209 offset:3072
	ds_read_b128 v[148:151], v210
	ds_read_b128 v[152:155], v210 offset:1024
	ds_read_b128 v[156:159], v210 offset:2048
	ds_read_b128 v[160:163], v210 offset:3072
	s_add_u32 s2, s78, 0xfffc0080
	s_addc_u32 s3, s79, -1
	s_cmp_eq_u32 s45, 12
	s_cselect_b32 s81, s1, s3
	s_cselect_b32 s80, s71, s2
	s_cselect_b32 s3, s69, s44
	s_cselect_b32 s2, vcc_lo, vcc_hi
	v_lshl_add_u64 v[2:3], s[78:79], 0, v[184:185]
	s_add_i32 m0, s77, 0xc000
	ds_read_b128 v[194:197], v211
	ds_read_b128 v[198:201], v211 offset:1024
	ds_read_b128 v[202:205], v211 offset:2048
	ds_read_b128 v[218:221], v211 offset:3072
	ds_read_b128 v[222:225], v211 offset:4096
	ds_read_b128 v[226:229], v211 offset:5120
	ds_read_b128 v[230:233], v211 offset:6144
	ds_read_b128 v[234:237], v211 offset:7168
	global_load_lds_dwordx4 v[2:3], off
	v_lshl_add_u64 v[2:3], s[78:79], 0, v[186:187]
	s_add_i32 m0, s77, 0xe000
	s_nop 0
	global_load_lds_dwordx4 v[2:3], off
	s_cmp_eq_u32 s45, s99
	s_cbranch_scc1 .Ls1a_P1_0
	s_waitcnt vmcnt(8)
	s_branch .Ls1b_P1_0
.Ls1a_P1_0:
	s_waitcnt vmcnt(18)
.Ls1b_P1_0:
	s_waitcnt lgkmcnt(0)
	s_barrier
	s_setprio 1
	s_waitcnt lgkmcnt(0)
	v_mfma_f32_16x16x32_bf16 v[128:131], v[132:135], v[194:197], v[128:131]
	v_mfma_f32_16x16x32_bf16 v[124:127], v[140:143], v[194:197], v[124:127]
	v_mfma_f32_16x16x32_bf16 v[120:123], v[132:135], v[202:205], v[120:123]
	v_mfma_f32_16x16x32_bf16 v[116:119], v[140:143], v[202:205], v[116:119]
	v_mfma_f32_16x16x32_bf16 v[100:103], v[132:135], v[222:225], v[100:103]
	v_mfma_f32_16x16x32_bf16 v[96:99], v[140:143], v[222:225], v[96:99]
	v_mfma_f32_16x16x32_bf16 v[80:83], v[132:135], v[230:233], v[80:83]
	v_mfma_f32_16x16x32_bf16 v[76:79], v[140:143], v[230:233], v[76:79]
	v_mfma_f32_16x16x32_bf16 v[128:131], v[136:139], v[198:201], v[128:131]
	v_mfma_f32_16x16x32_bf16 v[124:127], v[144:147], v[198:201], v[124:127]
	v_mfma_f32_16x16x32_bf16 v[120:123], v[136:139], v[218:221], v[120:123]
	v_mfma_f32_16x16x32_bf16 v[116:119], v[144:147], v[218:221], v[116:119]
	v_mfma_f32_16x16x32_bf16 v[100:103], v[136:139], v[226:229], v[100:103]
	v_mfma_f32_16x16x32_bf16 v[96:99], v[144:147], v[226:229], v[96:99]
	v_mfma_f32_16x16x32_bf16 v[80:83], v[136:139], v[234:237], v[80:83]
	v_mfma_f32_16x16x32_bf16 v[76:79], v[144:147], v[234:237], v[76:79]
	s_setprio 0
	s_setprio 1
	v_mfma_f32_16x16x32_bf16 v[104:107], v[148:151], v[194:197], v[104:107]
	v_mfma_f32_16x16x32_bf16 v[84:87], v[156:159], v[194:197], v[84:87]
	v_mfma_f32_16x16x32_bf16 v[112:115], v[148:151], v[202:205], v[112:115]
	v_mfma_f32_16x16x32_bf16 v[108:111], v[156:159], v[202:205], v[108:111]
	v_mfma_f32_16x16x32_bf16 v[92:95], v[148:151], v[222:225], v[92:95]
	v_mfma_f32_16x16x32_bf16 v[88:91], v[156:159], v[222:225], v[88:91]
	v_mfma_f32_16x16x32_bf16 v[72:75], v[148:151], v[230:233], v[72:75]
	v_mfma_f32_16x16x32_bf16 v[68:71], v[156:159], v[230:233], v[68:71]
	v_mfma_f32_16x16x32_bf16 v[104:107], v[152:155], v[198:201], v[104:107]
	v_mfma_f32_16x16x32_bf16 v[84:87], v[160:163], v[198:201], v[84:87]
	v_mfma_f32_16x16x32_bf16 v[112:115], v[152:155], v[218:221], v[112:115]
	v_mfma_f32_16x16x32_bf16 v[108:111], v[160:163], v[218:221], v[108:111]
	v_mfma_f32_16x16x32_bf16 v[92:95], v[152:155], v[226:229], v[92:95]
	v_mfma_f32_16x16x32_bf16 v[88:91], v[160:163], v[226:229], v[88:91]
	v_mfma_f32_16x16x32_bf16 v[72:75], v[152:155], v[234:237], v[72:75]
	v_mfma_f32_16x16x32_bf16 v[68:71], v[160:163], v[234:237], v[68:71]
	s_setprio 0
	s_barrier
	s_add_i32 s46, s61, s33
	v_lshl_add_u64 v[206:207], s[2:3], 0, v[166:167]
	s_mov_b32 m0, s46
	ds_read_b128 v[194:197], v211 offset:16384
	ds_read_b128 v[198:201], v211 offset:17408
	ds_read_b128 v[202:205], v211 offset:18432
	ds_read_b128 v[218:221], v211 offset:19456
	ds_read_b128 v[222:225], v211 offset:20480
	ds_read_b128 v[226:229], v211 offset:21504
	ds_read_b128 v[230:233], v211 offset:22528
	ds_read_b128 v[234:237], v211 offset:23552
	global_load_lds_dwordx4 v[206:207], off
	s_add_i32 m0, s46, 0x2000
	s_add_u32 s46, s2, 0x40000
	v_lshl_add_u64 v[238:239], s[2:3], 0, v[174:175]
	s_addc_u32 s47, s3, 0
	s_add_i32 s48, s40, s33
	global_load_lds_dwordx4 v[238:239], off
	v_lshl_add_u64 v[2:3], s[46:47], 0, v[166:167]
	s_mov_b32 m0, s48
	v_lshl_add_u64 v[240:241], s[80:81], 0, v[164:165]
	global_load_lds_dwordx4 v[2:3], off
	v_lshl_add_u64 v[2:3], s[46:47], 0, v[174:175]
	s_add_i32 m0, s48, 0x2000
	v_lshl_add_u64 v[242:243], s[80:81], 0, v[172:173]
	global_load_lds_dwordx4 v[2:3], off
	s_mov_b32 m0, s77
	s_nop 0
	global_load_lds_dwordx4 v[240:241], off
	s_mov_b32 m0, s83
	s_nop 0
	global_load_lds_dwordx4 v[242:243], off
	s_cmp_eq_u32 s45, s99
	s_cbranch_scc1 .Ls1a_P1_1
	s_waitcnt vmcnt(8)
	s_branch .Ls1b_P1_1
.Ls1a_P1_1:
	s_waitcnt vmcnt(24)
.Ls1b_P1_1:
	s_waitcnt lgkmcnt(0)
	s_barrier
	s_setprio 1
	s_waitcnt lgkmcnt(0)
	v_mfma_f32_16x16x32_bf16 v[64:67], v[132:135], v[194:197], v[64:67]
	v_mfma_f32_16x16x32_bf16 v[60:63], v[140:143], v[194:197], v[60:63]
	v_mfma_f32_16x16x32_bf16 v[48:51], v[132:135], v[202:205], v[48:51]
	v_mfma_f32_16x16x32_bf16 v[44:47], v[140:143], v[202:205], v[44:47]
	v_mfma_f32_16x16x32_bf16 v[32:35], v[132:135], v[222:225], v[32:35]
	v_mfma_f32_16x16x32_bf16 v[28:31], v[140:143], v[222:225], v[28:31]
	v_mfma_f32_16x16x32_bf16 v[16:19], v[132:135], v[230:233], v[16:19]
	v_mfma_f32_16x16x32_bf16 v[12:15], v[140:143], v[230:233], v[12:15]
	v_mfma_f32_16x16x32_bf16 v[64:67], v[136:139], v[198:201], v[64:67]
	v_mfma_f32_16x16x32_bf16 v[60:63], v[144:147], v[198:201], v[60:63]
	v_mfma_f32_16x16x32_bf16 v[48:51], v[136:139], v[218:221], v[48:51]
	v_mfma_f32_16x16x32_bf16 v[44:47], v[144:147], v[218:221], v[44:47]
	v_mfma_f32_16x16x32_bf16 v[32:35], v[136:139], v[226:229], v[32:35]
	v_mfma_f32_16x16x32_bf16 v[28:31], v[144:147], v[226:229], v[28:31]
	v_mfma_f32_16x16x32_bf16 v[16:19], v[136:139], v[234:237], v[16:19]
	v_mfma_f32_16x16x32_bf16 v[12:15], v[144:147], v[234:237], v[12:15]
	s_setprio 0
	s_setprio 1
	v_mfma_f32_16x16x32_bf16 v[56:59], v[148:151], v[194:197], v[56:59]
	v_mfma_f32_16x16x32_bf16 v[52:55], v[156:159], v[194:197], v[52:55]
	v_mfma_f32_16x16x32_bf16 v[40:43], v[148:151], v[202:205], v[40:43]
	v_mfma_f32_16x16x32_bf16 v[36:39], v[156:159], v[202:205], v[36:39]
	v_mfma_f32_16x16x32_bf16 v[24:27], v[148:151], v[222:225], v[24:27]
	v_mfma_f32_16x16x32_bf16 v[20:23], v[156:159], v[222:225], v[20:23]
	v_mfma_f32_16x16x32_bf16 v[8:11], v[148:151], v[230:233], v[8:11]
	v_mfma_f32_16x16x32_bf16 v[2:5], v[156:159], v[230:233], v[4:7]
	v_mfma_f32_16x16x32_bf16 v[56:59], v[152:155], v[198:201], v[56:59]
	v_mfma_f32_16x16x32_bf16 v[52:55], v[160:163], v[198:201], v[52:55]
	v_mfma_f32_16x16x32_bf16 v[40:43], v[152:155], v[218:221], v[40:43]
	v_mfma_f32_16x16x32_bf16 v[36:39], v[160:163], v[218:221], v[36:39]
	v_mfma_f32_16x16x32_bf16 v[24:27], v[152:155], v[226:229], v[24:27]
	v_mfma_f32_16x16x32_bf16 v[20:23], v[160:163], v[226:229], v[20:23]
	v_mfma_f32_16x16x32_bf16 v[8:11], v[152:155], v[234:237], v[8:11]
	v_mfma_f32_16x16x32_bf16 v[2:5], v[160:163], v[234:237], v[2:5]
	s_setprio 0
	s_barrier
	s_add_i32 s48, 0, 0x18000
	v_add_u32_e32 v0, s48, v171
	s_add_i32 s49, 0, 0x1c000
	ds_read_b128 v[132:135], v0
	ds_read_b128 v[136:139], v0 offset:1024
	ds_read_b128 v[140:143], v0 offset:2048
	ds_read_b128 v[144:147], v0 offset:3072
	v_add_u32_e32 v0, s49, v171
	ds_read_b128 v[148:151], v0
	ds_read_b128 v[152:155], v0 offset:1024
	ds_read_b128 v[156:159], v0 offset:2048
	ds_read_b128 v[160:163], v0 offset:3072
	s_add_u32 s46, s80, 0x40000
	s_addc_u32 s47, s81, 0
	s_mov_b32 m0, s84
	v_lshl_add_u64 v[6:7], s[46:47], 0, v[164:165]
	ds_read_b128 v[194:197], v211 offset:32768
	ds_read_b128 v[198:201], v211 offset:33792
	ds_read_b128 v[202:205], v211 offset:34816
	ds_read_b128 v[218:221], v211 offset:35840
	ds_read_b128 v[222:225], v211 offset:36864
	ds_read_b128 v[226:229], v211 offset:37888
	ds_read_b128 v[230:233], v211 offset:38912
	ds_read_b128 v[234:237], v211 offset:39936
	global_load_lds_dwordx4 v[6:7], off
	v_lshl_add_u64 v[6:7], s[46:47], 0, v[172:173]
	s_mov_b32 m0, s85
	s_nop 0
	global_load_lds_dwordx4 v[6:7], off
	s_waitcnt vmcnt(8)
	s_waitcnt lgkmcnt(0)
	s_barrier
	s_setprio 1
	s_waitcnt lgkmcnt(0)
	v_mfma_f32_16x16x32_bf16 v[128:131], v[132:135], v[194:197], v[128:131]
	v_mfma_f32_16x16x32_bf16 v[124:127], v[140:143], v[194:197], v[124:127]
	v_mfma_f32_16x16x32_bf16 v[120:123], v[132:135], v[202:205], v[120:123]
	v_mfma_f32_16x16x32_bf16 v[116:119], v[140:143], v[202:205], v[116:119]
	v_mfma_f32_16x16x32_bf16 v[100:103], v[132:135], v[222:225], v[100:103]
	v_mfma_f32_16x16x32_bf16 v[96:99], v[140:143], v[222:225], v[96:99]
	v_mfma_f32_16x16x32_bf16 v[80:83], v[132:135], v[230:233], v[80:83]
	v_mfma_f32_16x16x32_bf16 v[76:79], v[140:143], v[230:233], v[76:79]
	v_mfma_f32_16x16x32_bf16 v[128:131], v[136:139], v[198:201], v[128:131]
	v_mfma_f32_16x16x32_bf16 v[124:127], v[144:147], v[198:201], v[124:127]
	v_mfma_f32_16x16x32_bf16 v[120:123], v[136:139], v[218:221], v[120:123]
	v_mfma_f32_16x16x32_bf16 v[116:119], v[144:147], v[218:221], v[116:119]
	v_mfma_f32_16x16x32_bf16 v[100:103], v[136:139], v[226:229], v[100:103]
	v_mfma_f32_16x16x32_bf16 v[96:99], v[144:147], v[226:229], v[96:99]
	v_mfma_f32_16x16x32_bf16 v[80:83], v[136:139], v[234:237], v[80:83]
	v_mfma_f32_16x16x32_bf16 v[76:79], v[144:147], v[234:237], v[76:79]
	s_setprio 0
	s_setprio 1
	v_mfma_f32_16x16x32_bf16 v[104:107], v[148:151], v[194:197], v[104:107]
	v_mfma_f32_16x16x32_bf16 v[84:87], v[156:159], v[194:197], v[84:87]
	v_mfma_f32_16x16x32_bf16 v[112:115], v[148:151], v[202:205], v[112:115]
	v_mfma_f32_16x16x32_bf16 v[108:111], v[156:159], v[202:205], v[108:111]
	v_mfma_f32_16x16x32_bf16 v[92:95], v[148:151], v[222:225], v[92:95]
	v_mfma_f32_16x16x32_bf16 v[88:91], v[156:159], v[222:225], v[88:91]
	v_mfma_f32_16x16x32_bf16 v[72:75], v[148:151], v[230:233], v[72:75]
	v_mfma_f32_16x16x32_bf16 v[68:71], v[156:159], v[230:233], v[68:71]
	v_mfma_f32_16x16x32_bf16 v[104:107], v[152:155], v[198:201], v[104:107]
	v_mfma_f32_16x16x32_bf16 v[84:87], v[160:163], v[198:201], v[84:87]
	v_mfma_f32_16x16x32_bf16 v[112:115], v[152:155], v[218:221], v[112:115]
	v_mfma_f32_16x16x32_bf16 v[108:111], v[160:163], v[218:221], v[108:111]
	v_mfma_f32_16x16x32_bf16 v[92:95], v[152:155], v[226:229], v[92:95]
	v_mfma_f32_16x16x32_bf16 v[88:91], v[160:163], v[226:229], v[88:91]
	v_mfma_f32_16x16x32_bf16 v[72:75], v[152:155], v[234:237], v[72:75]
	v_mfma_f32_16x16x32_bf16 v[68:71], v[160:163], v[234:237], v[68:71]
	s_setprio 0
	s_barrier
	s_add_i32 s46, s48, s33
	v_lshl_add_u64 v[6:7], v[206:207], 0, s[64:65]
	s_mov_b32 m0, s46
	ds_read_b128 v[194:197], v211 offset:49152
	ds_read_b128 v[198:201], v211 offset:50176
	ds_read_b128 v[202:205], v211 offset:51200
	ds_read_b128 v[218:221], v211 offset:52224
	ds_read_b128 v[222:225], v211 offset:53248
	ds_read_b128 v[226:229], v211 offset:54272
	ds_read_b128 v[230:233], v211 offset:55296
	ds_read_b128 v[234:237], v211 offset:56320
	global_load_lds_dwordx4 v[6:7], off
	s_add_i32 m0, s46, 0x2000
	s_add_u32 s2, s2, 0x40080
	v_lshl_add_u64 v[6:7], v[238:239], 0, s[64:65]
	s_addc_u32 s3, s3, 0
	s_add_i32 s46, s49, s33
	global_load_lds_dwordx4 v[6:7], off
	v_lshl_add_u64 v[6:7], s[2:3], 0, v[166:167]
	s_mov_b32 m0, s46
	s_nop 0
	global_load_lds_dwordx4 v[6:7], off
	v_lshl_add_u64 v[6:7], s[2:3], 0, v[174:175]
	s_add_i32 m0, s46, 0x2000
	s_nop 0
	global_load_lds_dwordx4 v[6:7], off
	v_lshl_add_u64 v[6:7], v[240:241], 0, s[64:65]
	s_mov_b32 m0, s92
	s_nop 0
	global_load_lds_dwordx4 v[6:7], off
	v_lshl_add_u64 v[6:7], v[242:243], 0, s[64:65]
	s_mov_b32 m0, s93
	s_nop 0
	global_load_lds_dwordx4 v[6:7], off
	s_waitcnt vmcnt(8)
	s_waitcnt lgkmcnt(0)
	s_barrier
	s_setprio 1
	s_waitcnt lgkmcnt(0)
	v_mfma_f32_16x16x32_bf16 v[64:67], v[132:135], v[194:197], v[64:67]
	v_mfma_f32_16x16x32_bf16 v[60:63], v[140:143], v[194:197], v[60:63]
	v_mfma_f32_16x16x32_bf16 v[48:51], v[132:135], v[202:205], v[48:51]
	v_mfma_f32_16x16x32_bf16 v[44:47], v[140:143], v[202:205], v[44:47]
	v_mfma_f32_16x16x32_bf16 v[32:35], v[132:135], v[222:225], v[32:35]
	v_mfma_f32_16x16x32_bf16 v[28:31], v[140:143], v[222:225], v[28:31]
	v_mfma_f32_16x16x32_bf16 v[16:19], v[132:135], v[230:233], v[16:19]
	v_mfma_f32_16x16x32_bf16 v[12:15], v[140:143], v[230:233], v[12:15]
	v_mfma_f32_16x16x32_bf16 v[64:67], v[136:139], v[198:201], v[64:67]
	v_mfma_f32_16x16x32_bf16 v[60:63], v[144:147], v[198:201], v[60:63]
	v_mfma_f32_16x16x32_bf16 v[48:51], v[136:139], v[218:221], v[48:51]
	v_mfma_f32_16x16x32_bf16 v[44:47], v[144:147], v[218:221], v[44:47]
	v_mfma_f32_16x16x32_bf16 v[32:35], v[136:139], v[226:229], v[32:35]
	v_mfma_f32_16x16x32_bf16 v[28:31], v[144:147], v[226:229], v[28:31]
	v_mfma_f32_16x16x32_bf16 v[16:19], v[136:139], v[234:237], v[16:19]
	v_mfma_f32_16x16x32_bf16 v[12:15], v[144:147], v[234:237], v[12:15]
	s_setprio 0
	s_setprio 1
	v_mfma_f32_16x16x32_bf16 v[56:59], v[148:151], v[194:197], v[56:59]
	v_mfma_f32_16x16x32_bf16 v[52:55], v[156:159], v[194:197], v[52:55]
	v_mfma_f32_16x16x32_bf16 v[40:43], v[148:151], v[202:205], v[40:43]
	v_mfma_f32_16x16x32_bf16 v[36:39], v[156:159], v[202:205], v[36:39]
	v_mfma_f32_16x16x32_bf16 v[24:27], v[148:151], v[222:225], v[24:27]
	v_mfma_f32_16x16x32_bf16 v[20:23], v[156:159], v[222:225], v[20:23]
	v_mfma_f32_16x16x32_bf16 v[6:9], v[148:151], v[230:233], v[8:11]
	v_mfma_f32_16x16x32_bf16 v[2:5], v[156:159], v[230:233], v[2:5]
	v_mfma_f32_16x16x32_bf16 v[56:59], v[152:155], v[198:201], v[56:59]
	v_mfma_f32_16x16x32_bf16 v[52:55], v[160:163], v[198:201], v[52:55]
	v_mfma_f32_16x16x32_bf16 v[40:43], v[152:155], v[218:221], v[40:43]
	v_mfma_f32_16x16x32_bf16 v[36:39], v[160:163], v[218:221], v[36:39]
	v_mfma_f32_16x16x32_bf16 v[24:27], v[152:155], v[226:229], v[24:27]
	v_mfma_f32_16x16x32_bf16 v[20:23], v[160:163], v[226:229], v[20:23]
	v_mfma_f32_16x16x32_bf16 v[8:11], v[152:155], v[234:237], v[6:9]
	v_mfma_f32_16x16x32_bf16 v[4:7], v[160:163], v[234:237], v[2:5]
	s_setprio 0
	s_barrier
	s_add_i32 s45, s45, 2
	s_add_u32 s78, s78, 0x100
	s_addc_u32 s79, s79, 0
	s_add_u32 vcc_hi, vcc_hi, 0x100
	s_addc_u32 s44, s44, 0
	s_cmp_gt_u32 s45, 13
	s_cbranch_scc0 .LBB0_136
	s_mov_b32 s99, -2
	s_and_b64 vcc, exec, s[66:67]
	s_cbranch_vccz .LBB0_139
	s_barrier

.LBB0_528:
	s_lshl_b32 s7, s7, 5
	s_mov_b64 s[10:11], 0x80
	s_and_b32 s38, s7, 0x60
	s_add_i32 m0, s37, 0x18000
	v_lshl_add_u64 v[6:7], v[6:7], 0, s[10:11]
	s_lshl_b32 s36, s6, 13
	s_lshl_b32 s7, s38, 7
	s_waitcnt vmcnt(2)
	s_barrier
	global_load_lds_dwordx4 v[6:7], off
	v_lshl_add_u64 v[2:3], v[2:3], 0, s[10:11]
	s_add_i32 m0, s37, 0x1a000
	s_add_i32 s55, s37, 0x8000
	s_add_i32 s56, s37, 0xa000
	global_load_lds_dwordx4 v[2:3], off
	v_lshl_add_u64 v[0:1], v[0:1], 0, s[10:11]
	s_mov_b32 m0, s55
	s_add_u32 s34, s2, 0x40080
	global_load_lds_dwordx4 v[0:1], off
	v_lshl_add_u64 v[0:1], v[4:5], 0, s[10:11]
	s_mov_b32 m0, s56
	s_addc_u32 s35, s3, 0
	global_load_lds_dwordx4 v[0:1], off
	s_add_i32 m0, s37, 0x1c000
	v_lshl_add_u64 v[0:1], s[34:35], 0, v[132:133]
	global_load_lds_dwordx4 v[0:1], off
	v_lshl_add_u64 v[0:1], s[34:35], 0, v[128:129]
	s_add_i32 m0, s37, 0x1e000
	v_bfe_u32 v2, v10, 4, 2
	global_load_lds_dwordx4 v[0:1], off
	v_and_b32_e32 v0, 15, v10
	v_lshlrev_b32_e32 v1, 4, v2
	v_lshl_or_b32 v139, s6, 6, v0
	v_lshl_or_b32 v0, v0, 6, v1
	v_lshlrev_b32_e32 v1, 2, v10
	v_and_b32_e32 v1, 32, v1
	v_bitop3_b32 v3, v0, s36, v1 bitop3:0xde
	v_bitop3_b32 v141, v0, s7, v1 bitop3:0xde
	v_cmp_lt_u32_e32 vcc, 1, v2
	v_mov_b32_e32 v1, 0x80
	v_mov_b32_e32 v4, 0x90
	v_bfe_u32 v0, v10, 4, 1
	v_cndmask_b32_e32 v163, v1, v4, vcc
	v_mov_b32_e32 v1, 0xa0
	v_mov_b32_e32 v4, 0xb0
	v_cmp_eq_u32_e64 s[6:7], 0, v0
	v_cndmask_b32_e32 v164, v1, v4, vcc
	v_lshlrev_b32_e32 v0, 2, v0
	v_mov_b32_e32 v1, v133
	v_lshl_add_u64 v[144:145], s[30:31], 0, v[0:1]
	v_lshlrev_b32_e32 v0, 14, v13
	v_and_b32_e32 v0, 0xffff8000, v0
	v_lshl_add_u32 v0, v12, 11, v0
	v_and_b32_e32 v1, 1, v13
	v_lshl_or_b32 v0, v1, 6, v0
	v_lshl_add_u32 v146, v14, 1, v0
	v_lshlrev_b32_e32 v0, 14, v8
	v_and_b32_e32 v0, 0xffff8000, v0
	v_lshl_add_u32 v0, v9, 11, v0
	v_and_b32_e32 v1, 1, v8
	s_waitcnt vmcnt(6)
	s_mov_b32 s99, 0x7fff0000
	s_cmpk_lt_u32 s1, 0x100
	v_lshl_or_b32 v0, v1, 6, v0
	s_cselect_b64 s[34:35], -1, 0
	v_lshl_add_u32 v148, v11, 1, v0
	s_add_i32 s57, 0, 0x10000
	s_add_i32 s58, 0, 0x14000
	v_mbcnt_lo_u32_b32 v0, -1, 0
	s_sext_i32_i8 s59, s0
	v_cndmask_b32_e64 v136, 0, 1, vcc
	v_mov_b32_e32 v137, s54
	v_cndmask_b32_e64 v138, 2, 3, vcc
	v_cndmask_b32_e64 v143, 0, 16, vcc
	v_cndmask_b32_e64 v140, 4, 5, vcc
	v_cndmask_b32_e64 v162, 32, 48, vcc
	v_cndmask_b32_e64 v142, 6, 7, vcc
	v_lshl_or_b32 v165, v2, 3, s38
	v_mov_b32_e32 v147, v133
	v_mov_b32_e32 v149, v133
	v_mov_b64_e32 v[150:151], 0x200
	v_mov_b64_e32 v[152:153], 0x1ff
	v_add_u32_e32 v166, s57, v141
	v_add_u32_e32 v167, s58, v141
	v_add_u32_e32 v169, 0, v3
	v_mbcnt_hi_u32_b32 v171, -1, v0
	s_mov_b32 s36, 0x3fb504f3
	s_barrier
	s_branch .LBB0_531

.LBB0_537:
	s_ashr_i32 s41, s40, 31
	s_lshl_b64 s[42:43], s[40:41], 19
	s_add_u32 s42, s24, s42
	s_addc_u32 s43, s25, s43
	s_and_b64 s[44:45], s[0:1], exec
	s_cselect_b32 s41, s43, s49
	s_cselect_b32 s60, s42, s48
	s_ashr_i32 s39, s38, 31
	s_lshl_b64 s[44:45], s[38:39], 19
	s_add_u32 s44, s94, s44
	s_addc_u32 s45, s95, s45
	s_and_b64 s[50:51], s[0:1], exec
	s_cselect_b32 s39, s45, s3
	s_cselect_b32 s61, s44, s2
	s_add_u32 s48, s48, 0x40080
	s_addc_u32 s49, s49, 0
	s_add_u32 s62, s2, 0x100
	v_mov_b32_e32 v0, 0
	s_addc_u32 s63, s3, 0
	s_mov_b32 s64, -2
	v_mov_b32_e32 v1, v0
	v_mov_b32_e32 v2, v0
	v_mov_b32_e32 v3, v0
	v_mov_b32_e32 v4, v0
	v_mov_b32_e32 v5, v0
	v_mov_b32_e32 v6, v0
	v_mov_b32_e32 v7, v0
	v_mov_b32_e32 v16, v0
	v_mov_b32_e32 v17, v0
	v_mov_b32_e32 v18, v0
	v_mov_b32_e32 v19, v0
	v_mov_b32_e32 v20, v0
	v_mov_b32_e32 v21, v0
	v_mov_b32_e32 v22, v0
	v_mov_b32_e32 v23, v0
	v_mov_b32_e32 v32, v0
	v_mov_b32_e32 v33, v0
	v_mov_b32_e32 v34, v0
	v_mov_b32_e32 v35, v0
	v_mov_b32_e32 v36, v0
	v_mov_b32_e32 v37, v0
	v_mov_b32_e32 v38, v0
	v_mov_b32_e32 v39, v0
	v_mov_b32_e32 v48, v0
	v_mov_b32_e32 v49, v0
	v_mov_b32_e32 v50, v0
	v_mov_b32_e32 v51, v0
	v_mov_b32_e32 v52, v0
	v_mov_b32_e32 v53, v0
	v_mov_b32_e32 v54, v0
	v_mov_b32_e32 v55, v0
	v_mov_b32_e32 v8, v0
	v_mov_b32_e32 v9, v0
	v_mov_b32_e32 v10, v0
	v_mov_b32_e32 v11, v0
	v_mov_b32_e32 v12, v0
	v_mov_b32_e32 v13, v0
	v_mov_b32_e32 v14, v0
	v_mov_b32_e32 v15, v0
	v_mov_b32_e32 v24, v0
	v_mov_b32_e32 v25, v0
	v_mov_b32_e32 v26, v0
	v_mov_b32_e32 v27, v0
	v_mov_b32_e32 v28, v0
	v_mov_b32_e32 v29, v0
	v_mov_b32_e32 v30, v0
	v_mov_b32_e32 v31, v0
	v_mov_b32_e32 v40, v0
	v_mov_b32_e32 v41, v0
	v_mov_b32_e32 v42, v0
	v_mov_b32_e32 v43, v0
	v_mov_b32_e32 v44, v0
	v_mov_b32_e32 v45, v0
	v_mov_b32_e32 v46, v0
	v_mov_b32_e32 v47, v0
	v_mov_b32_e32 v56, v0
	v_mov_b32_e32 v57, v0
	v_mov_b32_e32 v58, v0
	v_mov_b32_e32 v59, v0
	v_mov_b32_e32 v60, v0
	v_mov_b32_e32 v61, v0
	v_mov_b32_e32 v62, v0
	v_mov_b32_e32 v63, v0
	v_mov_b32_e32 v64, v0
	v_mov_b32_e32 v65, v0
	v_mov_b32_e32 v66, v0
	v_mov_b32_e32 v67, v0
	v_mov_b32_e32 v68, v0
	v_mov_b32_e32 v69, v0
	v_mov_b32_e32 v70, v0
	v_mov_b32_e32 v71, v0
	v_mov_b32_e32 v80, v0
	v_mov_b32_e32 v81, v0
	v_mov_b32_e32 v82, v0
	v_mov_b32_e32 v83, v0
	v_mov_b32_e32 v84, v0
	v_mov_b32_e32 v85, v0
	v_mov_b32_e32 v86, v0
	v_mov_b32_e32 v87, v0
	v_mov_b32_e32 v96, v0
	v_mov_b32_e32 v97, v0
	v_mov_b32_e32 v98, v0
	v_mov_b32_e32 v99, v0
	v_mov_b32_e32 v100, v0
	v_mov_b32_e32 v101, v0
	v_mov_b32_e32 v102, v0
	v_mov_b32_e32 v103, v0
	v_mov_b32_e32 v112, v0
	v_mov_b32_e32 v113, v0
	v_mov_b32_e32 v114, v0
	v_mov_b32_e32 v115, v0
	v_mov_b32_e32 v116, v0
	v_mov_b32_e32 v117, v0
	v_mov_b32_e32 v118, v0
	v_mov_b32_e32 v119, v0
	v_mov_b32_e32 v72, v0
	v_mov_b32_e32 v73, v0
	v_mov_b32_e32 v74, v0
	v_mov_b32_e32 v75, v0
	v_mov_b32_e32 v76, v0
	v_mov_b32_e32 v77, v0
	v_mov_b32_e32 v78, v0
	v_mov_b32_e32 v79, v0
	v_mov_b32_e32 v88, v0
	v_mov_b32_e32 v89, v0
	v_mov_b32_e32 v90, v0
	v_mov_b32_e32 v91, v0
	v_mov_b32_e32 v92, v0
	v_mov_b32_e32 v93, v0
	v_mov_b32_e32 v94, v0
	v_mov_b32_e32 v95, v0
	v_mov_b32_e32 v104, v0
	v_mov_b32_e32 v105, v0
	v_mov_b32_e32 v106, v0
	v_mov_b32_e32 v107, v0
	v_mov_b32_e32 v108, v0
	v_mov_b32_e32 v109, v0
	v_mov_b32_e32 v110, v0
	v_mov_b32_e32 v111, v0
	v_mov_b32_e32 v120, v0
	v_mov_b32_e32 v121, v0
	v_mov_b32_e32 v122, v0
	v_mov_b32_e32 v123, v0
	v_mov_b32_e32 v124, v0
	v_mov_b32_e32 v125, v0
	v_mov_b32_e32 v126, v0
	v_mov_b32_e32 v127, v0
.LBB0_538:
	ds_read_b128 v[154:157], v166
	ds_read_b128 v[158:161], v166 offset:1024
	ds_read_b128 v[172:175], v166 offset:2048
	ds_read_b128 v[176:179], v166 offset:3072
	ds_read_b128 v[180:183], v167
	ds_read_b128 v[184:187], v167 offset:1024
	ds_read_b128 v[188:191], v167 offset:2048
	ds_read_b128 v[192:195], v167 offset:3072
	s_add_u32 s2, s48, 0xfffc0080
	s_addc_u32 s3, s49, -1
	s_cmp_eq_u32 s64, 12
	s_cselect_b32 s51, s41, s3
	s_cselect_b32 s50, s60, s2
	s_cselect_b32 s3, s39, s63
	s_cselect_b32 s2, s61, s62
	v_lshl_add_u64 v[212:213], s[48:49], 0, v[146:147]
	s_add_i32 m0, s37, 0xc000
	ds_read_b128 v[196:199], v169
	ds_read_b128 v[200:203], v169 offset:1024
	ds_read_b128 v[204:207], v169 offset:2048
	ds_read_b128 v[208:211], v169 offset:3072
	ds_read_b128 v[216:219], v169 offset:4096
	ds_read_b128 v[220:223], v169 offset:5120
	ds_read_b128 v[224:227], v169 offset:6144
	ds_read_b128 v[228:231], v169 offset:7168
	global_load_lds_dwordx4 v[212:213], off
	v_lshl_add_u64 v[212:213], s[48:49], 0, v[148:149]
	s_add_i32 m0, s37, 0xe000
	s_nop 0
	global_load_lds_dwordx4 v[212:213], off
	s_cmp_eq_u32 s64, s99
	s_cbranch_scc1 .Ls1a_P4_0
	s_waitcnt vmcnt(8)
	s_branch .Ls1b_P4_0
.Ls1a_P4_0:
	s_waitcnt vmcnt(22)
.Ls1b_P4_0:
	s_waitcnt lgkmcnt(0)
	s_barrier
	s_setprio 1
	s_waitcnt lgkmcnt(0)
	v_mfma_f32_16x16x32_bf16 v[124:127], v[154:157], v[196:199], v[124:127]
	v_mfma_f32_16x16x32_bf16 v[120:123], v[172:175], v[196:199], v[120:123]
	v_mfma_f32_16x16x32_bf16 v[108:111], v[154:157], v[204:207], v[108:111]
	v_mfma_f32_16x16x32_bf16 v[104:107], v[172:175], v[204:207], v[104:107]
	v_mfma_f32_16x16x32_bf16 v[92:95], v[154:157], v[216:219], v[92:95]
	v_mfma_f32_16x16x32_bf16 v[88:91], v[172:175], v[216:219], v[88:91]
	v_mfma_f32_16x16x32_bf16 v[76:79], v[154:157], v[224:227], v[76:79]
	v_mfma_f32_16x16x32_bf16 v[72:75], v[172:175], v[224:227], v[72:75]
	v_mfma_f32_16x16x32_bf16 v[124:127], v[158:161], v[200:203], v[124:127]
	v_mfma_f32_16x16x32_bf16 v[120:123], v[176:179], v[200:203], v[120:123]
	v_mfma_f32_16x16x32_bf16 v[108:111], v[158:161], v[208:211], v[108:111]
	v_mfma_f32_16x16x32_bf16 v[104:107], v[176:179], v[208:211], v[104:107]
	v_mfma_f32_16x16x32_bf16 v[92:95], v[158:161], v[220:223], v[92:95]
	v_mfma_f32_16x16x32_bf16 v[88:91], v[176:179], v[220:223], v[88:91]
	v_mfma_f32_16x16x32_bf16 v[76:79], v[158:161], v[228:231], v[76:79]
	v_mfma_f32_16x16x32_bf16 v[72:75], v[176:179], v[228:231], v[72:75]
	s_setprio 0
	s_setprio 1
	v_mfma_f32_16x16x32_bf16 v[116:119], v[180:183], v[196:199], v[116:119]
	v_mfma_f32_16x16x32_bf16 v[112:115], v[188:191], v[196:199], v[112:115]
	v_mfma_f32_16x16x32_bf16 v[100:103], v[180:183], v[204:207], v[100:103]
	v_mfma_f32_16x16x32_bf16 v[96:99], v[188:191], v[204:207], v[96:99]
	v_mfma_f32_16x16x32_bf16 v[84:87], v[180:183], v[216:219], v[84:87]
	v_mfma_f32_16x16x32_bf16 v[80:83], v[188:191], v[216:219], v[80:83]
	v_mfma_f32_16x16x32_bf16 v[68:71], v[180:183], v[224:227], v[68:71]
	v_mfma_f32_16x16x32_bf16 v[64:67], v[188:191], v[224:227], v[64:67]
	v_mfma_f32_16x16x32_bf16 v[116:119], v[184:187], v[200:203], v[116:119]
	v_mfma_f32_16x16x32_bf16 v[112:115], v[192:195], v[200:203], v[112:115]
	v_mfma_f32_16x16x32_bf16 v[100:103], v[184:187], v[208:211], v[100:103]
	v_mfma_f32_16x16x32_bf16 v[96:99], v[192:195], v[208:211], v[96:99]
	v_mfma_f32_16x16x32_bf16 v[84:87], v[184:187], v[220:223], v[84:87]
	v_mfma_f32_16x16x32_bf16 v[80:83], v[192:195], v[220:223], v[80:83]
	v_mfma_f32_16x16x32_bf16 v[68:71], v[184:187], v[228:231], v[68:71]
	v_mfma_f32_16x16x32_bf16 v[64:67], v[192:195], v[228:231], v[64:67]
	s_setprio 0
	s_barrier
	s_add_i32 s65, s57, s33
	v_lshl_add_u64 v[212:213], s[2:3], 0, v[132:133]
	s_mov_b32 m0, s65
	ds_read_b128 v[196:199], v169 offset:16384
	ds_read_b128 v[200:203], v169 offset:17408
	ds_read_b128 v[204:207], v169 offset:18432
	ds_read_b128 v[208:211], v169 offset:19456
	ds_read_b128 v[216:219], v169 offset:20480
	ds_read_b128 v[220:223], v169 offset:21504
	ds_read_b128 v[224:227], v169 offset:22528
	ds_read_b128 v[228:231], v169 offset:23552
	global_load_lds_dwordx4 v[212:213], off
	s_add_i32 m0, s65, 0x2000
	s_add_u32 s66, s2, 0x40000
	v_lshl_add_u64 v[232:233], s[2:3], 0, v[128:129]
	s_addc_u32 s67, s3, 0
	s_add_i32 s65, s58, s33
	global_load_lds_dwordx4 v[232:233], off
	v_lshl_add_u64 v[234:235], s[66:67], 0, v[132:133]
	s_mov_b32 m0, s65
	v_lshl_add_u64 v[236:237], s[50:51], 0, v[130:131]
	global_load_lds_dwordx4 v[234:235], off
	v_lshl_add_u64 v[234:235], s[66:67], 0, v[128:129]
	s_add_i32 m0, s65, 0x2000
	s_nop 0
	global_load_lds_dwordx4 v[234:235], off
	v_lshl_add_u64 v[234:235], s[50:51], 0, v[134:135]
	s_mov_b32 m0, s37
	s_nop 0
	global_load_lds_dwordx4 v[234:235], off
	s_mov_b32 m0, s47
	s_nop 0
	global_load_lds_dwordx4 v[236:237], off
	s_cmp_eq_u32 s64, s99
	s_cbranch_scc1 .Ls1a_P4_1
	s_waitcnt vmcnt(8)
	s_branch .Ls1b_P4_1
.Ls1a_P4_1:
	s_waitcnt vmcnt(28)
.Ls1b_P4_1:
	s_waitcnt lgkmcnt(0)
	s_barrier
	s_setprio 1
	s_waitcnt lgkmcnt(0)
	v_mfma_f32_16x16x32_bf16 v[60:63], v[154:157], v[196:199], v[60:63]
	v_mfma_f32_16x16x32_bf16 v[56:59], v[172:175], v[196:199], v[56:59]
	v_mfma_f32_16x16x32_bf16 v[44:47], v[154:157], v[204:207], v[44:47]
	v_mfma_f32_16x16x32_bf16 v[40:43], v[172:175], v[204:207], v[40:43]
	v_mfma_f32_16x16x32_bf16 v[28:31], v[154:157], v[216:219], v[28:31]
	v_mfma_f32_16x16x32_bf16 v[24:27], v[172:175], v[216:219], v[24:27]
	v_mfma_f32_16x16x32_bf16 v[12:15], v[154:157], v[224:227], v[12:15]
	v_mfma_f32_16x16x32_bf16 v[8:11], v[172:175], v[224:227], v[8:11]
	v_mfma_f32_16x16x32_bf16 v[60:63], v[158:161], v[200:203], v[60:63]
	v_mfma_f32_16x16x32_bf16 v[56:59], v[176:179], v[200:203], v[56:59]
	v_mfma_f32_16x16x32_bf16 v[44:47], v[158:161], v[208:211], v[44:47]
	v_mfma_f32_16x16x32_bf16 v[40:43], v[176:179], v[208:211], v[40:43]
	v_mfma_f32_16x16x32_bf16 v[28:31], v[158:161], v[220:223], v[28:31]
	v_mfma_f32_16x16x32_bf16 v[24:27], v[176:179], v[220:223], v[24:27]
	v_mfma_f32_16x16x32_bf16 v[12:15], v[158:161], v[228:231], v[12:15]
	v_mfma_f32_16x16x32_bf16 v[8:11], v[176:179], v[228:231], v[8:11]
	s_setprio 0
	s_setprio 1
	v_mfma_f32_16x16x32_bf16 v[52:55], v[180:183], v[196:199], v[52:55]
	v_mfma_f32_16x16x32_bf16 v[48:51], v[188:191], v[196:199], v[48:51]
	v_mfma_f32_16x16x32_bf16 v[36:39], v[180:183], v[204:207], v[36:39]
	v_mfma_f32_16x16x32_bf16 v[32:35], v[188:191], v[204:207], v[32:35]
	v_mfma_f32_16x16x32_bf16 v[20:23], v[180:183], v[216:219], v[20:23]
	v_mfma_f32_16x16x32_bf16 v[16:19], v[188:191], v[216:219], v[16:19]
	v_mfma_f32_16x16x32_bf16 v[4:7], v[180:183], v[224:227], v[4:7]
	v_mfma_f32_16x16x32_bf16 v[0:3], v[188:191], v[224:227], v[0:3]
	v_mfma_f32_16x16x32_bf16 v[52:55], v[184:187], v[200:203], v[52:55]
	v_mfma_f32_16x16x32_bf16 v[48:51], v[192:195], v[200:203], v[48:51]
	v_mfma_f32_16x16x32_bf16 v[36:39], v[184:187], v[208:211], v[36:39]
	v_mfma_f32_16x16x32_bf16 v[32:35], v[192:195], v[208:211], v[32:35]
	v_mfma_f32_16x16x32_bf16 v[20:23], v[184:187], v[220:223], v[20:23]
	v_mfma_f32_16x16x32_bf16 v[16:19], v[192:195], v[220:223], v[16:19]
	v_mfma_f32_16x16x32_bf16 v[4:7], v[184:187], v[228:231], v[4:7]
	v_mfma_f32_16x16x32_bf16 v[0:3], v[192:195], v[228:231], v[0:3]
	s_setprio 0
	s_barrier
	s_add_i32 s65, 0, 0x18000
	s_add_i32 s66, 0, 0x1c000
	v_add_u32_e32 v176, s65, v141
	v_add_u32_e32 v192, s66, v141
	ds_read_b128 v[154:157], v176
	ds_read_b128 v[158:161], v176 offset:1024
	ds_read_b128 v[172:175], v176 offset:2048
	ds_read_b128 v[176:179], v176 offset:3072
	ds_read_b128 v[180:183], v192
	ds_read_b128 v[184:187], v192 offset:1024
	ds_read_b128 v[188:191], v192 offset:2048
	ds_read_b128 v[192:195], v192 offset:3072
	s_add_u32 s50, s50, 0x40000
	s_addc_u32 s51, s51, 0
	s_mov_b32 m0, s52
	v_lshl_add_u64 v[238:239], s[50:51], 0, v[134:135]
	ds_read_b128 v[196:199], v169 offset:32768
	ds_read_b128 v[200:203], v169 offset:33792
	ds_read_b128 v[204:207], v169 offset:34816
	ds_read_b128 v[208:211], v169 offset:35840
	ds_read_b128 v[216:219], v169 offset:36864
	ds_read_b128 v[220:223], v169 offset:37888
	ds_read_b128 v[224:227], v169 offset:38912
	ds_read_b128 v[228:231], v169 offset:39936
	global_load_lds_dwordx4 v[238:239], off
	v_lshl_add_u64 v[238:239], s[50:51], 0, v[130:131]
	s_mov_b32 m0, s53
	s_nop 0
	global_load_lds_dwordx4 v[238:239], off
	s_waitcnt vmcnt(8)
	s_waitcnt lgkmcnt(0)
	s_barrier
	s_setprio 1
	s_waitcnt lgkmcnt(0)
	v_mfma_f32_16x16x32_bf16 v[124:127], v[154:157], v[196:199], v[124:127]
	v_mfma_f32_16x16x32_bf16 v[120:123], v[172:175], v[196:199], v[120:123]
	v_mfma_f32_16x16x32_bf16 v[108:111], v[154:157], v[204:207], v[108:111]
	v_mfma_f32_16x16x32_bf16 v[104:107], v[172:175], v[204:207], v[104:107]
	v_mfma_f32_16x16x32_bf16 v[92:95], v[154:157], v[216:219], v[92:95]
	v_mfma_f32_16x16x32_bf16 v[88:91], v[172:175], v[216:219], v[88:91]
	v_mfma_f32_16x16x32_bf16 v[76:79], v[154:157], v[224:227], v[76:79]
	v_mfma_f32_16x16x32_bf16 v[72:75], v[172:175], v[224:227], v[72:75]
	v_mfma_f32_16x16x32_bf16 v[124:127], v[158:161], v[200:203], v[124:127]
	v_mfma_f32_16x16x32_bf16 v[120:123], v[176:179], v[200:203], v[120:123]
	v_mfma_f32_16x16x32_bf16 v[108:111], v[158:161], v[208:211], v[108:111]
	v_mfma_f32_16x16x32_bf16 v[104:107], v[176:179], v[208:211], v[104:107]
	v_mfma_f32_16x16x32_bf16 v[92:95], v[158:161], v[220:223], v[92:95]
	v_mfma_f32_16x16x32_bf16 v[88:91], v[176:179], v[220:223], v[88:91]
	v_mfma_f32_16x16x32_bf16 v[76:79], v[158:161], v[228:231], v[76:79]
	v_mfma_f32_16x16x32_bf16 v[72:75], v[176:179], v[228:231], v[72:75]
	s_setprio 0
	s_setprio 1
	v_mfma_f32_16x16x32_bf16 v[116:119], v[180:183], v[196:199], v[116:119]
	v_mfma_f32_16x16x32_bf16 v[112:115], v[188:191], v[196:199], v[112:115]
	v_mfma_f32_16x16x32_bf16 v[100:103], v[180:183], v[204:207], v[100:103]
	v_mfma_f32_16x16x32_bf16 v[96:99], v[188:191], v[204:207], v[96:99]
	v_mfma_f32_16x16x32_bf16 v[84:87], v[180:183], v[216:219], v[84:87]
	v_mfma_f32_16x16x32_bf16 v[80:83], v[188:191], v[216:219], v[80:83]
	v_mfma_f32_16x16x32_bf16 v[68:71], v[180:183], v[224:227], v[68:71]
	v_mfma_f32_16x16x32_bf16 v[64:67], v[188:191], v[224:227], v[64:67]
	v_mfma_f32_16x16x32_bf16 v[116:119], v[184:187], v[200:203], v[116:119]
	v_mfma_f32_16x16x32_bf16 v[112:115], v[192:195], v[200:203], v[112:115]
	v_mfma_f32_16x16x32_bf16 v[100:103], v[184:187], v[208:211], v[100:103]
	v_mfma_f32_16x16x32_bf16 v[96:99], v[192:195], v[208:211], v[96:99]
	v_mfma_f32_16x16x32_bf16 v[84:87], v[184:187], v[220:223], v[84:87]
	v_mfma_f32_16x16x32_bf16 v[80:83], v[192:195], v[220:223], v[80:83]
	v_mfma_f32_16x16x32_bf16 v[68:71], v[184:187], v[228:231], v[68:71]
	v_mfma_f32_16x16x32_bf16 v[64:67], v[192:195], v[228:231], v[64:67]
	s_setprio 0
	s_barrier
	s_add_i32 s50, s65, s33
	v_lshl_add_u64 v[212:213], v[212:213], 0, s[10:11]
	s_mov_b32 m0, s50
	ds_read_b128 v[196:199], v169 offset:49152
	ds_read_b128 v[200:203], v169 offset:50176
	ds_read_b128 v[204:207], v169 offset:51200
	ds_read_b128 v[208:211], v169 offset:52224
	ds_read_b128 v[216:219], v169 offset:53248
	ds_read_b128 v[220:223], v169 offset:54272
	ds_read_b128 v[224:227], v169 offset:55296
	ds_read_b128 v[228:231], v169 offset:56320
	global_load_lds_dwordx4 v[212:213], off
	s_add_i32 m0, s50, 0x2000
	s_add_u32 s2, s2, 0x40080
	v_lshl_add_u64 v[212:213], v[232:233], 0, s[10:11]
	s_addc_u32 s3, s3, 0
	s_add_i32 s50, s66, s33
	global_load_lds_dwordx4 v[212:213], off
	v_lshl_add_u64 v[212:213], s[2:3], 0, v[132:133]
	s_mov_b32 m0, s50
	s_nop 0
	global_load_lds_dwordx4 v[212:213], off
	v_lshl_add_u64 v[212:213], s[2:3], 0, v[128:129]
	s_add_i32 m0, s50, 0x2000
	s_nop 0
	global_load_lds_dwordx4 v[212:213], off
	v_lshl_add_u64 v[212:213], v[234:235], 0, s[10:11]
	s_mov_b32 m0, s55
	s_nop 0
	global_load_lds_dwordx4 v[212:213], off
	v_lshl_add_u64 v[212:213], v[236:237], 0, s[10:11]
	s_mov_b32 m0, s56
	s_nop 0
	global_load_lds_dwordx4 v[212:213], off
	s_waitcnt vmcnt(8)
	s_waitcnt lgkmcnt(0)
	s_barrier
	s_setprio 1
	s_waitcnt lgkmcnt(0)
	v_mfma_f32_16x16x32_bf16 v[60:63], v[154:157], v[196:199], v[60:63]
	v_mfma_f32_16x16x32_bf16 v[56:59], v[172:175], v[196:199], v[56:59]
	v_mfma_f32_16x16x32_bf16 v[44:47], v[154:157], v[204:207], v[44:47]
	v_mfma_f32_16x16x32_bf16 v[40:43], v[172:175], v[204:207], v[40:43]
	v_mfma_f32_16x16x32_bf16 v[28:31], v[154:157], v[216:219], v[28:31]
	v_mfma_f32_16x16x32_bf16 v[24:27], v[172:175], v[216:219], v[24:27]
	v_mfma_f32_16x16x32_bf16 v[12:15], v[154:157], v[224:227], v[12:15]
	v_mfma_f32_16x16x32_bf16 v[8:11], v[172:175], v[224:227], v[8:11]
	v_mfma_f32_16x16x32_bf16 v[60:63], v[158:161], v[200:203], v[60:63]
	v_mfma_f32_16x16x32_bf16 v[56:59], v[176:179], v[200:203], v[56:59]
	v_mfma_f32_16x16x32_bf16 v[44:47], v[158:161], v[208:211], v[44:47]
	v_mfma_f32_16x16x32_bf16 v[40:43], v[176:179], v[208:211], v[40:43]
	v_mfma_f32_16x16x32_bf16 v[28:31], v[158:161], v[220:223], v[28:31]
	v_mfma_f32_16x16x32_bf16 v[24:27], v[176:179], v[220:223], v[24:27]
	v_mfma_f32_16x16x32_bf16 v[12:15], v[158:161], v[228:231], v[12:15]
	v_mfma_f32_16x16x32_bf16 v[8:11], v[176:179], v[228:231], v[8:11]
	s_setprio 0
	s_setprio 1
	v_mfma_f32_16x16x32_bf16 v[52:55], v[180:183], v[196:199], v[52:55]
	v_mfma_f32_16x16x32_bf16 v[48:51], v[188:191], v[196:199], v[48:51]
	v_mfma_f32_16x16x32_bf16 v[36:39], v[180:183], v[204:207], v[36:39]
	v_mfma_f32_16x16x32_bf16 v[32:35], v[188:191], v[204:207], v[32:35]
	v_mfma_f32_16x16x32_bf16 v[20:23], v[180:183], v[216:219], v[20:23]
	v_mfma_f32_16x16x32_bf16 v[16:19], v[188:191], v[216:219], v[16:19]
	v_mfma_f32_16x16x32_bf16 v[4:7], v[180:183], v[224:227], v[4:7]
	v_mfma_f32_16x16x32_bf16 v[0:3], v[188:191], v[224:227], v[0:3]
	v_mfma_f32_16x16x32_bf16 v[52:55], v[184:187], v[200:203], v[52:55]
	v_mfma_f32_16x16x32_bf16 v[48:51], v[192:195], v[200:203], v[48:51]
	v_mfma_f32_16x16x32_bf16 v[36:39], v[184:187], v[208:211], v[36:39]
	v_mfma_f32_16x16x32_bf16 v[32:35], v[192:195], v[208:211], v[32:35]
	v_mfma_f32_16x16x32_bf16 v[20:23], v[184:187], v[220:223], v[20:23]
	v_mfma_f32_16x16x32_bf16 v[16:19], v[192:195], v[220:223], v[16:19]
	v_mfma_f32_16x16x32_bf16 v[4:7], v[184:187], v[228:231], v[4:7]
	v_mfma_f32_16x16x32_bf16 v[0:3], v[192:195], v[228:231], v[0:3]
	s_setprio 0
	s_barrier
	s_add_i32 s64, s64, 2
	s_add_u32 s48, s48, 0x100
	s_addc_u32 s49, s49, 0
	s_add_u32 s62, s62, 0x100
	s_addc_u32 s63, s63, 0
	s_cmp_gt_u32 s64, 13
	s_cbranch_scc0 .LBB0_538
	s_mov_b32 s99, -2
	s_and_b64 vcc, exec, s[34:35]
	s_cbranch_vccz .LBB0_541
	s_barrier

.LBB0_601:
	s_lshl_b32 s7, s11, 5
	s_mov_b64 s[34:35], 0x80
	s_and_b32 s11, s7, 0x60
	s_add_i32 m0, s49, 0x18000
	v_lshl_add_u64 v[6:7], v[6:7], 0, s[34:35]
	s_lshl_b32 s38, s10, 13
	s_lshl_b32 s40, s11, 7
	s_waitcnt vmcnt(2)
	s_barrier
	global_load_lds_dwordx4 v[6:7], off
	v_lshl_add_u64 v[4:5], v[4:5], 0, s[34:35]
	s_add_i32 m0, s49, 0x1a000
	s_add_i32 s54, s49, 0x8000
	s_add_i32 s55, s49, 0xa000
	global_load_lds_dwordx4 v[4:5], off
	v_lshl_add_u64 v[0:1], v[0:1], 0, s[34:35]
	s_mov_b32 m0, s54
	s_add_u32 s36, s2, 0x40080
	global_load_lds_dwordx4 v[0:1], off
	v_lshl_add_u64 v[0:1], v[2:3], 0, s[34:35]
	s_mov_b32 m0, s55
	s_addc_u32 s37, s3, 0
	global_load_lds_dwordx4 v[0:1], off
	s_add_i32 m0, s49, 0x1c000
	v_lshl_add_u64 v[0:1], s[36:37], 0, v[164:165]
	global_load_lds_dwordx4 v[0:1], off
	v_lshl_add_u64 v[0:1], s[36:37], 0, v[160:161]
	s_add_i32 m0, s49, 0x1e000
	s_cmpk_lt_u32 s1, 0x100
	global_load_lds_dwordx4 v[0:1], off
	v_lshrrev_b32_e32 v1, 1, v9
	v_and_b32_e32 v1, 24, v1
	v_and_b32_e32 v0, 15, v9
	v_lshlrev_b32_e32 v2, 1, v1
	v_lshl_or_b32 v169, s10, 6, v0
	v_lshl_or_b32 v0, v0, 6, v2
	v_lshlrev_b32_e32 v2, 2, v9
	v_and_b32_e32 v2, 32, v2
	v_bitop3_b32 v3, v0, s38, v2 bitop3:0xde
	v_bitop3_b32 v171, v0, s40, v2 bitop3:0xde
	v_lshlrev_b32_e32 v0, 14, v13
	v_and_b32_e32 v0, 0xffff8000, v0
	v_or_b32_e32 v187, s11, v1
	v_lshl_add_u32 v0, v12, 11, v0
	v_and_b32_e32 v1, 1, v13
	v_lshl_or_b32 v0, v1, 6, v0
	v_lshl_add_u32 v172, v14, 1, v0
	v_lshlrev_b32_e32 v0, 14, v8
	v_and_b32_e32 v0, 0xffff8000, v0
	s_waitcnt vmcnt(6)
	s_mov_b32 s99, 0x7fff0000
	v_lshl_add_u32 v0, v10, 11, v0
	v_and_b32_e32 v1, 1, v8
	s_cselect_b64 s[36:37], -1, 0
	v_lshl_or_b32 v0, v1, 6, v0
	s_add_i32 s56, 0, 0x10000
	s_add_i32 s57, 0, 0x14000
	s_sext_i32_i8 s7, s0
	v_mov_b32_e32 v173, v165
	v_lshl_add_u32 v174, v11, 1, v0
	v_mov_b32_e32 v175, v165
	v_mov_b64_e32 v[176:177], 0x800
	v_mov_b64_e32 v[178:179], 0x7ff
	v_add_u32_e32 v197, s56, v171
	v_add_u32_e32 v205, s57, v171
	v_add_u32_e32 v211, 0, v3
	s_mov_b32 s38, 0x3a800000
	s_mov_b32 s58, 0xf800000
	v_mov_b32_e32 v217, 0x260
	s_barrier
	s_branch .LBB0_604

.LBB0_610:
	s_ashr_i32 s43, s42, 31
	s_lshl_b64 s[10:11], s[42:43], 19
	s_add_u32 s44, s26, s10
	s_addc_u32 s45, s27, s11
	s_and_b64 s[10:11], s[0:1], exec
	s_cselect_b32 s43, s45, s9
	s_cselect_b32 s59, s44, s8
	s_ashr_i32 s41, s40, 31
	s_lshl_b64 s[10:11], s[40:41], 19
	s_add_u32 s46, s33, s10
	s_addc_u32 s47, s39, s11
	s_and_b64 s[10:11], s[0:1], exec
	s_cselect_b32 s41, s47, s3
	s_cselect_b32 s60, s46, s2
	s_add_u32 s8, s8, 0x40080
	s_addc_u32 s9, s9, 0
	s_add_u32 s61, s2, 0x100
	v_mov_b32_e32 v0, 0
	s_addc_u32 s62, s3, 0
	s_mov_b32 s63, -2
	v_mov_b32_e32 v1, v0
	v_mov_b32_e32 v2, v0
	v_mov_b32_e32 v3, v0
	v_mov_b32_e32 v4, v0
	v_mov_b32_e32 v5, v0
	v_mov_b32_e32 v6, v0
	v_mov_b32_e32 v7, v0
	v_mov_b32_e32 v16, v0
	v_mov_b32_e32 v17, v0
	v_mov_b32_e32 v18, v0
	v_mov_b32_e32 v19, v0
	v_mov_b32_e32 v20, v0
	v_mov_b32_e32 v21, v0
	v_mov_b32_e32 v22, v0
	v_mov_b32_e32 v23, v0
	v_mov_b32_e32 v32, v0
	v_mov_b32_e32 v33, v0
	v_mov_b32_e32 v34, v0
	v_mov_b32_e32 v35, v0
	v_mov_b32_e32 v36, v0
	v_mov_b32_e32 v37, v0
	v_mov_b32_e32 v38, v0
	v_mov_b32_e32 v39, v0
	v_mov_b32_e32 v48, v0
	v_mov_b32_e32 v49, v0
	v_mov_b32_e32 v50, v0
	v_mov_b32_e32 v51, v0
	v_mov_b32_e32 v52, v0
	v_mov_b32_e32 v53, v0
	v_mov_b32_e32 v54, v0
	v_mov_b32_e32 v55, v0
	v_mov_b32_e32 v8, v0
	v_mov_b32_e32 v9, v0
	v_mov_b32_e32 v10, v0
	v_mov_b32_e32 v11, v0
	v_mov_b32_e32 v12, v0
	v_mov_b32_e32 v13, v0
	v_mov_b32_e32 v14, v0
	v_mov_b32_e32 v15, v0
	v_mov_b32_e32 v24, v0
	v_mov_b32_e32 v25, v0
	v_mov_b32_e32 v26, v0
	v_mov_b32_e32 v27, v0
	v_mov_b32_e32 v28, v0
	v_mov_b32_e32 v29, v0
	v_mov_b32_e32 v30, v0
	v_mov_b32_e32 v31, v0
	v_mov_b32_e32 v40, v0
	v_mov_b32_e32 v41, v0
	v_mov_b32_e32 v42, v0
	v_mov_b32_e32 v43, v0
	v_mov_b32_e32 v44, v0
	v_mov_b32_e32 v45, v0
	v_mov_b32_e32 v46, v0
	v_mov_b32_e32 v47, v0
	v_mov_b32_e32 v56, v0
	v_mov_b32_e32 v57, v0
	v_mov_b32_e32 v58, v0
	v_mov_b32_e32 v59, v0
	v_mov_b32_e32 v60, v0
	v_mov_b32_e32 v61, v0
	v_mov_b32_e32 v62, v0
	v_mov_b32_e32 v63, v0
	v_mov_b32_e32 v64, v0
	v_mov_b32_e32 v65, v0
	v_mov_b32_e32 v66, v0
	v_mov_b32_e32 v67, v0
	v_mov_b32_e32 v68, v0
	v_mov_b32_e32 v69, v0
	v_mov_b32_e32 v70, v0
	v_mov_b32_e32 v71, v0
	v_mov_b32_e32 v80, v0
	v_mov_b32_e32 v81, v0
	v_mov_b32_e32 v82, v0
	v_mov_b32_e32 v83, v0
	v_mov_b32_e32 v84, v0
	v_mov_b32_e32 v85, v0
	v_mov_b32_e32 v86, v0
	v_mov_b32_e32 v87, v0
	v_mov_b32_e32 v96, v0
	v_mov_b32_e32 v97, v0
	v_mov_b32_e32 v98, v0
	v_mov_b32_e32 v99, v0
	v_mov_b32_e32 v100, v0
	v_mov_b32_e32 v101, v0
	v_mov_b32_e32 v102, v0
	v_mov_b32_e32 v103, v0
	v_mov_b32_e32 v112, v0
	v_mov_b32_e32 v113, v0
	v_mov_b32_e32 v114, v0
	v_mov_b32_e32 v115, v0
	v_mov_b32_e32 v116, v0
	v_mov_b32_e32 v117, v0
	v_mov_b32_e32 v118, v0
	v_mov_b32_e32 v119, v0
	v_mov_b32_e32 v72, v0
	v_mov_b32_e32 v73, v0
	v_mov_b32_e32 v74, v0
	v_mov_b32_e32 v75, v0
	v_mov_b32_e32 v76, v0
	v_mov_b32_e32 v77, v0
	v_mov_b32_e32 v78, v0
	v_mov_b32_e32 v79, v0
	v_mov_b32_e32 v88, v0
	v_mov_b32_e32 v89, v0
	v_mov_b32_e32 v90, v0
	v_mov_b32_e32 v91, v0
	v_mov_b32_e32 v92, v0
	v_mov_b32_e32 v93, v0
	v_mov_b32_e32 v94, v0
	v_mov_b32_e32 v95, v0
	v_mov_b32_e32 v104, v0
	v_mov_b32_e32 v105, v0
	v_mov_b32_e32 v106, v0
	v_mov_b32_e32 v107, v0
	v_mov_b32_e32 v108, v0
	v_mov_b32_e32 v109, v0
	v_mov_b32_e32 v110, v0
	v_mov_b32_e32 v111, v0
	v_mov_b32_e32 v120, v0
	v_mov_b32_e32 v121, v0
	v_mov_b32_e32 v122, v0
	v_mov_b32_e32 v123, v0
	v_mov_b32_e32 v124, v0
	v_mov_b32_e32 v125, v0
	v_mov_b32_e32 v126, v0
	v_mov_b32_e32 v127, v0
.LBB0_611:
	ds_read_b128 v[128:131], v197
	ds_read_b128 v[132:135], v197 offset:1024
	ds_read_b128 v[136:139], v197 offset:2048
	ds_read_b128 v[140:143], v197 offset:3072
	ds_read_b128 v[144:147], v205
	ds_read_b128 v[148:151], v205 offset:1024
	ds_read_b128 v[152:155], v205 offset:2048
	ds_read_b128 v[156:159], v205 offset:3072
	s_add_u32 s2, s8, 0xfffc0080
	s_addc_u32 s3, s9, -1
	s_cmp_eq_u32 s63, 12
	s_cselect_b32 s11, s43, s3
	s_cselect_b32 s10, s59, s2
	s_cselect_b32 s3, s41, s62
	s_cselect_b32 s2, s60, s61
	v_lshl_add_u64 v[184:185], s[8:9], 0, v[172:173]
	s_add_i32 m0, s49, 0xc000
	ds_read_b128 v[180:183], v211
	ds_read_b128 v[188:191], v211 offset:1024
	ds_read_b128 v[192:195], v211 offset:2048
	ds_read_b128 v[198:201], v211 offset:3072
	ds_read_b128 v[206:209], v211 offset:4096
	ds_read_b128 v[218:221], v211 offset:5120
	ds_read_b128 v[222:225], v211 offset:6144
	ds_read_b128 v[226:229], v211 offset:7168
	global_load_lds_dwordx4 v[184:185], off
	v_lshl_add_u64 v[184:185], s[8:9], 0, v[174:175]
	s_add_i32 m0, s49, 0xe000
	s_nop 0
	global_load_lds_dwordx4 v[184:185], off
	s_cmp_eq_u32 s63, s99
	s_cbranch_scc1 .Ls1a_P6_0
	s_waitcnt vmcnt(8)
	s_branch .Ls1b_P6_0

.Ls1b_P6_0:
	s_waitcnt lgkmcnt(0)
	s_barrier
	s_setprio 1
	s_waitcnt lgkmcnt(0)
	v_mfma_f32_16x16x32_bf16 v[124:127], v[128:131], v[180:183], v[124:127]
	v_mfma_f32_16x16x32_bf16 v[120:123], v[136:139], v[180:183], v[120:123]
	v_mfma_f32_16x16x32_bf16 v[108:111], v[128:131], v[192:195], v[108:111]
	v_mfma_f32_16x16x32_bf16 v[104:107], v[136:139], v[192:195], v[104:107]
	v_mfma_f32_16x16x32_bf16 v[92:95], v[128:131], v[206:209], v[92:95]
	v_mfma_f32_16x16x32_bf16 v[88:91], v[136:139], v[206:209], v[88:91]
	v_mfma_f32_16x16x32_bf16 v[76:79], v[128:131], v[222:225], v[76:79]
	v_mfma_f32_16x16x32_bf16 v[72:75], v[136:139], v[222:225], v[72:75]
	v_mfma_f32_16x16x32_bf16 v[124:127], v[132:135], v[188:191], v[124:127]
	v_mfma_f32_16x16x32_bf16 v[120:123], v[140:143], v[188:191], v[120:123]
	v_mfma_f32_16x16x32_bf16 v[108:111], v[132:135], v[198:201], v[108:111]
	v_mfma_f32_16x16x32_bf16 v[104:107], v[140:143], v[198:201], v[104:107]
	v_mfma_f32_16x16x32_bf16 v[92:95], v[132:135], v[218:221], v[92:95]
	v_mfma_f32_16x16x32_bf16 v[88:91], v[140:143], v[218:221], v[88:91]
	v_mfma_f32_16x16x32_bf16 v[76:79], v[132:135], v[226:229], v[76:79]
	v_mfma_f32_16x16x32_bf16 v[72:75], v[140:143], v[226:229], v[72:75]
	s_setprio 0
	s_setprio 1
	v_mfma_f32_16x16x32_bf16 v[116:119], v[144:147], v[180:183], v[116:119]
	v_mfma_f32_16x16x32_bf16 v[112:115], v[152:155], v[180:183], v[112:115]
	v_mfma_f32_16x16x32_bf16 v[100:103], v[144:147], v[192:195], v[100:103]
	v_mfma_f32_16x16x32_bf16 v[96:99], v[152:155], v[192:195], v[96:99]
	v_mfma_f32_16x16x32_bf16 v[84:87], v[144:147], v[206:209], v[84:87]
	v_mfma_f32_16x16x32_bf16 v[80:83], v[152:155], v[206:209], v[80:83]
	v_mfma_f32_16x16x32_bf16 v[68:71], v[144:147], v[222:225], v[68:71]
	v_mfma_f32_16x16x32_bf16 v[64:67], v[152:155], v[222:225], v[64:67]
	v_mfma_f32_16x16x32_bf16 v[116:119], v[148:151], v[188:191], v[116:119]
	v_mfma_f32_16x16x32_bf16 v[112:115], v[156:159], v[188:191], v[112:115]
	v_mfma_f32_16x16x32_bf16 v[100:103], v[148:151], v[198:201], v[100:103]
	v_mfma_f32_16x16x32_bf16 v[96:99], v[156:159], v[198:201], v[96:99]
	v_mfma_f32_16x16x32_bf16 v[84:87], v[148:151], v[218:221], v[84:87]
	v_mfma_f32_16x16x32_bf16 v[80:83], v[156:159], v[218:221], v[80:83]
	v_mfma_f32_16x16x32_bf16 v[68:71], v[148:151], v[226:229], v[68:71]
	v_mfma_f32_16x16x32_bf16 v[64:67], v[156:159], v[226:229], v[64:67]
	s_setprio 0
	s_barrier
	s_add_i32 s64, s56, s48
	v_lshl_add_u64 v[184:185], s[2:3], 0, v[164:165]
	s_mov_b32 m0, s64
	ds_read_b128 v[180:183], v211 offset:16384
	ds_read_b128 v[188:191], v211 offset:17408
	ds_read_b128 v[192:195], v211 offset:18432
	ds_read_b128 v[198:201], v211 offset:19456
	ds_read_b128 v[206:209], v211 offset:20480
	ds_read_b128 v[218:221], v211 offset:21504
	ds_read_b128 v[222:225], v211 offset:22528
	ds_read_b128 v[226:229], v211 offset:23552
	global_load_lds_dwordx4 v[184:185], off
	s_add_i32 m0, s64, 0x2000
	s_add_u32 s64, s2, 0x40000
	v_lshl_add_u64 v[202:203], s[2:3], 0, v[160:161]
	s_addc_u32 s65, s3, 0
	s_add_i32 s66, s57, s48
	global_load_lds_dwordx4 v[202:203], off
	v_lshl_add_u64 v[212:213], s[64:65], 0, v[164:165]
	s_mov_b32 m0, s66
	v_lshl_add_u64 v[230:231], s[10:11], 0, v[162:163]
	global_load_lds_dwordx4 v[212:213], off
	v_lshl_add_u64 v[212:213], s[64:65], 0, v[160:161]
	s_add_i32 m0, s66, 0x2000
	s_nop 0
	global_load_lds_dwordx4 v[212:213], off
	v_lshl_add_u64 v[212:213], s[10:11], 0, v[166:167]
	s_mov_b32 m0, s49
	s_nop 0
	global_load_lds_dwordx4 v[212:213], off
	s_mov_b32 m0, s50
	s_nop 0
	global_load_lds_dwordx4 v[230:231], off
	s_cmp_eq_u32 s63, s99
	s_cbranch_scc1 .Ls1a_P6_1
	s_waitcnt vmcnt(8)
	s_branch .Ls1b_P6_1

.Ls1b_P6_1:
	s_waitcnt lgkmcnt(0)
	s_barrier
	s_setprio 1
	s_waitcnt lgkmcnt(0)
	v_mfma_f32_16x16x32_bf16 v[60:63], v[128:131], v[180:183], v[60:63]
	v_mfma_f32_16x16x32_bf16 v[56:59], v[136:139], v[180:183], v[56:59]
	v_mfma_f32_16x16x32_bf16 v[44:47], v[128:131], v[192:195], v[44:47]
	v_mfma_f32_16x16x32_bf16 v[40:43], v[136:139], v[192:195], v[40:43]
	v_mfma_f32_16x16x32_bf16 v[28:31], v[128:131], v[206:209], v[28:31]
	v_mfma_f32_16x16x32_bf16 v[24:27], v[136:139], v[206:209], v[24:27]
	v_mfma_f32_16x16x32_bf16 v[12:15], v[128:131], v[222:225], v[12:15]
	v_mfma_f32_16x16x32_bf16 v[8:11], v[136:139], v[222:225], v[8:11]
	v_mfma_f32_16x16x32_bf16 v[60:63], v[132:135], v[188:191], v[60:63]
	v_mfma_f32_16x16x32_bf16 v[56:59], v[140:143], v[188:191], v[56:59]
	v_mfma_f32_16x16x32_bf16 v[44:47], v[132:135], v[198:201], v[44:47]
	v_mfma_f32_16x16x32_bf16 v[40:43], v[140:143], v[198:201], v[40:43]
	v_mfma_f32_16x16x32_bf16 v[28:31], v[132:135], v[218:221], v[28:31]
	v_mfma_f32_16x16x32_bf16 v[24:27], v[140:143], v[218:221], v[24:27]
	v_mfma_f32_16x16x32_bf16 v[12:15], v[132:135], v[226:229], v[12:15]
	v_mfma_f32_16x16x32_bf16 v[8:11], v[140:143], v[226:229], v[8:11]
	s_setprio 0
	s_setprio 1
	v_mfma_f32_16x16x32_bf16 v[52:55], v[144:147], v[180:183], v[52:55]
	v_mfma_f32_16x16x32_bf16 v[48:51], v[152:155], v[180:183], v[48:51]
	v_mfma_f32_16x16x32_bf16 v[36:39], v[144:147], v[192:195], v[36:39]
	v_mfma_f32_16x16x32_bf16 v[32:35], v[152:155], v[192:195], v[32:35]
	v_mfma_f32_16x16x32_bf16 v[20:23], v[144:147], v[206:209], v[20:23]
	v_mfma_f32_16x16x32_bf16 v[16:19], v[152:155], v[206:209], v[16:19]
	v_mfma_f32_16x16x32_bf16 v[4:7], v[144:147], v[222:225], v[4:7]
	v_mfma_f32_16x16x32_bf16 v[0:3], v[152:155], v[222:225], v[0:3]
	v_mfma_f32_16x16x32_bf16 v[52:55], v[148:151], v[188:191], v[52:55]
	v_mfma_f32_16x16x32_bf16 v[48:51], v[156:159], v[188:191], v[48:51]
	v_mfma_f32_16x16x32_bf16 v[36:39], v[148:151], v[198:201], v[36:39]
	v_mfma_f32_16x16x32_bf16 v[32:35], v[156:159], v[198:201], v[32:35]
	v_mfma_f32_16x16x32_bf16 v[20:23], v[148:151], v[218:221], v[20:23]
	v_mfma_f32_16x16x32_bf16 v[16:19], v[156:159], v[218:221], v[16:19]
	v_mfma_f32_16x16x32_bf16 v[4:7], v[148:151], v[226:229], v[4:7]
	v_mfma_f32_16x16x32_bf16 v[0:3], v[156:159], v[226:229], v[0:3]
	s_setprio 0
	s_barrier
	s_add_i32 s64, 0, 0x18000
	s_add_i32 s65, 0, 0x1c000
	v_add_u32_e32 v140, s64, v171
	v_add_u32_e32 v156, s65, v171
	ds_read_b128 v[128:131], v140
	ds_read_b128 v[132:135], v140 offset:1024
	ds_read_b128 v[136:139], v140 offset:2048
	ds_read_b128 v[140:143], v140 offset:3072
	ds_read_b128 v[144:147], v156
	ds_read_b128 v[148:151], v156 offset:1024
	ds_read_b128 v[152:155], v156 offset:2048
	ds_read_b128 v[156:159], v156 offset:3072
	s_add_u32 s10, s10, 0x40000
	s_addc_u32 s11, s11, 0
	s_mov_b32 m0, s51
	v_lshl_add_u64 v[232:233], s[10:11], 0, v[166:167]
	ds_read_b128 v[180:183], v211 offset:32768
	ds_read_b128 v[188:191], v211 offset:33792
	ds_read_b128 v[192:195], v211 offset:34816
	ds_read_b128 v[198:201], v211 offset:35840
	ds_read_b128 v[206:209], v211 offset:36864
	ds_read_b128 v[218:221], v211 offset:37888
	ds_read_b128 v[222:225], v211 offset:38912
	ds_read_b128 v[226:229], v211 offset:39936
	global_load_lds_dwordx4 v[232:233], off
	v_lshl_add_u64 v[232:233], s[10:11], 0, v[162:163]
	s_mov_b32 m0, s52
	s_nop 0
	global_load_lds_dwordx4 v[232:233], off
	s_waitcnt vmcnt(8)
	s_waitcnt lgkmcnt(0)
	s_barrier
	s_setprio 1
	s_waitcnt lgkmcnt(0)
	v_mfma_f32_16x16x32_bf16 v[124:127], v[128:131], v[180:183], v[124:127]
	v_mfma_f32_16x16x32_bf16 v[120:123], v[136:139], v[180:183], v[120:123]
	v_mfma_f32_16x16x32_bf16 v[108:111], v[128:131], v[192:195], v[108:111]
	v_mfma_f32_16x16x32_bf16 v[104:107], v[136:139], v[192:195], v[104:107]
	v_mfma_f32_16x16x32_bf16 v[92:95], v[128:131], v[206:209], v[92:95]
	v_mfma_f32_16x16x32_bf16 v[88:91], v[136:139], v[206:209], v[88:91]
	v_mfma_f32_16x16x32_bf16 v[76:79], v[128:131], v[222:225], v[76:79]
	v_mfma_f32_16x16x32_bf16 v[72:75], v[136:139], v[222:225], v[72:75]
	v_mfma_f32_16x16x32_bf16 v[124:127], v[132:135], v[188:191], v[124:127]
	v_mfma_f32_16x16x32_bf16 v[120:123], v[140:143], v[188:191], v[120:123]
	v_mfma_f32_16x16x32_bf16 v[108:111], v[132:135], v[198:201], v[108:111]
	v_mfma_f32_16x16x32_bf16 v[104:107], v[140:143], v[198:201], v[104:107]
	v_mfma_f32_16x16x32_bf16 v[92:95], v[132:135], v[218:221], v[92:95]
	v_mfma_f32_16x16x32_bf16 v[88:91], v[140:143], v[218:221], v[88:91]
	v_mfma_f32_16x16x32_bf16 v[76:79], v[132:135], v[226:229], v[76:79]
	v_mfma_f32_16x16x32_bf16 v[72:75], v[140:143], v[226:229], v[72:75]
	s_setprio 0
	s_setprio 1
	v_mfma_f32_16x16x32_bf16 v[116:119], v[144:147], v[180:183], v[116:119]
	v_mfma_f32_16x16x32_bf16 v[112:115], v[152:155], v[180:183], v[112:115]
	v_mfma_f32_16x16x32_bf16 v[100:103], v[144:147], v[192:195], v[100:103]
	v_mfma_f32_16x16x32_bf16 v[96:99], v[152:155], v[192:195], v[96:99]
	v_mfma_f32_16x16x32_bf16 v[84:87], v[144:147], v[206:209], v[84:87]
	v_mfma_f32_16x16x32_bf16 v[80:83], v[152:155], v[206:209], v[80:83]
	v_mfma_f32_16x16x32_bf16 v[68:71], v[144:147], v[222:225], v[68:71]
	v_mfma_f32_16x16x32_bf16 v[64:67], v[152:155], v[222:225], v[64:67]
	v_mfma_f32_16x16x32_bf16 v[116:119], v[148:151], v[188:191], v[116:119]
	v_mfma_f32_16x16x32_bf16 v[112:115], v[156:159], v[188:191], v[112:115]
	v_mfma_f32_16x16x32_bf16 v[100:103], v[148:151], v[198:201], v[100:103]
	v_mfma_f32_16x16x32_bf16 v[96:99], v[156:159], v[198:201], v[96:99]
	v_mfma_f32_16x16x32_bf16 v[84:87], v[148:151], v[218:221], v[84:87]
	v_mfma_f32_16x16x32_bf16 v[80:83], v[156:159], v[218:221], v[80:83]
	v_mfma_f32_16x16x32_bf16 v[68:71], v[148:151], v[226:229], v[68:71]
	v_mfma_f32_16x16x32_bf16 v[64:67], v[156:159], v[226:229], v[64:67]
	s_setprio 0
	s_barrier
	s_add_i32 s10, s64, s48
	v_lshl_add_u64 v[184:185], v[184:185], 0, s[34:35]
	s_mov_b32 m0, s10
	ds_read_b128 v[180:183], v211 offset:49152
	ds_read_b128 v[188:191], v211 offset:50176
	ds_read_b128 v[192:195], v211 offset:51200
	ds_read_b128 v[198:201], v211 offset:52224
	ds_read_b128 v[206:209], v211 offset:53248
	ds_read_b128 v[218:221], v211 offset:54272
	ds_read_b128 v[222:225], v211 offset:55296
	ds_read_b128 v[226:229], v211 offset:56320
	global_load_lds_dwordx4 v[184:185], off
	s_add_i32 m0, s10, 0x2000
	s_add_u32 s2, s2, 0x40080
	v_lshl_add_u64 v[184:185], v[202:203], 0, s[34:35]
	s_addc_u32 s3, s3, 0
	s_add_i32 s10, s65, s48
	global_load_lds_dwordx4 v[184:185], off
	v_lshl_add_u64 v[184:185], s[2:3], 0, v[164:165]
	s_mov_b32 m0, s10
	s_nop 0
	global_load_lds_dwordx4 v[184:185], off
	v_lshl_add_u64 v[184:185], s[2:3], 0, v[160:161]
	s_add_i32 m0, s10, 0x2000
	s_nop 0
	global_load_lds_dwordx4 v[184:185], off
	v_lshl_add_u64 v[184:185], v[212:213], 0, s[34:35]
	s_mov_b32 m0, s54
	s_nop 0
	global_load_lds_dwordx4 v[184:185], off
	v_lshl_add_u64 v[184:185], v[230:231], 0, s[34:35]
	s_mov_b32 m0, s55
	s_nop 0
	global_load_lds_dwordx4 v[184:185], off
	s_waitcnt vmcnt(8)
	s_waitcnt lgkmcnt(0)
	s_barrier
	s_setprio 1
	s_waitcnt lgkmcnt(0)
	v_mfma_f32_16x16x32_bf16 v[60:63], v[128:131], v[180:183], v[60:63]
	v_mfma_f32_16x16x32_bf16 v[56:59], v[136:139], v[180:183], v[56:59]
	v_mfma_f32_16x16x32_bf16 v[44:47], v[128:131], v[192:195], v[44:47]
	v_mfma_f32_16x16x32_bf16 v[40:43], v[136:139], v[192:195], v[40:43]
	v_mfma_f32_16x16x32_bf16 v[28:31], v[128:131], v[206:209], v[28:31]
	v_mfma_f32_16x16x32_bf16 v[24:27], v[136:139], v[206:209], v[24:27]
	v_mfma_f32_16x16x32_bf16 v[12:15], v[128:131], v[222:225], v[12:15]
	v_mfma_f32_16x16x32_bf16 v[8:11], v[136:139], v[222:225], v[8:11]
	v_mfma_f32_16x16x32_bf16 v[60:63], v[132:135], v[188:191], v[60:63]
	v_mfma_f32_16x16x32_bf16 v[56:59], v[140:143], v[188:191], v[56:59]
	v_mfma_f32_16x16x32_bf16 v[44:47], v[132:135], v[198:201], v[44:47]
	v_mfma_f32_16x16x32_bf16 v[40:43], v[140:143], v[198:201], v[40:43]
	v_mfma_f32_16x16x32_bf16 v[28:31], v[132:135], v[218:221], v[28:31]
	v_mfma_f32_16x16x32_bf16 v[24:27], v[140:143], v[218:221], v[24:27]
	v_mfma_f32_16x16x32_bf16 v[12:15], v[132:135], v[226:229], v[12:15]
	v_mfma_f32_16x16x32_bf16 v[8:11], v[140:143], v[226:229], v[8:11]
	s_setprio 0
	s_setprio 1
	v_mfma_f32_16x16x32_bf16 v[52:55], v[144:147], v[180:183], v[52:55]
	v_mfma_f32_16x16x32_bf16 v[48:51], v[152:155], v[180:183], v[48:51]
	v_mfma_f32_16x16x32_bf16 v[36:39], v[144:147], v[192:195], v[36:39]
	v_mfma_f32_16x16x32_bf16 v[32:35], v[152:155], v[192:195], v[32:35]
	v_mfma_f32_16x16x32_bf16 v[20:23], v[144:147], v[206:209], v[20:23]
	v_mfma_f32_16x16x32_bf16 v[16:19], v[152:155], v[206:209], v[16:19]
	v_mfma_f32_16x16x32_bf16 v[4:7], v[144:147], v[222:225], v[4:7]
	v_mfma_f32_16x16x32_bf16 v[0:3], v[152:155], v[222:225], v[0:3]
	v_mfma_f32_16x16x32_bf16 v[52:55], v[148:151], v[188:191], v[52:55]
	v_mfma_f32_16x16x32_bf16 v[48:51], v[156:159], v[188:191], v[48:51]
	v_mfma_f32_16x16x32_bf16 v[36:39], v[148:151], v[198:201], v[36:39]
	v_mfma_f32_16x16x32_bf16 v[32:35], v[156:159], v[198:201], v[32:35]
	v_mfma_f32_16x16x32_bf16 v[20:23], v[148:151], v[218:221], v[20:23]
	v_mfma_f32_16x16x32_bf16 v[16:19], v[156:159], v[218:221], v[16:19]
	v_mfma_f32_16x16x32_bf16 v[4:7], v[148:151], v[226:229], v[4:7]
	v_mfma_f32_16x16x32_bf16 v[0:3], v[156:159], v[226:229], v[0:3]
	s_setprio 0
	s_barrier
	s_add_i32 s63, s63, 2
	s_add_u32 s8, s8, 0x100
	s_addc_u32 s9, s9, 0
	s_add_u32 s61, s61, 0x100
	s_addc_u32 s62, s62, 0
	s_cmp_gt_u32 s63, 13
	s_cbranch_scc0 .LBB0_611
	s_mov_b32 s99, -2
	s_and_b64 vcc, exec, s[36:37]
	s_cbranch_vccz .LBB0_614
	s_barrier

.LBB0_674:
	s_lshl_b32 s1, s9, 5
	s_mov_b64 s[34:35], 0x80
	s_and_b32 s9, s1, 0x60
	s_add_i32 m0, s54, 0x18000
	v_lshl_add_u64 v[6:7], v[6:7], 0, s[34:35]
	s_lshl_b32 s38, s8, 13
	s_lshl_b32 s40, s9, 7
	s_waitcnt vmcnt(2)
	s_barrier
	global_load_lds_dwordx4 v[6:7], off
	v_lshl_add_u64 v[4:5], v[4:5], 0, s[34:35]
	s_add_i32 m0, s54, 0x1a000
	s_add_i32 s59, s54, 0x8000
	s_add_i32 s60, s54, 0xa000
	global_load_lds_dwordx4 v[4:5], off
	v_lshl_add_u64 v[0:1], v[0:1], 0, s[34:35]
	s_mov_b32 m0, s59
	s_add_u32 s36, s2, 0x100080
	global_load_lds_dwordx4 v[0:1], off
	v_lshl_add_u64 v[0:1], v[2:3], 0, s[34:35]
	s_mov_b32 m0, s60
	s_addc_u32 s37, s3, 0
	global_load_lds_dwordx4 v[0:1], off
	s_add_i32 m0, s54, 0x1c000
	v_lshl_add_u64 v[0:1], s[36:37], 0, v[176:177]
	global_load_lds_dwordx4 v[0:1], off
	v_lshl_add_u64 v[0:1], s[36:37], 0, v[172:173]
	s_add_i32 m0, s54, 0x1e000
	v_bfe_u32 v2, v10, 4, 2
	global_load_lds_dwordx4 v[0:1], off
	v_and_b32_e32 v0, 15, v10
	v_lshlrev_b32_e32 v1, 4, v2
	v_lshl_or_b32 v169, s8, 6, v0
	v_lshl_or_b32 v0, v0, 6, v1
	v_lshlrev_b32_e32 v1, 2, v10
	v_and_b32_e32 v1, 32, v1
	v_bitop3_b32 v3, v0, s38, v1 bitop3:0xde
	v_bitop3_b32 v171, v0, s40, v1 bitop3:0xde
	v_cmp_lt_u32_e32 vcc, 1, v2
	v_mov_b32_e32 v1, 0x80
	v_mov_b32_e32 v4, 0x90
	v_bfe_u32 v0, v10, 4, 1
	v_cndmask_b32_e32 v187, v1, v4, vcc
	v_mov_b32_e32 v1, 0xa0
	v_mov_b32_e32 v4, 0xb0
	s_sext_i32_i8 s1, s6
	s_cmpk_lt_u32 s7, 0x100
	v_cmp_eq_u32_e64 s[6:7], 0, v0
	v_cndmask_b32_e32 v210, v1, v4, vcc
	v_lshlrev_b32_e32 v0, 2, v0
	v_mov_b32_e32 v1, v177
	v_lshl_add_u64 v[188:189], s[10:11], 0, v[0:1]
	v_lshlrev_b32_e32 v0, 16, v13
	v_and_b32_e32 v0, 0xfffe0000, v0
	v_lshl_add_u32 v0, v12, 13, v0
	v_and_b32_e32 v1, 1, v13
	v_lshl_or_b32 v0, v1, 6, v0
	v_lshl_add_u32 v190, v14, 1, v0
	v_lshlrev_b32_e32 v0, 16, v8
	v_and_b32_e32 v0, 0xfffe0000, v0
	v_lshl_add_u32 v0, v9, 13, v0
	v_and_b32_e32 v1, 1, v8
	s_waitcnt vmcnt(6)
	s_mov_b32 s99, 0x7fff0000
	v_lshl_or_b32 v0, v1, 6, v0
	s_cselect_b64 s[36:37], -1, 0
	v_lshl_add_u32 v192, v11, 1, v0
	s_add_i32 s61, 0, 0x10000
	s_add_i32 s62, 0, 0x14000
	v_mbcnt_lo_u32_b32 v0, -1, 0
	v_cndmask_b32_e64 v180, 0, 1, vcc
	v_mov_b32_e32 v181, s58
	v_cndmask_b32_e64 v182, 2, 3, vcc
	v_cndmask_b32_e64 v183, 0, 16, vcc
	v_cndmask_b32_e64 v184, 4, 5, vcc
	v_cndmask_b32_e64 v185, 32, 48, vcc
	v_cndmask_b32_e64 v186, 6, 7, vcc
	v_lshl_or_b32 v211, v2, 3, s9
	v_mov_b32_e32 v191, v177
	v_mov_b32_e32 v193, v177
	s_waitcnt vmcnt(0)
	v_mov_b64_e32 v[194:195], 0x200
	v_mov_b64_e32 v[196:197], 0x1ff
	v_add_u32_e32 v212, s61, v171
	v_add_u32_e32 v213, s62, v171
	v_add_u32_e32 v214, 0, v3
	v_mbcnt_hi_u32_b32 v216, -1, v0
	s_mov_b32 s38, 0x3a800000
	s_mov_b32 s63, 0xf800000
	v_mov_b32_e32 v217, 0x260
	s_mov_b32 s40, 0x3fb504f3
	s_barrier
	s_branch .LBB0_677

.LBB0_684:
	ds_read_b128 v[64:67], v212
	ds_read_b128 v[68:71], v212 offset:1024
	ds_read_b128 v[72:75], v212 offset:2048
	ds_read_b128 v[76:79], v212 offset:3072
	ds_read_b128 v[88:91], v213
	ds_read_b128 v[92:95], v213 offset:1024
	ds_read_b128 v[96:99], v213 offset:2048
	ds_read_b128 v[100:103], v213 offset:3072
	s_add_u32 s2, s50, 0xfff00080
	s_addc_u32 s3, s51, -1
	s_cmp_eq_u32 s68, 60
	s_cselect_b32 s53, s45, s3
	s_cselect_b32 s52, s64, s2
	s_cselect_b32 s3, s43, s67
	s_cselect_b32 s2, s65, s66
	v_lshl_add_u64 v[230:231], s[50:51], 0, v[190:191]
	s_add_i32 m0, s54, 0xc000
	ds_read_b128 v[160:163], v214
	ds_read_b128 v[164:167], v214 offset:1024
	ds_read_b128 v[198:201], v214 offset:2048
	ds_read_b128 v[202:205], v214 offset:3072
	ds_read_b128 v[206:209], v214 offset:4096
	ds_read_b128 v[218:221], v214 offset:5120
	ds_read_b128 v[222:225], v214 offset:6144
	ds_read_b128 v[226:229], v214 offset:7168
	global_load_lds_dwordx4 v[230:231], off
	v_lshl_add_u64 v[230:231], s[50:51], 0, v[192:193]
	s_add_i32 m0, s54, 0xe000
	s_nop 0
	global_load_lds_dwordx4 v[230:231], off
	s_cmp_eq_u32 s68, s99
	s_cbranch_scc1 .Ls1a_P7_0
	s_waitcnt vmcnt(8)
	s_branch .Ls1b_P7_0

.Ls1b_P7_0:
	s_waitcnt lgkmcnt(0)
	s_barrier
	s_setprio 1
	s_waitcnt lgkmcnt(0)
	v_mfma_f32_16x16x32_bf16 v[156:159], v[64:67], v[160:163], v[156:159]
	v_mfma_f32_16x16x32_bf16 v[152:155], v[72:75], v[160:163], v[152:155]
	v_mfma_f32_16x16x32_bf16 v[140:143], v[64:67], v[198:201], v[140:143]
	v_mfma_f32_16x16x32_bf16 v[136:139], v[72:75], v[198:201], v[136:139]
	v_mfma_f32_16x16x32_bf16 v[124:127], v[64:67], v[206:209], v[124:127]
	v_mfma_f32_16x16x32_bf16 v[120:123], v[72:75], v[206:209], v[120:123]
	v_mfma_f32_16x16x32_bf16 v[108:111], v[64:67], v[222:225], v[108:111]
	v_mfma_f32_16x16x32_bf16 v[104:107], v[72:75], v[222:225], v[104:107]
	v_mfma_f32_16x16x32_bf16 v[156:159], v[68:71], v[164:167], v[156:159]
	v_mfma_f32_16x16x32_bf16 v[152:155], v[76:79], v[164:167], v[152:155]
	v_mfma_f32_16x16x32_bf16 v[140:143], v[68:71], v[202:205], v[140:143]
	v_mfma_f32_16x16x32_bf16 v[136:139], v[76:79], v[202:205], v[136:139]
	v_mfma_f32_16x16x32_bf16 v[124:127], v[68:71], v[218:221], v[124:127]
	v_mfma_f32_16x16x32_bf16 v[120:123], v[76:79], v[218:221], v[120:123]
	v_mfma_f32_16x16x32_bf16 v[108:111], v[68:71], v[226:229], v[108:111]
	v_mfma_f32_16x16x32_bf16 v[104:107], v[76:79], v[226:229], v[104:107]
	s_setprio 0
	s_setprio 1
	v_mfma_f32_16x16x32_bf16 v[148:151], v[88:91], v[160:163], v[148:151]
	v_mfma_f32_16x16x32_bf16 v[144:147], v[96:99], v[160:163], v[144:147]
	v_mfma_f32_16x16x32_bf16 v[132:135], v[88:91], v[198:201], v[132:135]
	v_mfma_f32_16x16x32_bf16 v[128:131], v[96:99], v[198:201], v[128:131]
	v_mfma_f32_16x16x32_bf16 v[116:119], v[88:91], v[206:209], v[116:119]
	v_mfma_f32_16x16x32_bf16 v[112:115], v[96:99], v[206:209], v[112:115]
	v_mfma_f32_16x16x32_bf16 v[84:87], v[88:91], v[222:225], v[84:87]
	v_mfma_f32_16x16x32_bf16 v[80:83], v[96:99], v[222:225], v[80:83]
	v_mfma_f32_16x16x32_bf16 v[148:151], v[92:95], v[164:167], v[148:151]
	v_mfma_f32_16x16x32_bf16 v[144:147], v[100:103], v[164:167], v[144:147]
	v_mfma_f32_16x16x32_bf16 v[132:135], v[92:95], v[202:205], v[132:135]
	v_mfma_f32_16x16x32_bf16 v[128:131], v[100:103], v[202:205], v[128:131]
	v_mfma_f32_16x16x32_bf16 v[116:119], v[92:95], v[218:221], v[116:119]
	v_mfma_f32_16x16x32_bf16 v[112:115], v[100:103], v[218:221], v[112:115]
	v_mfma_f32_16x16x32_bf16 v[84:87], v[92:95], v[226:229], v[84:87]
	v_mfma_f32_16x16x32_bf16 v[80:83], v[100:103], v[226:229], v[80:83]
	s_setprio 0
	s_barrier
	s_add_i32 s69, s61, s41
	v_lshl_add_u64 v[230:231], s[2:3], 0, v[176:177]
	s_mov_b32 m0, s69
	ds_read_b128 v[160:163], v214 offset:16384
	ds_read_b128 v[164:167], v214 offset:17408
	ds_read_b128 v[198:201], v214 offset:18432
	ds_read_b128 v[202:205], v214 offset:19456
	ds_read_b128 v[206:209], v214 offset:20480
	ds_read_b128 v[218:221], v214 offset:21504
	ds_read_b128 v[222:225], v214 offset:22528
	ds_read_b128 v[226:229], v214 offset:23552
	global_load_lds_dwordx4 v[230:231], off
	s_add_i32 m0, s69, 0x2000
	s_add_u32 s70, s2, 0x100000
	v_lshl_add_u64 v[232:233], s[2:3], 0, v[172:173]
	s_addc_u32 s71, s3, 0
	s_add_i32 s69, s62, s41
	global_load_lds_dwordx4 v[232:233], off
	v_lshl_add_u64 v[234:235], s[70:71], 0, v[176:177]
	s_mov_b32 m0, s69
	v_lshl_add_u64 v[236:237], s[52:53], 0, v[174:175]
	global_load_lds_dwordx4 v[234:235], off
	v_lshl_add_u64 v[234:235], s[70:71], 0, v[172:173]
	s_add_i32 m0, s69, 0x2000
	s_nop 0
	global_load_lds_dwordx4 v[234:235], off
	v_lshl_add_u64 v[234:235], s[52:53], 0, v[178:179]
	s_mov_b32 m0, s54
	s_nop 0
	global_load_lds_dwordx4 v[234:235], off
	s_mov_b32 m0, s55
	s_nop 0
	global_load_lds_dwordx4 v[236:237], off
	s_cmp_eq_u32 s68, s99
	s_cbranch_scc1 .Ls1a_P7_1
	s_waitcnt vmcnt(8)
	s_branch .Ls1b_P7_1

.Ls1b_P7_1:
	s_waitcnt lgkmcnt(0)
	s_barrier
	s_setprio 1
	s_waitcnt lgkmcnt(0)
	v_mfma_f32_16x16x32_bf16 v[60:63], v[64:67], v[160:163], v[60:63]
	v_mfma_f32_16x16x32_bf16 v[56:59], v[72:75], v[160:163], v[56:59]
	v_mfma_f32_16x16x32_bf16 v[44:47], v[64:67], v[198:201], v[44:47]
	v_mfma_f32_16x16x32_bf16 v[40:43], v[72:75], v[198:201], v[40:43]
	v_mfma_f32_16x16x32_bf16 v[28:31], v[64:67], v[206:209], v[28:31]
	v_mfma_f32_16x16x32_bf16 v[24:27], v[72:75], v[206:209], v[24:27]
	v_mfma_f32_16x16x32_bf16 v[12:15], v[64:67], v[222:225], v[12:15]
	v_mfma_f32_16x16x32_bf16 v[8:11], v[72:75], v[222:225], v[8:11]
	v_mfma_f32_16x16x32_bf16 v[60:63], v[68:71], v[164:167], v[60:63]
	v_mfma_f32_16x16x32_bf16 v[56:59], v[76:79], v[164:167], v[56:59]
	v_mfma_f32_16x16x32_bf16 v[44:47], v[68:71], v[202:205], v[44:47]
	v_mfma_f32_16x16x32_bf16 v[40:43], v[76:79], v[202:205], v[40:43]
	v_mfma_f32_16x16x32_bf16 v[28:31], v[68:71], v[218:221], v[28:31]
	v_mfma_f32_16x16x32_bf16 v[24:27], v[76:79], v[218:221], v[24:27]
	v_mfma_f32_16x16x32_bf16 v[12:15], v[68:71], v[226:229], v[12:15]
	v_mfma_f32_16x16x32_bf16 v[8:11], v[76:79], v[226:229], v[8:11]
	s_setprio 0
	s_setprio 1
	v_mfma_f32_16x16x32_bf16 v[52:55], v[88:91], v[160:163], v[52:55]
	v_mfma_f32_16x16x32_bf16 v[48:51], v[96:99], v[160:163], v[48:51]
	v_mfma_f32_16x16x32_bf16 v[36:39], v[88:91], v[198:201], v[36:39]
	v_mfma_f32_16x16x32_bf16 v[32:35], v[96:99], v[198:201], v[32:35]
	v_mfma_f32_16x16x32_bf16 v[20:23], v[88:91], v[206:209], v[20:23]
	v_mfma_f32_16x16x32_bf16 v[16:19], v[96:99], v[206:209], v[16:19]
	v_mfma_f32_16x16x32_bf16 v[4:7], v[88:91], v[222:225], v[4:7]
	v_mfma_f32_16x16x32_bf16 v[0:3], v[96:99], v[222:225], v[0:3]
	v_mfma_f32_16x16x32_bf16 v[52:55], v[92:95], v[164:167], v[52:55]
	v_mfma_f32_16x16x32_bf16 v[48:51], v[100:103], v[164:167], v[48:51]
	v_mfma_f32_16x16x32_bf16 v[36:39], v[92:95], v[202:205], v[36:39]
	v_mfma_f32_16x16x32_bf16 v[32:35], v[100:103], v[202:205], v[32:35]
	v_mfma_f32_16x16x32_bf16 v[20:23], v[92:95], v[218:221], v[20:23]
	v_mfma_f32_16x16x32_bf16 v[16:19], v[100:103], v[218:221], v[16:19]
	v_mfma_f32_16x16x32_bf16 v[4:7], v[92:95], v[226:229], v[4:7]
	v_mfma_f32_16x16x32_bf16 v[0:3], v[100:103], v[226:229], v[0:3]
	s_setprio 0
	s_barrier
	s_add_i32 s69, 0, 0x18000
	s_add_i32 s70, 0, 0x1c000
	v_add_u32_e32 v76, s69, v171
	v_add_u32_e32 v100, s70, v171
	ds_read_b128 v[64:67], v76
	ds_read_b128 v[68:71], v76 offset:1024
	ds_read_b128 v[72:75], v76 offset:2048
	ds_read_b128 v[76:79], v76 offset:3072
	ds_read_b128 v[88:91], v100
	ds_read_b128 v[92:95], v100 offset:1024
	ds_read_b128 v[96:99], v100 offset:2048
	ds_read_b128 v[100:103], v100 offset:3072
	s_add_u32 s52, s52, 0x100000
	s_addc_u32 s53, s53, 0
	s_mov_b32 m0, s56
	v_lshl_add_u64 v[238:239], s[52:53], 0, v[178:179]
	ds_read_b128 v[160:163], v214 offset:32768
	ds_read_b128 v[164:167], v214 offset:33792
	ds_read_b128 v[198:201], v214 offset:34816
	ds_read_b128 v[202:205], v214 offset:35840
	ds_read_b128 v[206:209], v214 offset:36864
	ds_read_b128 v[218:221], v214 offset:37888
	ds_read_b128 v[222:225], v214 offset:38912
	ds_read_b128 v[226:229], v214 offset:39936
	global_load_lds_dwordx4 v[238:239], off
	v_lshl_add_u64 v[238:239], s[52:53], 0, v[174:175]
	s_mov_b32 m0, s57
	s_nop 0
	global_load_lds_dwordx4 v[238:239], off
	s_waitcnt vmcnt(8)
	s_waitcnt lgkmcnt(0)
	s_barrier
	s_setprio 1
	s_waitcnt lgkmcnt(0)
	v_mfma_f32_16x16x32_bf16 v[156:159], v[64:67], v[160:163], v[156:159]
	v_mfma_f32_16x16x32_bf16 v[152:155], v[72:75], v[160:163], v[152:155]
	v_mfma_f32_16x16x32_bf16 v[140:143], v[64:67], v[198:201], v[140:143]
	v_mfma_f32_16x16x32_bf16 v[136:139], v[72:75], v[198:201], v[136:139]
	v_mfma_f32_16x16x32_bf16 v[124:127], v[64:67], v[206:209], v[124:127]
	v_mfma_f32_16x16x32_bf16 v[120:123], v[72:75], v[206:209], v[120:123]
	v_mfma_f32_16x16x32_bf16 v[108:111], v[64:67], v[222:225], v[108:111]
	v_mfma_f32_16x16x32_bf16 v[104:107], v[72:75], v[222:225], v[104:107]
	v_mfma_f32_16x16x32_bf16 v[156:159], v[68:71], v[164:167], v[156:159]
	v_mfma_f32_16x16x32_bf16 v[152:155], v[76:79], v[164:167], v[152:155]
	v_mfma_f32_16x16x32_bf16 v[140:143], v[68:71], v[202:205], v[140:143]
	v_mfma_f32_16x16x32_bf16 v[136:139], v[76:79], v[202:205], v[136:139]
	v_mfma_f32_16x16x32_bf16 v[124:127], v[68:71], v[218:221], v[124:127]
	v_mfma_f32_16x16x32_bf16 v[120:123], v[76:79], v[218:221], v[120:123]
	v_mfma_f32_16x16x32_bf16 v[108:111], v[68:71], v[226:229], v[108:111]
	v_mfma_f32_16x16x32_bf16 v[104:107], v[76:79], v[226:229], v[104:107]
	s_setprio 0
	s_setprio 1
	v_mfma_f32_16x16x32_bf16 v[148:151], v[88:91], v[160:163], v[148:151]
	v_mfma_f32_16x16x32_bf16 v[144:147], v[96:99], v[160:163], v[144:147]
	v_mfma_f32_16x16x32_bf16 v[132:135], v[88:91], v[198:201], v[132:135]
	v_mfma_f32_16x16x32_bf16 v[128:131], v[96:99], v[198:201], v[128:131]
	v_mfma_f32_16x16x32_bf16 v[116:119], v[88:91], v[206:209], v[116:119]
	v_mfma_f32_16x16x32_bf16 v[112:115], v[96:99], v[206:209], v[112:115]
	v_mfma_f32_16x16x32_bf16 v[84:87], v[88:91], v[222:225], v[84:87]
	v_mfma_f32_16x16x32_bf16 v[80:83], v[96:99], v[222:225], v[80:83]
	v_mfma_f32_16x16x32_bf16 v[148:151], v[92:95], v[164:167], v[148:151]
	v_mfma_f32_16x16x32_bf16 v[144:147], v[100:103], v[164:167], v[144:147]
	v_mfma_f32_16x16x32_bf16 v[132:135], v[92:95], v[202:205], v[132:135]
	v_mfma_f32_16x16x32_bf16 v[128:131], v[100:103], v[202:205], v[128:131]
	v_mfma_f32_16x16x32_bf16 v[116:119], v[92:95], v[218:221], v[116:119]
	v_mfma_f32_16x16x32_bf16 v[112:115], v[100:103], v[218:221], v[112:115]
	v_mfma_f32_16x16x32_bf16 v[84:87], v[92:95], v[226:229], v[84:87]
	v_mfma_f32_16x16x32_bf16 v[80:83], v[100:103], v[226:229], v[80:83]
	s_setprio 0
	s_barrier
	s_add_i32 s52, s69, s41
	v_lshl_add_u64 v[230:231], v[230:231], 0, s[34:35]
	s_mov_b32 m0, s52
	ds_read_b128 v[160:163], v214 offset:49152
	ds_read_b128 v[164:167], v214 offset:50176
	ds_read_b128 v[198:201], v214 offset:51200
	ds_read_b128 v[202:205], v214 offset:52224
	ds_read_b128 v[206:209], v214 offset:53248
	ds_read_b128 v[218:221], v214 offset:54272
	ds_read_b128 v[222:225], v214 offset:55296
	ds_read_b128 v[226:229], v214 offset:56320
	global_load_lds_dwordx4 v[230:231], off
	s_add_i32 m0, s52, 0x2000
	s_add_u32 s2, s2, 0x100080
	v_lshl_add_u64 v[230:231], v[232:233], 0, s[34:35]
	s_addc_u32 s3, s3, 0
	s_add_i32 s52, s70, s41
	global_load_lds_dwordx4 v[230:231], off
	v_lshl_add_u64 v[230:231], s[2:3], 0, v[176:177]
	s_mov_b32 m0, s52
	s_nop 0
	global_load_lds_dwordx4 v[230:231], off
	v_lshl_add_u64 v[230:231], s[2:3], 0, v[172:173]
	s_add_i32 m0, s52, 0x2000
	s_nop 0
	global_load_lds_dwordx4 v[230:231], off
	v_lshl_add_u64 v[230:231], v[234:235], 0, s[34:35]
	s_mov_b32 m0, s59
	s_nop 0
	global_load_lds_dwordx4 v[230:231], off
	v_lshl_add_u64 v[230:231], v[236:237], 0, s[34:35]
	s_mov_b32 m0, s60
	s_nop 0
	global_load_lds_dwordx4 v[230:231], off
	s_waitcnt vmcnt(8)
	s_waitcnt lgkmcnt(0)
	s_barrier
	s_setprio 1
	s_waitcnt lgkmcnt(0)
	v_mfma_f32_16x16x32_bf16 v[60:63], v[64:67], v[160:163], v[60:63]
	v_mfma_f32_16x16x32_bf16 v[56:59], v[72:75], v[160:163], v[56:59]
	v_mfma_f32_16x16x32_bf16 v[44:47], v[64:67], v[198:201], v[44:47]
	v_mfma_f32_16x16x32_bf16 v[40:43], v[72:75], v[198:201], v[40:43]
	v_mfma_f32_16x16x32_bf16 v[28:31], v[64:67], v[206:209], v[28:31]
	v_mfma_f32_16x16x32_bf16 v[24:27], v[72:75], v[206:209], v[24:27]
	v_mfma_f32_16x16x32_bf16 v[12:15], v[64:67], v[222:225], v[12:15]
	v_mfma_f32_16x16x32_bf16 v[8:11], v[72:75], v[222:225], v[8:11]
	v_mfma_f32_16x16x32_bf16 v[60:63], v[68:71], v[164:167], v[60:63]
	v_mfma_f32_16x16x32_bf16 v[56:59], v[76:79], v[164:167], v[56:59]
	v_mfma_f32_16x16x32_bf16 v[44:47], v[68:71], v[202:205], v[44:47]
	v_mfma_f32_16x16x32_bf16 v[40:43], v[76:79], v[202:205], v[40:43]
	v_mfma_f32_16x16x32_bf16 v[28:31], v[68:71], v[218:221], v[28:31]
	v_mfma_f32_16x16x32_bf16 v[24:27], v[76:79], v[218:221], v[24:27]
	v_mfma_f32_16x16x32_bf16 v[12:15], v[68:71], v[226:229], v[12:15]
	v_mfma_f32_16x16x32_bf16 v[8:11], v[76:79], v[226:229], v[8:11]
	s_setprio 0
	s_setprio 1
	v_mfma_f32_16x16x32_bf16 v[52:55], v[88:91], v[160:163], v[52:55]
	v_mfma_f32_16x16x32_bf16 v[48:51], v[96:99], v[160:163], v[48:51]
	v_mfma_f32_16x16x32_bf16 v[36:39], v[88:91], v[198:201], v[36:39]
	v_mfma_f32_16x16x32_bf16 v[32:35], v[96:99], v[198:201], v[32:35]
	v_mfma_f32_16x16x32_bf16 v[20:23], v[88:91], v[206:209], v[20:23]
	v_mfma_f32_16x16x32_bf16 v[16:19], v[96:99], v[206:209], v[16:19]
	v_mfma_f32_16x16x32_bf16 v[4:7], v[88:91], v[222:225], v[4:7]
	v_mfma_f32_16x16x32_bf16 v[0:3], v[96:99], v[222:225], v[0:3]
	v_mfma_f32_16x16x32_bf16 v[52:55], v[92:95], v[164:167], v[52:55]
	v_mfma_f32_16x16x32_bf16 v[48:51], v[100:103], v[164:167], v[48:51]
	v_mfma_f32_16x16x32_bf16 v[36:39], v[92:95], v[202:205], v[36:39]
	v_mfma_f32_16x16x32_bf16 v[32:35], v[100:103], v[202:205], v[32:35]
	v_mfma_f32_16x16x32_bf16 v[20:23], v[92:95], v[218:221], v[20:23]
	v_mfma_f32_16x16x32_bf16 v[16:19], v[100:103], v[218:221], v[16:19]
	v_mfma_f32_16x16x32_bf16 v[4:7], v[92:95], v[226:229], v[4:7]
	v_mfma_f32_16x16x32_bf16 v[0:3], v[100:103], v[226:229], v[0:3]
	s_setprio 0
	s_barrier
	s_add_i32 s68, s68, 2
	s_add_u32 s50, s50, 0x100
	s_addc_u32 s51, s51, 0
	s_add_u32 s66, s66, 0x100
	s_addc_u32 s67, s67, 0
	s_cmp_gt_u32 s68, 61
	s_cbranch_scc0 .LBB0_684
	s_mov_b32 s99, -2
	s_and_b64 vcc, exec, s[36:37]
	s_cbranch_vccz .LBB0_687
	s_barrier

.LBB0_747:
	s_add_u32 s30, s20, 0xa8000
	s_addc_u32 s31, s21, 0
	s_add_u32 s34, s20, 0xb2400
	s_addc_u32 s35, s21, 0
	s_and_b32 s62, s37, 3
	s_lshl_b32 s63, s36, 6
	s_lshl_b32 s1, s36, 13
	s_mov_b64 s[36:37], 0x80
	s_add_i32 m0, s54, 0x18000
	v_lshl_add_u64 v[6:7], v[6:7], 0, s[36:37]
	s_lshl_b32 s40, s62, 12
	s_waitcnt vmcnt(2)
	s_barrier
	global_load_lds_dwordx4 v[6:7], off
	v_lshl_add_u64 v[4:5], v[4:5], 0, s[36:37]
	s_add_i32 m0, s54, 0x1a000
	s_add_i32 s64, s54, 0x8000
	s_add_i32 s65, s54, 0xa000
	global_load_lds_dwordx4 v[4:5], off
	v_lshl_add_u64 v[2:3], v[2:3], 0, s[36:37]
	s_mov_b32 m0, s64
	s_add_u32 s38, s2, 0x40080
	global_load_lds_dwordx4 v[2:3], off
	v_lshl_add_u64 v[0:1], v[0:1], 0, s[36:37]
	s_mov_b32 m0, s65
	s_addc_u32 s39, s3, 0
	global_load_lds_dwordx4 v[0:1], off
	s_add_i32 m0, s54, 0x1c000
	v_lshl_add_u64 v[0:1], s[38:39], 0, v[172:173]
	global_load_lds_dwordx4 v[0:1], off
	v_lshl_add_u64 v[0:1], s[38:39], 0, v[164:165]
	s_add_i32 m0, s54, 0x1e000
	s_sext_i32_i8 s83, s6
	global_load_lds_dwordx4 v[0:1], off
	v_bfe_u32 v1, v11, 4, 2
	s_cmpk_lt_u32 s7, 0x100
	v_readlane_b32 s6, v251, 41
	v_lshlrev_b32_e32 v176, 5, v1
	v_readlane_b32 s7, v251, 42
	v_and_b32_e32 v169, 15, v11
	v_lshlrev_b32_e32 v0, 3, v1
	v_lshl_add_u64 v[178:179], s[6:7], 0, v[176:177]
	v_readlane_b32 s6, v251, 43
	v_readlane_b32 s7, v251, 44
	v_lshlrev_b32_e32 v2, 4, v1
	v_lshlrev_b32_e32 v3, 2, v11
	v_lshl_add_u64 v[180:181], s[6:7], 0, v[176:177]
	v_lshlrev_b32_e32 v176, 17, v1
	v_lshlrev_b32_e32 v1, 14, v13
	v_lshl_or_b32 v2, v169, 6, v2
	v_and_b32_e32 v3, 32, v3
	v_and_b32_e32 v1, 0xffff8000, v1
	v_bitop3_b32 v4, v2, s1, v3 bitop3:0xde
	v_bitop3_b32 v171, v2, s40, v3 bitop3:0xde
	v_lshl_add_u32 v1, v12, 11, v1
	v_and_b32_e32 v2, 1, v13
	v_lshl_or_b32 v1, v2, 6, v1
	v_lshl_add_u32 v184, v14, 1, v1
	v_lshlrev_b32_e32 v1, 14, v8
	v_and_b32_e32 v1, 0xffff8000, v1
	s_waitcnt vmcnt(6)
	s_mov_b32 s99, 0x7fff0000
	v_readlane_b32 s6, v251, 50
	v_lshl_add_u32 v1, v9, 11, v1
	v_and_b32_e32 v2, 1, v8
	s_cselect_b64 s[38:39], -1, 0
	v_readlane_b32 s7, v251, 51
	v_lshl_or_b32 v1, v2, 6, v1
	s_add_i32 s69, 0, 0x10000
	s_add_i32 s70, 0, 0x14000
	s_mov_b32 s66, 0x18000
	s_mov_b32 s67, 0x8000
	s_mov_b32 s68, 0x1c000
	v_lshl_add_u64 v[182:183], s[6:7], 0, v[176:177]
	v_lshl_or_b32 v199, s62, 5, v0
	v_mov_b32_e32 v185, v177
	v_lshl_add_u32 v186, v10, 1, v1
	v_mov_b32_e32 v187, v177
	v_mov_b64_e32 v[188:189], 0x480
	v_mov_b64_e32 v[190:191], 0x47f
	v_add_u32_e32 v202, s69, v171
	v_add_u32_e32 v203, s70, v171
	v_add_u32_e32 v204, 0, v4
	s_mov_b32 s71, 0xc000
	s_movk_i32 s72, 0x1ff3
	s_mov_b32 s40, 0x3a800000
	s_mov_b32 s73, 0xf800000
	v_mov_b32_e32 v205, 0x260
	s_mov_b32 s74, 0x80000
	s_mov_b32 s75, 0x84000
	s_mov_b32 s76, 0x88000
	s_mov_b32 s77, 0x8c000
	s_mov_b32 s78, 0x90000
	s_mov_b32 s79, 0x94000
	s_mov_b32 s80, 0x98000
	s_mov_b32 s81, 0x9c000
	v_lshlrev_b32_e32 v192, 1, v0
	s_movk_i32 s82, 0x600
	v_mov_b32_e32 v206, 0x3e38aa3b
	s_barrier
	s_branch .LBB0_750

.LBB0_752:
	s_ashr_i32 s45, s44, 31
	s_lshl_b64 s[46:47], s[44:45], 19
	s_add_u32 s46, s26, s46
	s_addc_u32 s47, s27, s47
	s_and_b64 s[48:49], s[6:7], exec
	s_cselect_b32 s1, s47, s51
	s_cselect_b32 s45, s46, s50
	s_ashr_i32 s43, s42, 31
	s_lshl_b64 s[48:49], s[42:43], 19
	v_readlane_b32 s52, v251, 22
	v_readlane_b32 s53, v251, 23
	s_add_u32 s48, s52, s48
	s_addc_u32 s49, s53, s49
	s_and_b64 s[52:53], s[6:7], exec
	s_cselect_b32 s43, s49, s3
	s_cselect_b32 s84, s48, s2
	s_add_u32 s50, s50, 0x40080
	s_addc_u32 s51, s51, 0
	s_add_u32 s85, s2, 0x100
	v_mov_b32_e32 v0, 0
	s_addc_u32 s86, s3, 0
	s_mov_b32 s87, -2
	v_mov_b32_e32 v1, v0
	v_mov_b32_e32 v2, v0
	v_mov_b32_e32 v3, v0
	v_mov_b32_e32 v4, v0
	v_mov_b32_e32 v5, v0
	v_mov_b32_e32 v6, v0
	v_mov_b32_e32 v7, v0
	v_mov_b32_e32 v16, v0
	v_mov_b32_e32 v17, v0
	v_mov_b32_e32 v18, v0
	v_mov_b32_e32 v19, v0
	v_mov_b32_e32 v20, v0
	v_mov_b32_e32 v21, v0
	v_mov_b32_e32 v22, v0
	v_mov_b32_e32 v23, v0
	v_mov_b32_e32 v32, v0
	v_mov_b32_e32 v33, v0
	v_mov_b32_e32 v34, v0
	v_mov_b32_e32 v35, v0
	v_mov_b32_e32 v36, v0
	v_mov_b32_e32 v37, v0
	v_mov_b32_e32 v38, v0
	v_mov_b32_e32 v39, v0
	v_mov_b32_e32 v48, v0
	v_mov_b32_e32 v49, v0
	v_mov_b32_e32 v50, v0
	v_mov_b32_e32 v51, v0
	v_mov_b32_e32 v52, v0
	v_mov_b32_e32 v53, v0
	v_mov_b32_e32 v54, v0
	v_mov_b32_e32 v55, v0
	v_mov_b32_e32 v8, v0
	v_mov_b32_e32 v9, v0
	v_mov_b32_e32 v10, v0
	v_mov_b32_e32 v11, v0
	v_mov_b32_e32 v12, v0
	v_mov_b32_e32 v13, v0
	v_mov_b32_e32 v14, v0
	v_mov_b32_e32 v15, v0
	v_mov_b32_e32 v24, v0
	v_mov_b32_e32 v25, v0
	v_mov_b32_e32 v26, v0
	v_mov_b32_e32 v27, v0
	v_mov_b32_e32 v28, v0
	v_mov_b32_e32 v29, v0
	v_mov_b32_e32 v30, v0
	v_mov_b32_e32 v31, v0
	v_mov_b32_e32 v40, v0
	v_mov_b32_e32 v41, v0
	v_mov_b32_e32 v42, v0
	v_mov_b32_e32 v43, v0
	v_mov_b32_e32 v44, v0
	v_mov_b32_e32 v45, v0
	v_mov_b32_e32 v46, v0
	v_mov_b32_e32 v47, v0
	v_mov_b32_e32 v56, v0
	v_mov_b32_e32 v57, v0
	v_mov_b32_e32 v58, v0
	v_mov_b32_e32 v59, v0
	v_mov_b32_e32 v60, v0
	v_mov_b32_e32 v61, v0
	v_mov_b32_e32 v62, v0
	v_mov_b32_e32 v63, v0
	v_mov_b32_e32 v64, v0
	v_mov_b32_e32 v65, v0
	v_mov_b32_e32 v66, v0
	v_mov_b32_e32 v67, v0
	v_mov_b32_e32 v68, v0
	v_mov_b32_e32 v69, v0
	v_mov_b32_e32 v70, v0
	v_mov_b32_e32 v71, v0
	v_mov_b32_e32 v80, v0
	v_mov_b32_e32 v81, v0
	v_mov_b32_e32 v82, v0
	v_mov_b32_e32 v83, v0
	v_mov_b32_e32 v84, v0
	v_mov_b32_e32 v85, v0
	v_mov_b32_e32 v86, v0
	v_mov_b32_e32 v87, v0
	v_mov_b32_e32 v128, v0
	v_mov_b32_e32 v129, v0
	v_mov_b32_e32 v130, v0
	v_mov_b32_e32 v131, v0
	v_mov_b32_e32 v132, v0
	v_mov_b32_e32 v133, v0
	v_mov_b32_e32 v134, v0
	v_mov_b32_e32 v135, v0
	v_mov_b32_e32 v144, v0
	v_mov_b32_e32 v145, v0
	v_mov_b32_e32 v146, v0
	v_mov_b32_e32 v147, v0
	v_mov_b32_e32 v148, v0
	v_mov_b32_e32 v149, v0
	v_mov_b32_e32 v150, v0
	v_mov_b32_e32 v151, v0
	v_mov_b32_e32 v72, v0
	v_mov_b32_e32 v73, v0
	v_mov_b32_e32 v74, v0
	v_mov_b32_e32 v75, v0
	v_mov_b32_e32 v76, v0
	v_mov_b32_e32 v77, v0
	v_mov_b32_e32 v78, v0
	v_mov_b32_e32 v79, v0
	v_mov_b32_e32 v88, v0
	v_mov_b32_e32 v89, v0
	v_mov_b32_e32 v90, v0
	v_mov_b32_e32 v91, v0
	v_mov_b32_e32 v92, v0
	v_mov_b32_e32 v93, v0
	v_mov_b32_e32 v94, v0
	v_mov_b32_e32 v95, v0
	v_mov_b32_e32 v136, v0
	v_mov_b32_e32 v137, v0
	v_mov_b32_e32 v138, v0
	v_mov_b32_e32 v139, v0
	v_mov_b32_e32 v140, v0
	v_mov_b32_e32 v141, v0
	v_mov_b32_e32 v142, v0
	v_mov_b32_e32 v143, v0
	v_mov_b32_e32 v152, v0
	v_mov_b32_e32 v153, v0
	v_mov_b32_e32 v154, v0
	v_mov_b32_e32 v155, v0
	v_mov_b32_e32 v156, v0
	v_mov_b32_e32 v157, v0
	v_mov_b32_e32 v158, v0
	v_mov_b32_e32 v159, v0
.LBB0_753:
	ds_read_b128 v[96:99], v202
	ds_read_b128 v[100:103], v202 offset:1024
	ds_read_b128 v[104:107], v202 offset:2048
	ds_read_b128 v[108:111], v202 offset:3072
	ds_read_b128 v[112:115], v203
	ds_read_b128 v[116:119], v203 offset:1024
	ds_read_b128 v[120:123], v203 offset:2048
	ds_read_b128 v[124:127], v203 offset:3072
	s_add_u32 s2, s50, 0xfffc0080
	s_addc_u32 s3, s51, -1
	s_cmp_eq_u32 s87, 12
	s_cselect_b32 s53, s1, s3
	s_cselect_b32 s52, s45, s2
	s_cselect_b32 s3, s43, s86
	s_cselect_b32 s2, s84, s85
	v_lshl_add_u64 v[200:201], s[50:51], 0, v[184:185]
	s_add_i32 m0, s54, 0xc000
	ds_read_b128 v[160:163], v204
	ds_read_b128 v[194:197], v204 offset:1024
	ds_read_b128 v[208:211], v204 offset:2048
	ds_read_b128 v[216:219], v204 offset:3072
	ds_read_b128 v[220:223], v204 offset:4096
	ds_read_b128 v[224:227], v204 offset:5120
	ds_read_b128 v[228:231], v204 offset:6144
	ds_read_b128 v[232:235], v204 offset:7168
	global_load_lds_dwordx4 v[200:201], off
	v_lshl_add_u64 v[200:201], s[50:51], 0, v[186:187]
	s_add_i32 m0, s54, 0xe000
	s_nop 0
	global_load_lds_dwordx4 v[200:201], off
	s_cmp_eq_u32 s87, s99
	s_cbranch_scc1 .Ls1a_P9_0
	s_waitcnt vmcnt(8)
	s_branch .Ls1b_P9_0

.Ls1b_P9_0:
	s_waitcnt lgkmcnt(0)
	s_barrier
	s_setprio 1
	s_waitcnt lgkmcnt(0)
	v_mfma_f32_16x16x32_bf16 v[156:159], v[96:99], v[160:163], v[156:159]
	v_mfma_f32_16x16x32_bf16 v[152:155], v[104:107], v[160:163], v[152:155]
	v_mfma_f32_16x16x32_bf16 v[140:143], v[96:99], v[208:211], v[140:143]
	v_mfma_f32_16x16x32_bf16 v[136:139], v[104:107], v[208:211], v[136:139]
	v_mfma_f32_16x16x32_bf16 v[92:95], v[96:99], v[220:223], v[92:95]
	v_mfma_f32_16x16x32_bf16 v[88:91], v[104:107], v[220:223], v[88:91]
	v_mfma_f32_16x16x32_bf16 v[76:79], v[96:99], v[228:231], v[76:79]
	v_mfma_f32_16x16x32_bf16 v[72:75], v[104:107], v[228:231], v[72:75]
	v_mfma_f32_16x16x32_bf16 v[156:159], v[100:103], v[194:197], v[156:159]
	v_mfma_f32_16x16x32_bf16 v[152:155], v[108:111], v[194:197], v[152:155]
	v_mfma_f32_16x16x32_bf16 v[140:143], v[100:103], v[216:219], v[140:143]
	v_mfma_f32_16x16x32_bf16 v[136:139], v[108:111], v[216:219], v[136:139]
	v_mfma_f32_16x16x32_bf16 v[92:95], v[100:103], v[224:227], v[92:95]
	v_mfma_f32_16x16x32_bf16 v[88:91], v[108:111], v[224:227], v[88:91]
	v_mfma_f32_16x16x32_bf16 v[76:79], v[100:103], v[232:235], v[76:79]
	v_mfma_f32_16x16x32_bf16 v[72:75], v[108:111], v[232:235], v[72:75]
	s_setprio 0
	s_setprio 1
	v_mfma_f32_16x16x32_bf16 v[148:151], v[112:115], v[160:163], v[148:151]
	v_mfma_f32_16x16x32_bf16 v[144:147], v[120:123], v[160:163], v[144:147]
	v_mfma_f32_16x16x32_bf16 v[132:135], v[112:115], v[208:211], v[132:135]
	v_mfma_f32_16x16x32_bf16 v[128:131], v[120:123], v[208:211], v[128:131]
	v_mfma_f32_16x16x32_bf16 v[84:87], v[112:115], v[220:223], v[84:87]
	v_mfma_f32_16x16x32_bf16 v[80:83], v[120:123], v[220:223], v[80:83]
	v_mfma_f32_16x16x32_bf16 v[68:71], v[112:115], v[228:231], v[68:71]
	v_mfma_f32_16x16x32_bf16 v[64:67], v[120:123], v[228:231], v[64:67]
	v_mfma_f32_16x16x32_bf16 v[148:151], v[116:119], v[194:197], v[148:151]
	v_mfma_f32_16x16x32_bf16 v[144:147], v[124:127], v[194:197], v[144:147]
	v_mfma_f32_16x16x32_bf16 v[132:135], v[116:119], v[216:219], v[132:135]
	v_mfma_f32_16x16x32_bf16 v[128:131], v[124:127], v[216:219], v[128:131]
	v_mfma_f32_16x16x32_bf16 v[84:87], v[116:119], v[224:227], v[84:87]
	v_mfma_f32_16x16x32_bf16 v[80:83], v[124:127], v[224:227], v[80:83]
	v_mfma_f32_16x16x32_bf16 v[68:71], v[116:119], v[232:235], v[68:71]
	v_mfma_f32_16x16x32_bf16 v[64:67], v[124:127], v[232:235], v[64:67]
	s_setprio 0
	s_barrier
	s_add_i32 s89, s69, s33
	v_lshl_add_u64 v[200:201], s[2:3], 0, v[172:173]
	s_mov_b32 m0, s89
	ds_read_b128 v[160:163], v204 offset:16384
	ds_read_b128 v[194:197], v204 offset:17408
	ds_read_b128 v[208:211], v204 offset:18432
	ds_read_b128 v[216:219], v204 offset:19456
	ds_read_b128 v[220:223], v204 offset:20480
	ds_read_b128 v[224:227], v204 offset:21504
	ds_read_b128 v[228:231], v204 offset:22528
	ds_read_b128 v[232:235], v204 offset:23552
	global_load_lds_dwordx4 v[200:201], off
	s_add_i32 m0, s89, 0x2000
	s_add_u32 s90, s2, 0x40000
	v_lshl_add_u64 v[212:213], s[2:3], 0, v[164:165]
	s_addc_u32 s91, s3, 0
	s_add_i32 s89, s70, s33
	global_load_lds_dwordx4 v[212:213], off
	v_lshl_add_u64 v[236:237], s[90:91], 0, v[172:173]
	s_mov_b32 m0, s89
	v_lshl_add_u64 v[238:239], s[52:53], 0, v[166:167]
	global_load_lds_dwordx4 v[236:237], off
	v_lshl_add_u64 v[236:237], s[90:91], 0, v[164:165]
	s_add_i32 m0, s89, 0x2000
	s_nop 0
	global_load_lds_dwordx4 v[236:237], off
	v_lshl_add_u64 v[236:237], s[52:53], 0, v[174:175]
	s_mov_b32 m0, s54
	s_nop 0
	global_load_lds_dwordx4 v[236:237], off
	s_mov_b32 m0, s55
	s_nop 0
	global_load_lds_dwordx4 v[238:239], off
	s_cmp_eq_u32 s87, s99
	s_cbranch_scc1 .Ls1a_P9_1
	s_waitcnt vmcnt(8)
	s_branch .Ls1b_P9_1

.Ls1b_P9_1:
	s_waitcnt lgkmcnt(0)
	s_barrier
	s_setprio 1
	s_waitcnt lgkmcnt(0)
	v_mfma_f32_16x16x32_bf16 v[60:63], v[96:99], v[160:163], v[60:63]
	v_mfma_f32_16x16x32_bf16 v[56:59], v[104:107], v[160:163], v[56:59]
	v_mfma_f32_16x16x32_bf16 v[44:47], v[96:99], v[208:211], v[44:47]
	v_mfma_f32_16x16x32_bf16 v[40:43], v[104:107], v[208:211], v[40:43]
	v_mfma_f32_16x16x32_bf16 v[28:31], v[96:99], v[220:223], v[28:31]
	v_mfma_f32_16x16x32_bf16 v[24:27], v[104:107], v[220:223], v[24:27]
	v_mfma_f32_16x16x32_bf16 v[12:15], v[96:99], v[228:231], v[12:15]
	v_mfma_f32_16x16x32_bf16 v[8:11], v[104:107], v[228:231], v[8:11]
	v_mfma_f32_16x16x32_bf16 v[60:63], v[100:103], v[194:197], v[60:63]
	v_mfma_f32_16x16x32_bf16 v[56:59], v[108:111], v[194:197], v[56:59]
	v_mfma_f32_16x16x32_bf16 v[44:47], v[100:103], v[216:219], v[44:47]
	v_mfma_f32_16x16x32_bf16 v[40:43], v[108:111], v[216:219], v[40:43]
	v_mfma_f32_16x16x32_bf16 v[28:31], v[100:103], v[224:227], v[28:31]
	v_mfma_f32_16x16x32_bf16 v[24:27], v[108:111], v[224:227], v[24:27]
	v_mfma_f32_16x16x32_bf16 v[12:15], v[100:103], v[232:235], v[12:15]
	v_mfma_f32_16x16x32_bf16 v[8:11], v[108:111], v[232:235], v[8:11]
	s_setprio 0
	s_setprio 1
	v_mfma_f32_16x16x32_bf16 v[52:55], v[112:115], v[160:163], v[52:55]
	v_mfma_f32_16x16x32_bf16 v[48:51], v[120:123], v[160:163], v[48:51]
	v_mfma_f32_16x16x32_bf16 v[36:39], v[112:115], v[208:211], v[36:39]
	v_mfma_f32_16x16x32_bf16 v[32:35], v[120:123], v[208:211], v[32:35]
	v_mfma_f32_16x16x32_bf16 v[20:23], v[112:115], v[220:223], v[20:23]
	v_mfma_f32_16x16x32_bf16 v[16:19], v[120:123], v[220:223], v[16:19]
	v_mfma_f32_16x16x32_bf16 v[4:7], v[112:115], v[228:231], v[4:7]
	v_mfma_f32_16x16x32_bf16 v[0:3], v[120:123], v[228:231], v[0:3]
	v_mfma_f32_16x16x32_bf16 v[52:55], v[116:119], v[194:197], v[52:55]
	v_mfma_f32_16x16x32_bf16 v[48:51], v[124:127], v[194:197], v[48:51]
	v_mfma_f32_16x16x32_bf16 v[36:39], v[116:119], v[216:219], v[36:39]
	v_mfma_f32_16x16x32_bf16 v[32:35], v[124:127], v[216:219], v[32:35]
	v_mfma_f32_16x16x32_bf16 v[20:23], v[116:119], v[224:227], v[20:23]
	v_mfma_f32_16x16x32_bf16 v[16:19], v[124:127], v[224:227], v[16:19]
	v_mfma_f32_16x16x32_bf16 v[4:7], v[116:119], v[232:235], v[4:7]
	v_mfma_f32_16x16x32_bf16 v[0:3], v[124:127], v[232:235], v[0:3]
	s_setprio 0
	s_barrier
	s_add_i32 s89, 0, 0x18000
	s_add_i32 s90, 0, 0x1c000
	v_add_u32_e32 v108, s89, v171
	v_add_u32_e32 v124, s90, v171
	ds_read_b128 v[96:99], v108
	ds_read_b128 v[100:103], v108 offset:1024
	ds_read_b128 v[104:107], v108 offset:2048
	ds_read_b128 v[108:111], v108 offset:3072
	ds_read_b128 v[112:115], v124
	ds_read_b128 v[116:119], v124 offset:1024
	ds_read_b128 v[120:123], v124 offset:2048
	ds_read_b128 v[124:127], v124 offset:3072
	s_add_u32 s52, s52, 0x40000
	s_addc_u32 s53, s53, 0
	s_mov_b32 m0, s56
	v_lshl_add_u64 v[240:241], s[52:53], 0, v[174:175]
	ds_read_b128 v[160:163], v204 offset:32768
	ds_read_b128 v[194:197], v204 offset:33792
	ds_read_b128 v[208:211], v204 offset:34816
	ds_read_b128 v[216:219], v204 offset:35840
	ds_read_b128 v[220:223], v204 offset:36864
	ds_read_b128 v[224:227], v204 offset:37888
	ds_read_b128 v[228:231], v204 offset:38912
	ds_read_b128 v[232:235], v204 offset:39936
	global_load_lds_dwordx4 v[240:241], off
	v_lshl_add_u64 v[240:241], s[52:53], 0, v[166:167]
	s_mov_b32 m0, s57
	s_nop 0
	global_load_lds_dwordx4 v[240:241], off
	s_waitcnt vmcnt(8)
	s_waitcnt lgkmcnt(0)
	s_barrier
	s_setprio 1
	s_waitcnt lgkmcnt(0)
	v_mfma_f32_16x16x32_bf16 v[156:159], v[96:99], v[160:163], v[156:159]
	v_mfma_f32_16x16x32_bf16 v[152:155], v[104:107], v[160:163], v[152:155]
	v_mfma_f32_16x16x32_bf16 v[140:143], v[96:99], v[208:211], v[140:143]
	v_mfma_f32_16x16x32_bf16 v[136:139], v[104:107], v[208:211], v[136:139]
	v_mfma_f32_16x16x32_bf16 v[92:95], v[96:99], v[220:223], v[92:95]
	v_mfma_f32_16x16x32_bf16 v[88:91], v[104:107], v[220:223], v[88:91]
	v_mfma_f32_16x16x32_bf16 v[76:79], v[96:99], v[228:231], v[76:79]
	v_mfma_f32_16x16x32_bf16 v[72:75], v[104:107], v[228:231], v[72:75]
	v_mfma_f32_16x16x32_bf16 v[156:159], v[100:103], v[194:197], v[156:159]
	v_mfma_f32_16x16x32_bf16 v[152:155], v[108:111], v[194:197], v[152:155]
	v_mfma_f32_16x16x32_bf16 v[140:143], v[100:103], v[216:219], v[140:143]
	v_mfma_f32_16x16x32_bf16 v[136:139], v[108:111], v[216:219], v[136:139]
	v_mfma_f32_16x16x32_bf16 v[92:95], v[100:103], v[224:227], v[92:95]
	v_mfma_f32_16x16x32_bf16 v[88:91], v[108:111], v[224:227], v[88:91]
	v_mfma_f32_16x16x32_bf16 v[76:79], v[100:103], v[232:235], v[76:79]
	v_mfma_f32_16x16x32_bf16 v[72:75], v[108:111], v[232:235], v[72:75]
	s_setprio 0
	s_setprio 1
	v_mfma_f32_16x16x32_bf16 v[148:151], v[112:115], v[160:163], v[148:151]
	v_mfma_f32_16x16x32_bf16 v[144:147], v[120:123], v[160:163], v[144:147]
	v_mfma_f32_16x16x32_bf16 v[132:135], v[112:115], v[208:211], v[132:135]
	v_mfma_f32_16x16x32_bf16 v[128:131], v[120:123], v[208:211], v[128:131]
	v_mfma_f32_16x16x32_bf16 v[84:87], v[112:115], v[220:223], v[84:87]
	v_mfma_f32_16x16x32_bf16 v[80:83], v[120:123], v[220:223], v[80:83]
	v_mfma_f32_16x16x32_bf16 v[68:71], v[112:115], v[228:231], v[68:71]
	v_mfma_f32_16x16x32_bf16 v[64:67], v[120:123], v[228:231], v[64:67]
	v_mfma_f32_16x16x32_bf16 v[148:151], v[116:119], v[194:197], v[148:151]
	v_mfma_f32_16x16x32_bf16 v[144:147], v[124:127], v[194:197], v[144:147]
	v_mfma_f32_16x16x32_bf16 v[132:135], v[116:119], v[216:219], v[132:135]
	v_mfma_f32_16x16x32_bf16 v[128:131], v[124:127], v[216:219], v[128:131]
	v_mfma_f32_16x16x32_bf16 v[84:87], v[116:119], v[224:227], v[84:87]
	v_mfma_f32_16x16x32_bf16 v[80:83], v[124:127], v[224:227], v[80:83]
	v_mfma_f32_16x16x32_bf16 v[68:71], v[116:119], v[232:235], v[68:71]
	v_mfma_f32_16x16x32_bf16 v[64:67], v[124:127], v[232:235], v[64:67]
	s_setprio 0
	s_barrier
	s_add_i32 s52, s89, s33
	v_lshl_add_u64 v[200:201], v[200:201], 0, s[36:37]
	s_mov_b32 m0, s52
	ds_read_b128 v[160:163], v204 offset:49152
	ds_read_b128 v[194:197], v204 offset:50176
	ds_read_b128 v[208:211], v204 offset:51200
	ds_read_b128 v[216:219], v204 offset:52224
	ds_read_b128 v[220:223], v204 offset:53248
	ds_read_b128 v[224:227], v204 offset:54272
	ds_read_b128 v[228:231], v204 offset:55296
	ds_read_b128 v[232:235], v204 offset:56320
	global_load_lds_dwordx4 v[200:201], off
	s_add_i32 m0, s52, 0x2000
	s_add_u32 s2, s2, 0x40080
	v_lshl_add_u64 v[200:201], v[212:213], 0, s[36:37]
	s_addc_u32 s3, s3, 0
	s_add_i32 s52, s90, s33
	global_load_lds_dwordx4 v[200:201], off
	v_lshl_add_u64 v[200:201], s[2:3], 0, v[172:173]
	s_mov_b32 m0, s52
	s_nop 0
	global_load_lds_dwordx4 v[200:201], off
	v_lshl_add_u64 v[200:201], s[2:3], 0, v[164:165]
	s_add_i32 m0, s52, 0x2000
	s_nop 0
	global_load_lds_dwordx4 v[200:201], off
	v_lshl_add_u64 v[200:201], v[236:237], 0, s[36:37]
	s_mov_b32 m0, s64
	s_nop 0
	global_load_lds_dwordx4 v[200:201], off
	v_lshl_add_u64 v[200:201], v[238:239], 0, s[36:37]
	s_mov_b32 m0, s65
	s_nop 0
	global_load_lds_dwordx4 v[200:201], off
	s_waitcnt vmcnt(8)
	s_waitcnt lgkmcnt(0)
	s_barrier
	s_setprio 1
	s_waitcnt lgkmcnt(0)
	v_mfma_f32_16x16x32_bf16 v[60:63], v[96:99], v[160:163], v[60:63]
	v_mfma_f32_16x16x32_bf16 v[56:59], v[104:107], v[160:163], v[56:59]
	v_mfma_f32_16x16x32_bf16 v[44:47], v[96:99], v[208:211], v[44:47]
	v_mfma_f32_16x16x32_bf16 v[40:43], v[104:107], v[208:211], v[40:43]
	v_mfma_f32_16x16x32_bf16 v[28:31], v[96:99], v[220:223], v[28:31]
	v_mfma_f32_16x16x32_bf16 v[24:27], v[104:107], v[220:223], v[24:27]
	v_mfma_f32_16x16x32_bf16 v[12:15], v[96:99], v[228:231], v[12:15]
	v_mfma_f32_16x16x32_bf16 v[8:11], v[104:107], v[228:231], v[8:11]
	v_mfma_f32_16x16x32_bf16 v[60:63], v[100:103], v[194:197], v[60:63]
	v_mfma_f32_16x16x32_bf16 v[56:59], v[108:111], v[194:197], v[56:59]
	v_mfma_f32_16x16x32_bf16 v[44:47], v[100:103], v[216:219], v[44:47]
	v_mfma_f32_16x16x32_bf16 v[40:43], v[108:111], v[216:219], v[40:43]
	v_mfma_f32_16x16x32_bf16 v[28:31], v[100:103], v[224:227], v[28:31]
	v_mfma_f32_16x16x32_bf16 v[24:27], v[108:111], v[224:227], v[24:27]
	v_mfma_f32_16x16x32_bf16 v[12:15], v[100:103], v[232:235], v[12:15]
	v_mfma_f32_16x16x32_bf16 v[8:11], v[108:111], v[232:235], v[8:11]
	s_setprio 0
	s_setprio 1
	v_mfma_f32_16x16x32_bf16 v[52:55], v[112:115], v[160:163], v[52:55]
	v_mfma_f32_16x16x32_bf16 v[48:51], v[120:123], v[160:163], v[48:51]
	v_mfma_f32_16x16x32_bf16 v[36:39], v[112:115], v[208:211], v[36:39]
	v_mfma_f32_16x16x32_bf16 v[32:35], v[120:123], v[208:211], v[32:35]
	v_mfma_f32_16x16x32_bf16 v[20:23], v[112:115], v[220:223], v[20:23]
	v_mfma_f32_16x16x32_bf16 v[16:19], v[120:123], v[220:223], v[16:19]
	v_mfma_f32_16x16x32_bf16 v[4:7], v[112:115], v[228:231], v[4:7]
	v_mfma_f32_16x16x32_bf16 v[0:3], v[120:123], v[228:231], v[0:3]
	v_mfma_f32_16x16x32_bf16 v[52:55], v[116:119], v[194:197], v[52:55]
	v_mfma_f32_16x16x32_bf16 v[48:51], v[124:127], v[194:197], v[48:51]
	v_mfma_f32_16x16x32_bf16 v[36:39], v[116:119], v[216:219], v[36:39]
	v_mfma_f32_16x16x32_bf16 v[32:35], v[124:127], v[216:219], v[32:35]
	v_mfma_f32_16x16x32_bf16 v[20:23], v[116:119], v[224:227], v[20:23]
	v_mfma_f32_16x16x32_bf16 v[16:19], v[124:127], v[224:227], v[16:19]
	v_mfma_f32_16x16x32_bf16 v[4:7], v[116:119], v[232:235], v[4:7]
	v_mfma_f32_16x16x32_bf16 v[0:3], v[124:127], v[232:235], v[0:3]
	s_setprio 0
	s_barrier
	s_add_i32 s87, s87, 2
	s_add_u32 s50, s50, 0x100
	s_addc_u32 s51, s51, 0
	s_add_u32 s85, s85, 0x100
	s_addc_u32 s86, s86, 0
	s_cmp_gt_u32 s87, 13
	s_cbranch_scc0 .LBB0_753
	s_mov_b32 s99, -2
	s_and_b64 vcc, exec, s[38:39]
	s_cbranch_vccz .LBB0_756
	s_barrier

.LBB0_996:
	s_lshl_b32 s5, s5, 5
	s_mov_b64 s[30:31], 0x80
	s_and_b32 s36, s5, 0x60
	s_add_i32 m0, s37, 0x18000
	v_lshl_add_u64 v[6:7], v[6:7], 0, s[30:31]
	s_lshl_b32 s7, s4, 13
	s_lshl_b32 s5, s36, 7
	s_waitcnt vmcnt(2)
	s_barrier
	global_load_lds_dwordx4 v[6:7], off
	v_lshl_add_u64 v[4:5], v[4:5], 0, s[30:31]
	s_add_i32 m0, s37, 0x1a000
	s_add_i32 s51, s37, 0x8000
	s_add_i32 s52, s37, 0xa000
	global_load_lds_dwordx4 v[4:5], off
	v_lshl_add_u64 v[0:1], v[0:1], 0, s[30:31]
	s_mov_b32 m0, s51
	s_add_u32 s34, s2, 0x30080
	global_load_lds_dwordx4 v[0:1], off
	v_lshl_add_u64 v[0:1], v[2:3], 0, s[30:31]
	s_mov_b32 m0, s52
	s_addc_u32 s35, s3, 0
	global_load_lds_dwordx4 v[0:1], off
	s_add_i32 m0, s37, 0x1c000
	v_lshl_add_u64 v[0:1], s[34:35], 0, v[176:177]
	global_load_lds_dwordx4 v[0:1], off
	v_lshl_add_u64 v[0:1], s[34:35], 0, v[172:173]
	s_add_i32 m0, s37, 0x1e000
	v_bfe_u32 v2, v10, 4, 2
	global_load_lds_dwordx4 v[0:1], off
	v_and_b32_e32 v0, 15, v10
	v_lshlrev_b32_e32 v1, 4, v2
	v_lshl_or_b32 v169, s4, 6, v0
	v_lshl_or_b32 v0, v0, 6, v1
	v_lshlrev_b32_e32 v1, 2, v10
	v_and_b32_e32 v1, 32, v1
	v_bitop3_b32 v3, v0, s7, v1 bitop3:0xde
	v_bitop3_b32 v171, v0, s5, v1 bitop3:0xde
	v_cmp_lt_u32_e32 vcc, 1, v2
	v_mov_b32_e32 v1, 0x80
	v_mov_b32_e32 v4, 0x90
	v_bfe_u32 v0, v10, 4, 1
	v_cndmask_b32_e32 v187, v1, v4, vcc
	v_mov_b32_e32 v1, 0xa0
	v_mov_b32_e32 v4, 0xb0
	v_cmp_eq_u32_e64 s[4:5], 0, v0
	v_cndmask_b32_e32 v208, v1, v4, vcc
	v_lshlrev_b32_e32 v0, 2, v0
	v_mov_b32_e32 v1, v177
	s_cmpk_lt_u32 s1, 0x100
	v_lshl_add_u64 v[188:189], s[28:29], 0, v[0:1]
	v_lshrrev_b32_e32 v1, 1, v14
	v_mul_lo_u32 v0, v13, s0
	s_movk_i32 s1, 0x3000
	v_mad_u64_u32 v[0:1], s[40:41], v1, s1, v[0:1]
	v_or_b32_e32 v0, v0, v15
	s_sext_i32_i8 s59, s6
	s_mov_b64 s[6:7], 0x30080
	v_add_lshl_u32 v0, v0, v16, 1
	v_mov_b32_e32 v1, v177
	v_lshl_add_u64 v[190:191], v[0:1], 0, s[6:7]
	v_lshrrev_b32_e32 v1, 1, v8
	v_mul_lo_u32 v0, v9, s0
	v_mad_u64_u32 v[0:1], s[0:1], v1, s1, v[0:1]
	v_or_b32_e32 v0, v0, v11
	s_waitcnt vmcnt(6)
	s_mov_b32 s99, 0x7fff0000
	v_add_lshl_u32 v0, v0, v12, 1
	v_mov_b32_e32 v1, v177
	s_cselect_b64 s[34:35], -1, 0
	v_lshl_add_u64 v[192:193], v[0:1], 0, s[6:7]
	s_add_i32 s53, 0, 0x10000
	s_add_i32 s54, 0, 0x14000
	v_mbcnt_lo_u32_b32 v0, -1, 0
	v_cndmask_b32_e64 v180, 0, 1, vcc
	v_mov_b32_e32 v181, s50
	v_cndmask_b32_e64 v182, 2, 3, vcc
	v_cndmask_b32_e64 v183, 0, 16, vcc
	v_cndmask_b32_e64 v184, 4, 5, vcc
	v_cndmask_b32_e64 v185, 32, 48, vcc
	v_cndmask_b32_e64 v186, 6, 7, vcc
	v_lshl_or_b32 v209, v2, 3, s36
	v_mov_b64_e32 v[194:195], 0x200
	v_mov_b64_e32 v[196:197], 0x1ff
	v_add_u32_e32 v210, s53, v171
	v_add_u32_e32 v211, s54, v171
	v_add_u32_e32 v212, 0, v3
	v_mbcnt_hi_u32_b32 v213, -1, v0
	s_mov_b32 s36, 0x3a800000
	s_mov_b32 s55, 0xf800000
	v_mov_b32_e32 v214, 0x260
	s_mov_b32 s38, 0x3fb504f3
	s_barrier
	s_branch .LBB0_999

.LBB0_1009:
	s_add_u32 s60, s2, 0x100
	v_mov_b32_e32 v0, 0
	s_addc_u32 s61, s3, 0
	s_mov_b32 s62, -2
	v_mov_b32_e32 v1, v0
	v_mov_b32_e32 v2, v0
	v_mov_b32_e32 v3, v0
	v_mov_b32_e32 v4, v0
	v_mov_b32_e32 v5, v0
	v_mov_b32_e32 v6, v0
	v_mov_b32_e32 v7, v0
	v_mov_b32_e32 v16, v0
	v_mov_b32_e32 v17, v0
	v_mov_b32_e32 v18, v0
	v_mov_b32_e32 v19, v0
	v_mov_b32_e32 v20, v0
	v_mov_b32_e32 v21, v0
	v_mov_b32_e32 v22, v0
	v_mov_b32_e32 v23, v0
	v_mov_b32_e32 v32, v0
	v_mov_b32_e32 v33, v0
	v_mov_b32_e32 v34, v0
	v_mov_b32_e32 v35, v0
	v_mov_b32_e32 v36, v0
	v_mov_b32_e32 v37, v0
	v_mov_b32_e32 v38, v0
	v_mov_b32_e32 v39, v0
	v_mov_b32_e32 v48, v0
	v_mov_b32_e32 v49, v0
	v_mov_b32_e32 v50, v0
	v_mov_b32_e32 v51, v0
	v_mov_b32_e32 v52, v0
	v_mov_b32_e32 v53, v0
	v_mov_b32_e32 v54, v0
	v_mov_b32_e32 v55, v0
	v_mov_b32_e32 v8, v0
	v_mov_b32_e32 v9, v0
	v_mov_b32_e32 v10, v0
	v_mov_b32_e32 v11, v0
	v_mov_b32_e32 v12, v0
	v_mov_b32_e32 v13, v0
	v_mov_b32_e32 v14, v0
	v_mov_b32_e32 v15, v0
	v_mov_b32_e32 v24, v0
	v_mov_b32_e32 v25, v0
	v_mov_b32_e32 v26, v0
	v_mov_b32_e32 v27, v0
	v_mov_b32_e32 v28, v0
	v_mov_b32_e32 v29, v0
	v_mov_b32_e32 v30, v0
	v_mov_b32_e32 v31, v0
	v_mov_b32_e32 v40, v0
	v_mov_b32_e32 v41, v0
	v_mov_b32_e32 v42, v0
	v_mov_b32_e32 v43, v0
	v_mov_b32_e32 v44, v0
	v_mov_b32_e32 v45, v0
	v_mov_b32_e32 v46, v0
	v_mov_b32_e32 v47, v0
	v_mov_b32_e32 v56, v0
	v_mov_b32_e32 v57, v0
	v_mov_b32_e32 v58, v0
	v_mov_b32_e32 v59, v0
	v_mov_b32_e32 v60, v0
	v_mov_b32_e32 v61, v0
	v_mov_b32_e32 v62, v0
	v_mov_b32_e32 v63, v0
	v_mov_b32_e32 v80, v0
	v_mov_b32_e32 v81, v0
	v_mov_b32_e32 v82, v0
	v_mov_b32_e32 v83, v0
	v_mov_b32_e32 v84, v0
	v_mov_b32_e32 v85, v0
	v_mov_b32_e32 v86, v0
	v_mov_b32_e32 v87, v0
	v_mov_b32_e32 v112, v0
	v_mov_b32_e32 v113, v0
	v_mov_b32_e32 v114, v0
	v_mov_b32_e32 v115, v0
	v_mov_b32_e32 v116, v0
	v_mov_b32_e32 v117, v0
	v_mov_b32_e32 v118, v0
	v_mov_b32_e32 v119, v0
	v_mov_b32_e32 v128, v0
	v_mov_b32_e32 v129, v0
	v_mov_b32_e32 v130, v0
	v_mov_b32_e32 v131, v0
	v_mov_b32_e32 v132, v0
	v_mov_b32_e32 v133, v0
	v_mov_b32_e32 v134, v0
	v_mov_b32_e32 v135, v0
	v_mov_b32_e32 v144, v0
	v_mov_b32_e32 v145, v0
	v_mov_b32_e32 v146, v0
	v_mov_b32_e32 v147, v0
	v_mov_b32_e32 v148, v0
	v_mov_b32_e32 v149, v0
	v_mov_b32_e32 v150, v0
	v_mov_b32_e32 v151, v0
	v_mov_b32_e32 v104, v0
	v_mov_b32_e32 v105, v0
	v_mov_b32_e32 v106, v0
	v_mov_b32_e32 v107, v0
	v_mov_b32_e32 v108, v0
	v_mov_b32_e32 v109, v0
	v_mov_b32_e32 v110, v0
	v_mov_b32_e32 v111, v0
	v_mov_b32_e32 v120, v0
	v_mov_b32_e32 v121, v0
	v_mov_b32_e32 v122, v0
	v_mov_b32_e32 v123, v0
	v_mov_b32_e32 v124, v0
	v_mov_b32_e32 v125, v0
	v_mov_b32_e32 v126, v0
	v_mov_b32_e32 v127, v0
	v_mov_b32_e32 v136, v0
	v_mov_b32_e32 v137, v0
	v_mov_b32_e32 v138, v0
	v_mov_b32_e32 v139, v0
	v_mov_b32_e32 v140, v0
	v_mov_b32_e32 v141, v0
	v_mov_b32_e32 v142, v0
	v_mov_b32_e32 v143, v0
	v_mov_b32_e32 v152, v0
	v_mov_b32_e32 v153, v0
	v_mov_b32_e32 v154, v0
	v_mov_b32_e32 v155, v0
	v_mov_b32_e32 v156, v0
	v_mov_b32_e32 v157, v0
	v_mov_b32_e32 v158, v0
	v_mov_b32_e32 v159, v0
.LBB0_1010:
	ds_read_b128 v[64:67], v210
	ds_read_b128 v[68:71], v210 offset:1024
	ds_read_b128 v[72:75], v210 offset:2048
	ds_read_b128 v[76:79], v210 offset:3072
	ds_read_b128 v[88:91], v211
	ds_read_b128 v[92:95], v211 offset:1024
	ds_read_b128 v[96:99], v211 offset:2048
	ds_read_b128 v[100:103], v211 offset:3072
	s_add_u32 s0, s44, 0x100
	s_addc_u32 s1, s45, 0
	s_cmp_eq_u32 s62, 8
	s_cselect_b32 s47, s41, s1
	s_cselect_b32 s46, s40, s0
	s_cselect_b32 s3, s43, s61
	s_cselect_b32 s2, s42, s60
	v_lshl_add_u64 v[206:207], s[44:45], 0, v[190:191]
	s_add_i32 m0, s37, 0xc000
	ds_read_b128 v[160:163], v212
	ds_read_b128 v[164:167], v212 offset:1024
	ds_read_b128 v[198:201], v212 offset:2048
	ds_read_b128 v[202:205], v212 offset:3072
	ds_read_b128 v[216:219], v212 offset:4096
	ds_read_b128 v[220:223], v212 offset:5120
	ds_read_b128 v[224:227], v212 offset:6144
	ds_read_b128 v[228:231], v212 offset:7168
	global_load_lds_dwordx4 v[206:207], off
	v_lshl_add_u64 v[206:207], s[44:45], 0, v[192:193]
	s_add_i32 m0, s37, 0xe000
	s_nop 0
	global_load_lds_dwordx4 v[206:207], off
	s_cmp_eq_u32 s62, s99
	s_cbranch_scc1 .Ls1a_P11_0
	s_waitcnt vmcnt(8)
	s_branch .Ls1b_P11_0

.Ls1b_P11_0:
	s_waitcnt lgkmcnt(0)
	s_barrier
	s_setprio 1
	s_waitcnt lgkmcnt(0)
	v_mfma_f32_16x16x32_bf16 v[156:159], v[64:67], v[160:163], v[156:159]
	v_mfma_f32_16x16x32_bf16 v[152:155], v[72:75], v[160:163], v[152:155]
	v_mfma_f32_16x16x32_bf16 v[140:143], v[64:67], v[198:201], v[140:143]
	v_mfma_f32_16x16x32_bf16 v[136:139], v[72:75], v[198:201], v[136:139]
	v_mfma_f32_16x16x32_bf16 v[124:127], v[64:67], v[216:219], v[124:127]
	v_mfma_f32_16x16x32_bf16 v[120:123], v[72:75], v[216:219], v[120:123]
	v_mfma_f32_16x16x32_bf16 v[108:111], v[64:67], v[224:227], v[108:111]
	v_mfma_f32_16x16x32_bf16 v[104:107], v[72:75], v[224:227], v[104:107]
	v_mfma_f32_16x16x32_bf16 v[156:159], v[68:71], v[164:167], v[156:159]
	v_mfma_f32_16x16x32_bf16 v[152:155], v[76:79], v[164:167], v[152:155]
	v_mfma_f32_16x16x32_bf16 v[140:143], v[68:71], v[202:205], v[140:143]
	v_mfma_f32_16x16x32_bf16 v[136:139], v[76:79], v[202:205], v[136:139]
	v_mfma_f32_16x16x32_bf16 v[124:127], v[68:71], v[220:223], v[124:127]
	v_mfma_f32_16x16x32_bf16 v[120:123], v[76:79], v[220:223], v[120:123]
	v_mfma_f32_16x16x32_bf16 v[108:111], v[68:71], v[228:231], v[108:111]
	v_mfma_f32_16x16x32_bf16 v[104:107], v[76:79], v[228:231], v[104:107]
	s_setprio 0
	s_setprio 1
	v_mfma_f32_16x16x32_bf16 v[148:151], v[88:91], v[160:163], v[148:151]
	v_mfma_f32_16x16x32_bf16 v[144:147], v[96:99], v[160:163], v[144:147]
	v_mfma_f32_16x16x32_bf16 v[132:135], v[88:91], v[198:201], v[132:135]
	v_mfma_f32_16x16x32_bf16 v[128:131], v[96:99], v[198:201], v[128:131]
	v_mfma_f32_16x16x32_bf16 v[116:119], v[88:91], v[216:219], v[116:119]
	v_mfma_f32_16x16x32_bf16 v[112:115], v[96:99], v[216:219], v[112:115]
	v_mfma_f32_16x16x32_bf16 v[84:87], v[88:91], v[224:227], v[84:87]
	v_mfma_f32_16x16x32_bf16 v[80:83], v[96:99], v[224:227], v[80:83]
	v_mfma_f32_16x16x32_bf16 v[148:151], v[92:95], v[164:167], v[148:151]
	v_mfma_f32_16x16x32_bf16 v[144:147], v[100:103], v[164:167], v[144:147]
	v_mfma_f32_16x16x32_bf16 v[132:135], v[92:95], v[202:205], v[132:135]
	v_mfma_f32_16x16x32_bf16 v[128:131], v[100:103], v[202:205], v[128:131]
	v_mfma_f32_16x16x32_bf16 v[116:119], v[92:95], v[220:223], v[116:119]
	v_mfma_f32_16x16x32_bf16 v[112:115], v[100:103], v[220:223], v[112:115]
	v_mfma_f32_16x16x32_bf16 v[84:87], v[92:95], v[228:231], v[84:87]
	v_mfma_f32_16x16x32_bf16 v[80:83], v[100:103], v[228:231], v[80:83]
	s_setprio 0
	s_barrier
	s_add_i32 s44, s53, s33
	v_lshl_add_u64 v[206:207], s[2:3], 0, v[176:177]
	s_mov_b32 m0, s44
	ds_read_b128 v[160:163], v212 offset:16384
	ds_read_b128 v[164:167], v212 offset:17408
	ds_read_b128 v[198:201], v212 offset:18432
	ds_read_b128 v[202:205], v212 offset:19456
	ds_read_b128 v[216:219], v212 offset:20480
	ds_read_b128 v[220:223], v212 offset:21504
	ds_read_b128 v[224:227], v212 offset:22528
	ds_read_b128 v[228:231], v212 offset:23552
	global_load_lds_dwordx4 v[206:207], off
	s_add_i32 m0, s44, 0x2000
	s_add_u32 s44, s2, 0x30000
	v_lshl_add_u64 v[232:233], s[2:3], 0, v[172:173]
	s_addc_u32 s45, s3, 0
	s_add_i32 s63, s54, s33
	global_load_lds_dwordx4 v[232:233], off
	v_lshl_add_u64 v[234:235], s[44:45], 0, v[176:177]
	s_mov_b32 m0, s63
	v_lshl_add_u64 v[236:237], s[46:47], 0, v[174:175]
	global_load_lds_dwordx4 v[234:235], off
	v_lshl_add_u64 v[234:235], s[44:45], 0, v[172:173]
	s_add_i32 m0, s63, 0x2000
	s_nop 0
	global_load_lds_dwordx4 v[234:235], off
	v_lshl_add_u64 v[234:235], s[46:47], 0, v[178:179]
	s_mov_b32 m0, s37
	s_nop 0
	global_load_lds_dwordx4 v[234:235], off
	s_mov_b32 m0, s39
	s_nop 0
	global_load_lds_dwordx4 v[236:237], off
	s_cmp_eq_u32 s62, s99
	s_cbranch_scc1 .Ls1a_P11_1
	s_waitcnt vmcnt(8)
	s_branch .Ls1b_P11_1

.Ls1b_P11_1:
	s_waitcnt lgkmcnt(0)
	s_barrier
	s_setprio 1
	s_waitcnt lgkmcnt(0)
	v_mfma_f32_16x16x32_bf16 v[60:63], v[64:67], v[160:163], v[60:63]
	v_mfma_f32_16x16x32_bf16 v[56:59], v[72:75], v[160:163], v[56:59]
	v_mfma_f32_16x16x32_bf16 v[44:47], v[64:67], v[198:201], v[44:47]
	v_mfma_f32_16x16x32_bf16 v[40:43], v[72:75], v[198:201], v[40:43]
	v_mfma_f32_16x16x32_bf16 v[28:31], v[64:67], v[216:219], v[28:31]
	v_mfma_f32_16x16x32_bf16 v[24:27], v[72:75], v[216:219], v[24:27]
	v_mfma_f32_16x16x32_bf16 v[12:15], v[64:67], v[224:227], v[12:15]
	v_mfma_f32_16x16x32_bf16 v[8:11], v[72:75], v[224:227], v[8:11]
	v_mfma_f32_16x16x32_bf16 v[60:63], v[68:71], v[164:167], v[60:63]
	v_mfma_f32_16x16x32_bf16 v[56:59], v[76:79], v[164:167], v[56:59]
	v_mfma_f32_16x16x32_bf16 v[44:47], v[68:71], v[202:205], v[44:47]
	v_mfma_f32_16x16x32_bf16 v[40:43], v[76:79], v[202:205], v[40:43]
	v_mfma_f32_16x16x32_bf16 v[28:31], v[68:71], v[220:223], v[28:31]
	v_mfma_f32_16x16x32_bf16 v[24:27], v[76:79], v[220:223], v[24:27]
	v_mfma_f32_16x16x32_bf16 v[12:15], v[68:71], v[228:231], v[12:15]
	v_mfma_f32_16x16x32_bf16 v[8:11], v[76:79], v[228:231], v[8:11]
	s_setprio 0
	s_setprio 1
	v_mfma_f32_16x16x32_bf16 v[52:55], v[88:91], v[160:163], v[52:55]
	v_mfma_f32_16x16x32_bf16 v[48:51], v[96:99], v[160:163], v[48:51]
	v_mfma_f32_16x16x32_bf16 v[36:39], v[88:91], v[198:201], v[36:39]
	v_mfma_f32_16x16x32_bf16 v[32:35], v[96:99], v[198:201], v[32:35]
	v_mfma_f32_16x16x32_bf16 v[20:23], v[88:91], v[216:219], v[20:23]
	v_mfma_f32_16x16x32_bf16 v[16:19], v[96:99], v[216:219], v[16:19]
	v_mfma_f32_16x16x32_bf16 v[4:7], v[88:91], v[224:227], v[4:7]
	v_mfma_f32_16x16x32_bf16 v[0:3], v[96:99], v[224:227], v[0:3]
	v_mfma_f32_16x16x32_bf16 v[52:55], v[92:95], v[164:167], v[52:55]
	v_mfma_f32_16x16x32_bf16 v[48:51], v[100:103], v[164:167], v[48:51]
	v_mfma_f32_16x16x32_bf16 v[36:39], v[92:95], v[202:205], v[36:39]
	v_mfma_f32_16x16x32_bf16 v[32:35], v[100:103], v[202:205], v[32:35]
	v_mfma_f32_16x16x32_bf16 v[20:23], v[92:95], v[220:223], v[20:23]
	v_mfma_f32_16x16x32_bf16 v[16:19], v[100:103], v[220:223], v[16:19]
	v_mfma_f32_16x16x32_bf16 v[4:7], v[92:95], v[228:231], v[4:7]
	v_mfma_f32_16x16x32_bf16 v[0:3], v[100:103], v[228:231], v[0:3]
	s_setprio 0
	s_barrier
	s_add_i32 s63, 0, 0x18000
	s_add_i32 s64, 0, 0x1c000
	v_add_u32_e32 v76, s63, v171
	v_add_u32_e32 v100, s64, v171
	ds_read_b128 v[64:67], v76
	ds_read_b128 v[68:71], v76 offset:1024
	ds_read_b128 v[72:75], v76 offset:2048
	ds_read_b128 v[76:79], v76 offset:3072
	ds_read_b128 v[88:91], v100
	ds_read_b128 v[92:95], v100 offset:1024
	ds_read_b128 v[96:99], v100 offset:2048
	ds_read_b128 v[100:103], v100 offset:3072
	s_add_u32 s44, s46, 0x30000
	s_addc_u32 s45, s47, 0
	s_mov_b32 m0, s48
	v_lshl_add_u64 v[238:239], s[44:45], 0, v[178:179]
	ds_read_b128 v[160:163], v212 offset:32768
	ds_read_b128 v[164:167], v212 offset:33792
	ds_read_b128 v[198:201], v212 offset:34816
	ds_read_b128 v[202:205], v212 offset:35840
	ds_read_b128 v[216:219], v212 offset:36864
	ds_read_b128 v[220:223], v212 offset:37888
	ds_read_b128 v[224:227], v212 offset:38912
	ds_read_b128 v[228:231], v212 offset:39936
	global_load_lds_dwordx4 v[238:239], off
	v_lshl_add_u64 v[238:239], s[44:45], 0, v[174:175]
	s_mov_b32 m0, s49
	s_nop 0
	global_load_lds_dwordx4 v[238:239], off
	s_waitcnt vmcnt(8)
	s_waitcnt lgkmcnt(0)
	s_barrier
	s_setprio 1
	s_waitcnt lgkmcnt(0)
	v_mfma_f32_16x16x32_bf16 v[156:159], v[64:67], v[160:163], v[156:159]
	v_mfma_f32_16x16x32_bf16 v[152:155], v[72:75], v[160:163], v[152:155]
	v_mfma_f32_16x16x32_bf16 v[140:143], v[64:67], v[198:201], v[140:143]
	v_mfma_f32_16x16x32_bf16 v[136:139], v[72:75], v[198:201], v[136:139]
	v_mfma_f32_16x16x32_bf16 v[124:127], v[64:67], v[216:219], v[124:127]
	v_mfma_f32_16x16x32_bf16 v[120:123], v[72:75], v[216:219], v[120:123]
	v_mfma_f32_16x16x32_bf16 v[108:111], v[64:67], v[224:227], v[108:111]
	v_mfma_f32_16x16x32_bf16 v[104:107], v[72:75], v[224:227], v[104:107]
	v_mfma_f32_16x16x32_bf16 v[156:159], v[68:71], v[164:167], v[156:159]
	v_mfma_f32_16x16x32_bf16 v[152:155], v[76:79], v[164:167], v[152:155]
	v_mfma_f32_16x16x32_bf16 v[140:143], v[68:71], v[202:205], v[140:143]
	v_mfma_f32_16x16x32_bf16 v[136:139], v[76:79], v[202:205], v[136:139]
	v_mfma_f32_16x16x32_bf16 v[124:127], v[68:71], v[220:223], v[124:127]
	v_mfma_f32_16x16x32_bf16 v[120:123], v[76:79], v[220:223], v[120:123]
	v_mfma_f32_16x16x32_bf16 v[108:111], v[68:71], v[228:231], v[108:111]
	v_mfma_f32_16x16x32_bf16 v[104:107], v[76:79], v[228:231], v[104:107]
	s_setprio 0
	s_setprio 1
	v_mfma_f32_16x16x32_bf16 v[148:151], v[88:91], v[160:163], v[148:151]
	v_mfma_f32_16x16x32_bf16 v[144:147], v[96:99], v[160:163], v[144:147]
	v_mfma_f32_16x16x32_bf16 v[132:135], v[88:91], v[198:201], v[132:135]
	v_mfma_f32_16x16x32_bf16 v[128:131], v[96:99], v[198:201], v[128:131]
	v_mfma_f32_16x16x32_bf16 v[116:119], v[88:91], v[216:219], v[116:119]
	v_mfma_f32_16x16x32_bf16 v[112:115], v[96:99], v[216:219], v[112:115]
	v_mfma_f32_16x16x32_bf16 v[84:87], v[88:91], v[224:227], v[84:87]
	v_mfma_f32_16x16x32_bf16 v[80:83], v[96:99], v[224:227], v[80:83]
	v_mfma_f32_16x16x32_bf16 v[148:151], v[92:95], v[164:167], v[148:151]
	v_mfma_f32_16x16x32_bf16 v[144:147], v[100:103], v[164:167], v[144:147]
	v_mfma_f32_16x16x32_bf16 v[132:135], v[92:95], v[202:205], v[132:135]
	v_mfma_f32_16x16x32_bf16 v[128:131], v[100:103], v[202:205], v[128:131]
	v_mfma_f32_16x16x32_bf16 v[116:119], v[92:95], v[220:223], v[116:119]
	v_mfma_f32_16x16x32_bf16 v[112:115], v[100:103], v[220:223], v[112:115]
	v_mfma_f32_16x16x32_bf16 v[84:87], v[92:95], v[228:231], v[84:87]
	v_mfma_f32_16x16x32_bf16 v[80:83], v[100:103], v[228:231], v[80:83]
	s_setprio 0
	s_barrier
	s_add_i32 s44, s63, s33
	v_lshl_add_u64 v[206:207], v[206:207], 0, s[30:31]
	s_mov_b32 m0, s44
	ds_read_b128 v[160:163], v212 offset:49152
	ds_read_b128 v[164:167], v212 offset:50176
	ds_read_b128 v[198:201], v212 offset:51200
	ds_read_b128 v[202:205], v212 offset:52224
	ds_read_b128 v[216:219], v212 offset:53248
	ds_read_b128 v[220:223], v212 offset:54272
	ds_read_b128 v[224:227], v212 offset:55296
	ds_read_b128 v[228:231], v212 offset:56320
	global_load_lds_dwordx4 v[206:207], off
	s_add_i32 m0, s44, 0x2000
	s_add_u32 s2, s2, 0x30080
	v_lshl_add_u64 v[206:207], v[232:233], 0, s[30:31]
	s_addc_u32 s3, s3, 0
	s_add_i32 s44, s64, s33
	global_load_lds_dwordx4 v[206:207], off
	v_lshl_add_u64 v[206:207], s[2:3], 0, v[176:177]
	s_mov_b32 m0, s44
	s_nop 0
	global_load_lds_dwordx4 v[206:207], off
	v_lshl_add_u64 v[206:207], s[2:3], 0, v[172:173]
	s_add_i32 m0, s44, 0x2000
	s_nop 0
	global_load_lds_dwordx4 v[206:207], off
	v_lshl_add_u64 v[206:207], v[234:235], 0, s[30:31]
	s_mov_b32 m0, s51
	s_nop 0
	global_load_lds_dwordx4 v[206:207], off
	v_lshl_add_u64 v[206:207], v[236:237], 0, s[30:31]
	s_mov_b32 m0, s52
	s_nop 0
	global_load_lds_dwordx4 v[206:207], off
	s_waitcnt vmcnt(8)
	s_waitcnt lgkmcnt(0)
	s_barrier
	s_setprio 1
	s_waitcnt lgkmcnt(0)
	v_mfma_f32_16x16x32_bf16 v[60:63], v[64:67], v[160:163], v[60:63]
	v_mfma_f32_16x16x32_bf16 v[56:59], v[72:75], v[160:163], v[56:59]
	v_mfma_f32_16x16x32_bf16 v[44:47], v[64:67], v[198:201], v[44:47]
	v_mfma_f32_16x16x32_bf16 v[40:43], v[72:75], v[198:201], v[40:43]
	v_mfma_f32_16x16x32_bf16 v[28:31], v[64:67], v[216:219], v[28:31]
	v_mfma_f32_16x16x32_bf16 v[24:27], v[72:75], v[216:219], v[24:27]
	v_mfma_f32_16x16x32_bf16 v[12:15], v[64:67], v[224:227], v[12:15]
	v_mfma_f32_16x16x32_bf16 v[8:11], v[72:75], v[224:227], v[8:11]
	v_mfma_f32_16x16x32_bf16 v[60:63], v[68:71], v[164:167], v[60:63]
	v_mfma_f32_16x16x32_bf16 v[56:59], v[76:79], v[164:167], v[56:59]
	v_mfma_f32_16x16x32_bf16 v[44:47], v[68:71], v[202:205], v[44:47]
	v_mfma_f32_16x16x32_bf16 v[40:43], v[76:79], v[202:205], v[40:43]
	v_mfma_f32_16x16x32_bf16 v[28:31], v[68:71], v[220:223], v[28:31]
	v_mfma_f32_16x16x32_bf16 v[24:27], v[76:79], v[220:223], v[24:27]
	v_mfma_f32_16x16x32_bf16 v[12:15], v[68:71], v[228:231], v[12:15]
	v_mfma_f32_16x16x32_bf16 v[8:11], v[76:79], v[228:231], v[8:11]
	s_setprio 0
	s_setprio 1
	v_mfma_f32_16x16x32_bf16 v[52:55], v[88:91], v[160:163], v[52:55]
	v_mfma_f32_16x16x32_bf16 v[48:51], v[96:99], v[160:163], v[48:51]
	v_mfma_f32_16x16x32_bf16 v[36:39], v[88:91], v[198:201], v[36:39]
	v_mfma_f32_16x16x32_bf16 v[32:35], v[96:99], v[198:201], v[32:35]
	v_mfma_f32_16x16x32_bf16 v[20:23], v[88:91], v[216:219], v[20:23]
	v_mfma_f32_16x16x32_bf16 v[16:19], v[96:99], v[216:219], v[16:19]
	v_mfma_f32_16x16x32_bf16 v[4:7], v[88:91], v[224:227], v[4:7]
	v_mfma_f32_16x16x32_bf16 v[0:3], v[96:99], v[224:227], v[0:3]
	v_mfma_f32_16x16x32_bf16 v[52:55], v[92:95], v[164:167], v[52:55]
	v_mfma_f32_16x16x32_bf16 v[48:51], v[100:103], v[164:167], v[48:51]
	v_mfma_f32_16x16x32_bf16 v[36:39], v[92:95], v[202:205], v[36:39]
	v_mfma_f32_16x16x32_bf16 v[32:35], v[100:103], v[202:205], v[32:35]
	v_mfma_f32_16x16x32_bf16 v[20:23], v[92:95], v[220:223], v[20:23]
	v_mfma_f32_16x16x32_bf16 v[16:19], v[100:103], v[220:223], v[16:19]
	v_mfma_f32_16x16x32_bf16 v[4:7], v[92:95], v[228:231], v[4:7]
	v_mfma_f32_16x16x32_bf16 v[0:3], v[100:103], v[228:231], v[0:3]
	s_setprio 0
	s_barrier
	s_add_i32 s62, s62, 2
	s_add_u32 s60, s60, 0x100
	s_addc_u32 s61, s61, 0
	s_cmp_gt_u32 s62, 9
	s_mov_b64 s[44:45], s[0:1]
	s_cbranch_scc0 .LBB0_1010
	s_mov_b32 s99, -2
	s_and_b64 vcc, exec, s[34:35]
	s_cbranch_vccz .LBB0_1013
	s_barrier

.LBB0_1073:
	s_add_u32 s30, s20, 0xa4000
	s_addc_u32 s31, s21, 0
	s_add_u32 s34, s20, 0xae400
	s_addc_u32 s35, s21, 0
	s_lshl_b32 s5, s9, 5
	s_mov_b64 s[36:37], 0x80
	s_and_b32 s9, s5, 0x60
	s_add_i32 m0, s57, 0x18000
	v_lshl_add_u64 v[6:7], v[6:7], 0, s[36:37]
	s_lshl_b32 s40, s8, 13
	s_lshl_b32 s42, s9, 7
	s_waitcnt vmcnt(2)
	s_barrier
	global_load_lds_dwordx4 v[6:7], off
	v_lshl_add_u64 v[4:5], v[4:5], 0, s[36:37]
	s_add_i32 m0, s57, 0x1a000
	s_add_i32 s62, s57, 0x8000
	s_add_i32 s63, s57, 0xa000
	global_load_lds_dwordx4 v[4:5], off
	v_lshl_add_u64 v[0:1], v[0:1], 0, s[36:37]
	s_mov_b32 m0, s62
	s_add_u32 s38, s2, 0x40080
	global_load_lds_dwordx4 v[0:1], off
	v_lshl_add_u64 v[0:1], v[2:3], 0, s[36:37]
	s_mov_b32 m0, s63
	s_addc_u32 s39, s3, 0
	global_load_lds_dwordx4 v[0:1], off
	s_add_i32 m0, s57, 0x1c000
	v_lshl_add_u64 v[0:1], s[38:39], 0, v[164:165]
	global_load_lds_dwordx4 v[0:1], off
	v_lshl_add_u64 v[0:1], s[38:39], 0, v[160:161]
	s_add_i32 m0, s57, 0x1e000
	s_cmpk_lt_u32 s1, 0x100
	global_load_lds_dwordx4 v[0:1], off
	v_lshrrev_b32_e32 v1, 1, v9
	v_and_b32_e32 v1, 24, v1
	v_and_b32_e32 v0, 15, v9
	v_lshlrev_b32_e32 v2, 1, v1
	v_lshl_or_b32 v169, s8, 6, v0
	v_lshl_or_b32 v0, v0, 6, v2
	v_lshlrev_b32_e32 v2, 2, v9
	v_and_b32_e32 v2, 32, v2
	v_bitop3_b32 v3, v0, s40, v2 bitop3:0xde
	v_bitop3_b32 v171, v0, s42, v2 bitop3:0xde
	v_lshlrev_b32_e32 v0, 14, v13
	v_and_b32_e32 v0, 0xffff8000, v0
	v_or_b32_e32 v187, s9, v1
	v_lshl_add_u32 v0, v12, 11, v0
	v_and_b32_e32 v1, 1, v13
	v_lshl_or_b32 v0, v1, 6, v0
	v_lshl_add_u32 v172, v14, 1, v0
	v_lshlrev_b32_e32 v0, 14, v8
	v_and_b32_e32 v0, 0xffff8000, v0
	s_waitcnt vmcnt(6)
	s_mov_b32 s99, 0x7fff0000
	v_lshl_add_u32 v0, v10, 11, v0
	v_and_b32_e32 v1, 1, v8
	s_cselect_b64 s[38:39], -1, 0
	v_lshl_or_b32 v0, v1, 6, v0
	s_add_i32 s64, 0, 0x10000
	s_add_i32 s65, 0, 0x14000
	s_sext_i32_i8 s5, s0
	v_mov_b32_e32 v173, v165
	v_lshl_add_u32 v174, v11, 1, v0
	v_mov_b32_e32 v175, v165
	v_mov_b64_e32 v[176:177], 0x800
	v_mov_b64_e32 v[178:179], 0x7ff
	v_add_u32_e32 v199, s64, v171
	v_add_u32_e32 v205, s65, v171
	v_add_u32_e32 v211, 0, v3
	s_mov_b32 s40, 0x3a800000
	s_mov_b32 s66, 0xf800000
	v_mov_b32_e32 v217, 0x260
	s_mov_b64 s[42:43], 0x120000
	s_mov_b32 s67, 0x120000
	s_mov_b64 s[44:45], 0x140000
	s_mov_b32 s68, 0x140000
	s_mov_b64 s[46:47], 0x160000
	s_mov_b32 s69, 0x160000
	s_barrier
	s_branch .LBB0_1076

.LBB0_1082:
	s_ashr_i32 s51, s50, 31
	s_lshl_b64 s[8:9], s[50:51], 19
	s_add_u32 s52, s26, s8
	s_addc_u32 s53, s27, s9
	s_and_b64 s[8:9], s[0:1], exec
	s_cselect_b32 s51, s53, s7
	s_cselect_b32 s70, s52, s6
	s_ashr_i32 s49, s48, 31
	s_lshl_b64 s[8:9], s[48:49], 19
	s_add_u32 s54, s33, s8
	s_addc_u32 s55, s41, s9
	s_and_b64 s[8:9], s[0:1], exec
	s_cselect_b32 s49, s55, s3
	s_cselect_b32 s71, s54, s2
	s_add_u32 s6, s6, 0x40080
	s_addc_u32 s7, s7, 0
	s_add_u32 s72, s2, 0x100
	v_mov_b32_e32 v0, 0
	s_addc_u32 s73, s3, 0
	s_mov_b32 s74, -2
	v_mov_b32_e32 v1, v0
	v_mov_b32_e32 v2, v0
	v_mov_b32_e32 v3, v0
	v_mov_b32_e32 v4, v0
	v_mov_b32_e32 v5, v0
	v_mov_b32_e32 v6, v0
	v_mov_b32_e32 v7, v0
	v_mov_b32_e32 v16, v0
	v_mov_b32_e32 v17, v0
	v_mov_b32_e32 v18, v0
	v_mov_b32_e32 v19, v0
	v_mov_b32_e32 v20, v0
	v_mov_b32_e32 v21, v0
	v_mov_b32_e32 v22, v0
	v_mov_b32_e32 v23, v0
	v_mov_b32_e32 v32, v0
	v_mov_b32_e32 v33, v0
	v_mov_b32_e32 v34, v0
	v_mov_b32_e32 v35, v0
	v_mov_b32_e32 v36, v0
	v_mov_b32_e32 v37, v0
	v_mov_b32_e32 v38, v0
	v_mov_b32_e32 v39, v0
	v_mov_b32_e32 v48, v0
	v_mov_b32_e32 v49, v0
	v_mov_b32_e32 v50, v0
	v_mov_b32_e32 v51, v0
	v_mov_b32_e32 v52, v0
	v_mov_b32_e32 v53, v0
	v_mov_b32_e32 v54, v0
	v_mov_b32_e32 v55, v0
	v_mov_b32_e32 v8, v0
	v_mov_b32_e32 v9, v0
	v_mov_b32_e32 v10, v0
	v_mov_b32_e32 v11, v0
	v_mov_b32_e32 v12, v0
	v_mov_b32_e32 v13, v0
	v_mov_b32_e32 v14, v0
	v_mov_b32_e32 v15, v0
	v_mov_b32_e32 v24, v0
	v_mov_b32_e32 v25, v0
	v_mov_b32_e32 v26, v0
	v_mov_b32_e32 v27, v0
	v_mov_b32_e32 v28, v0
	v_mov_b32_e32 v29, v0
	v_mov_b32_e32 v30, v0
	v_mov_b32_e32 v31, v0
	v_mov_b32_e32 v40, v0
	v_mov_b32_e32 v41, v0
	v_mov_b32_e32 v42, v0
	v_mov_b32_e32 v43, v0
	v_mov_b32_e32 v44, v0
	v_mov_b32_e32 v45, v0
	v_mov_b32_e32 v46, v0
	v_mov_b32_e32 v47, v0
	v_mov_b32_e32 v56, v0
	v_mov_b32_e32 v57, v0
	v_mov_b32_e32 v58, v0
	v_mov_b32_e32 v59, v0
	v_mov_b32_e32 v60, v0
	v_mov_b32_e32 v61, v0
	v_mov_b32_e32 v62, v0
	v_mov_b32_e32 v63, v0
	v_mov_b32_e32 v64, v0
	v_mov_b32_e32 v65, v0
	v_mov_b32_e32 v66, v0
	v_mov_b32_e32 v67, v0
	v_mov_b32_e32 v68, v0
	v_mov_b32_e32 v69, v0
	v_mov_b32_e32 v70, v0
	v_mov_b32_e32 v71, v0
	v_mov_b32_e32 v80, v0
	v_mov_b32_e32 v81, v0
	v_mov_b32_e32 v82, v0
	v_mov_b32_e32 v83, v0
	v_mov_b32_e32 v84, v0
	v_mov_b32_e32 v85, v0
	v_mov_b32_e32 v86, v0
	v_mov_b32_e32 v87, v0
	v_mov_b32_e32 v96, v0
	v_mov_b32_e32 v97, v0
	v_mov_b32_e32 v98, v0
	v_mov_b32_e32 v99, v0
	v_mov_b32_e32 v100, v0
	v_mov_b32_e32 v101, v0
	v_mov_b32_e32 v102, v0
	v_mov_b32_e32 v103, v0
	v_mov_b32_e32 v112, v0
	v_mov_b32_e32 v113, v0
	v_mov_b32_e32 v114, v0
	v_mov_b32_e32 v115, v0
	v_mov_b32_e32 v116, v0
	v_mov_b32_e32 v117, v0
	v_mov_b32_e32 v118, v0
	v_mov_b32_e32 v119, v0
	v_mov_b32_e32 v72, v0
	v_mov_b32_e32 v73, v0
	v_mov_b32_e32 v74, v0
	v_mov_b32_e32 v75, v0
	v_mov_b32_e32 v76, v0
	v_mov_b32_e32 v77, v0
	v_mov_b32_e32 v78, v0
	v_mov_b32_e32 v79, v0
	v_mov_b32_e32 v88, v0
	v_mov_b32_e32 v89, v0
	v_mov_b32_e32 v90, v0
	v_mov_b32_e32 v91, v0
	v_mov_b32_e32 v92, v0
	v_mov_b32_e32 v93, v0
	v_mov_b32_e32 v94, v0
	v_mov_b32_e32 v95, v0
	v_mov_b32_e32 v104, v0
	v_mov_b32_e32 v105, v0
	v_mov_b32_e32 v106, v0
	v_mov_b32_e32 v107, v0
	v_mov_b32_e32 v108, v0
	v_mov_b32_e32 v109, v0
	v_mov_b32_e32 v110, v0
	v_mov_b32_e32 v111, v0
	v_mov_b32_e32 v120, v0
	v_mov_b32_e32 v121, v0
	v_mov_b32_e32 v122, v0
	v_mov_b32_e32 v123, v0
	v_mov_b32_e32 v124, v0
	v_mov_b32_e32 v125, v0
	v_mov_b32_e32 v126, v0
	v_mov_b32_e32 v127, v0
.LBB0_1083:
	ds_read_b128 v[128:131], v199
	ds_read_b128 v[132:135], v199 offset:1024
	ds_read_b128 v[136:139], v199 offset:2048
	ds_read_b128 v[140:143], v199 offset:3072
	ds_read_b128 v[144:147], v205
	ds_read_b128 v[148:151], v205 offset:1024
	ds_read_b128 v[152:155], v205 offset:2048
	ds_read_b128 v[156:159], v205 offset:3072
	s_add_u32 s2, s6, 0xfffc0080
	s_addc_u32 s3, s7, -1
	s_cmp_eq_u32 s74, 12
	s_cselect_b32 s9, s51, s3
	s_cselect_b32 s8, s70, s2
	s_cselect_b32 s3, s49, s73
	s_cselect_b32 s2, s71, s72
	v_lshl_add_u64 v[184:185], s[6:7], 0, v[172:173]
	s_add_i32 m0, s57, 0xc000
	ds_read_b128 v[180:183], v211
	ds_read_b128 v[188:191], v211 offset:1024
	ds_read_b128 v[192:195], v211 offset:2048
	ds_read_b128 v[200:203], v211 offset:3072
	ds_read_b128 v[206:209], v211 offset:4096
	ds_read_b128 v[218:221], v211 offset:5120
	ds_read_b128 v[222:225], v211 offset:6144
	ds_read_b128 v[226:229], v211 offset:7168
	global_load_lds_dwordx4 v[184:185], off
	v_lshl_add_u64 v[184:185], s[6:7], 0, v[174:175]
	s_add_i32 m0, s57, 0xe000
	s_nop 0
	global_load_lds_dwordx4 v[184:185], off
	s_cmp_eq_u32 s74, s99
	s_cbranch_scc1 .Ls1a_P12_0
	s_waitcnt vmcnt(8)
	s_branch .Ls1b_P12_0

.Ls1b_P12_0:
	s_waitcnt lgkmcnt(0)
	s_barrier
	s_setprio 1
	s_waitcnt lgkmcnt(0)
	v_mfma_f32_16x16x32_bf16 v[124:127], v[128:131], v[180:183], v[124:127]
	v_mfma_f32_16x16x32_bf16 v[120:123], v[136:139], v[180:183], v[120:123]
	v_mfma_f32_16x16x32_bf16 v[108:111], v[128:131], v[192:195], v[108:111]
	v_mfma_f32_16x16x32_bf16 v[104:107], v[136:139], v[192:195], v[104:107]
	v_mfma_f32_16x16x32_bf16 v[92:95], v[128:131], v[206:209], v[92:95]
	v_mfma_f32_16x16x32_bf16 v[88:91], v[136:139], v[206:209], v[88:91]
	v_mfma_f32_16x16x32_bf16 v[76:79], v[128:131], v[222:225], v[76:79]
	v_mfma_f32_16x16x32_bf16 v[72:75], v[136:139], v[222:225], v[72:75]
	v_mfma_f32_16x16x32_bf16 v[124:127], v[132:135], v[188:191], v[124:127]
	v_mfma_f32_16x16x32_bf16 v[120:123], v[140:143], v[188:191], v[120:123]
	v_mfma_f32_16x16x32_bf16 v[108:111], v[132:135], v[200:203], v[108:111]
	v_mfma_f32_16x16x32_bf16 v[104:107], v[140:143], v[200:203], v[104:107]
	v_mfma_f32_16x16x32_bf16 v[92:95], v[132:135], v[218:221], v[92:95]
	v_mfma_f32_16x16x32_bf16 v[88:91], v[140:143], v[218:221], v[88:91]
	v_mfma_f32_16x16x32_bf16 v[76:79], v[132:135], v[226:229], v[76:79]
	v_mfma_f32_16x16x32_bf16 v[72:75], v[140:143], v[226:229], v[72:75]
	s_setprio 0
	s_setprio 1
	v_mfma_f32_16x16x32_bf16 v[116:119], v[144:147], v[180:183], v[116:119]
	v_mfma_f32_16x16x32_bf16 v[112:115], v[152:155], v[180:183], v[112:115]
	v_mfma_f32_16x16x32_bf16 v[100:103], v[144:147], v[192:195], v[100:103]
	v_mfma_f32_16x16x32_bf16 v[96:99], v[152:155], v[192:195], v[96:99]
	v_mfma_f32_16x16x32_bf16 v[84:87], v[144:147], v[206:209], v[84:87]
	v_mfma_f32_16x16x32_bf16 v[80:83], v[152:155], v[206:209], v[80:83]
	v_mfma_f32_16x16x32_bf16 v[68:71], v[144:147], v[222:225], v[68:71]
	v_mfma_f32_16x16x32_bf16 v[64:67], v[152:155], v[222:225], v[64:67]
	v_mfma_f32_16x16x32_bf16 v[116:119], v[148:151], v[188:191], v[116:119]
	v_mfma_f32_16x16x32_bf16 v[112:115], v[156:159], v[188:191], v[112:115]
	v_mfma_f32_16x16x32_bf16 v[100:103], v[148:151], v[200:203], v[100:103]
	v_mfma_f32_16x16x32_bf16 v[96:99], v[156:159], v[200:203], v[96:99]
	v_mfma_f32_16x16x32_bf16 v[84:87], v[148:151], v[218:221], v[84:87]
	v_mfma_f32_16x16x32_bf16 v[80:83], v[156:159], v[218:221], v[80:83]
	v_mfma_f32_16x16x32_bf16 v[68:71], v[148:151], v[226:229], v[68:71]
	v_mfma_f32_16x16x32_bf16 v[64:67], v[156:159], v[226:229], v[64:67]
	s_setprio 0
	s_barrier
	s_add_i32 s75, s64, s56
	v_lshl_add_u64 v[184:185], s[2:3], 0, v[164:165]
	s_mov_b32 m0, s75
	ds_read_b128 v[180:183], v211 offset:16384
	ds_read_b128 v[188:191], v211 offset:17408
	ds_read_b128 v[192:195], v211 offset:18432
	ds_read_b128 v[200:203], v211 offset:19456
	ds_read_b128 v[206:209], v211 offset:20480
	ds_read_b128 v[218:221], v211 offset:21504
	ds_read_b128 v[222:225], v211 offset:22528
	ds_read_b128 v[226:229], v211 offset:23552
	global_load_lds_dwordx4 v[184:185], off
	s_add_i32 m0, s75, 0x2000
	s_add_u32 s76, s2, 0x40000
	v_lshl_add_u64 v[196:197], s[2:3], 0, v[160:161]
	s_addc_u32 s77, s3, 0
	s_add_i32 s75, s65, s56
	global_load_lds_dwordx4 v[196:197], off
	v_lshl_add_u64 v[212:213], s[76:77], 0, v[164:165]
	s_mov_b32 m0, s75
	v_lshl_add_u64 v[230:231], s[8:9], 0, v[162:163]
	global_load_lds_dwordx4 v[212:213], off
	v_lshl_add_u64 v[212:213], s[76:77], 0, v[160:161]
	s_add_i32 m0, s75, 0x2000
	s_nop 0
	global_load_lds_dwordx4 v[212:213], off
	v_lshl_add_u64 v[212:213], s[8:9], 0, v[166:167]
	s_mov_b32 m0, s57
	s_nop 0
	global_load_lds_dwordx4 v[212:213], off
	s_mov_b32 m0, s58
	s_nop 0
	global_load_lds_dwordx4 v[230:231], off
	s_cmp_eq_u32 s74, s99
	s_cbranch_scc1 .Ls1a_P12_1
	s_waitcnt vmcnt(8)
	s_branch .Ls1b_P12_1

.Ls1b_P12_1:
	s_waitcnt lgkmcnt(0)
	s_barrier
	s_setprio 1
	s_waitcnt lgkmcnt(0)
	v_mfma_f32_16x16x32_bf16 v[60:63], v[128:131], v[180:183], v[60:63]
	v_mfma_f32_16x16x32_bf16 v[56:59], v[136:139], v[180:183], v[56:59]
	v_mfma_f32_16x16x32_bf16 v[44:47], v[128:131], v[192:195], v[44:47]
	v_mfma_f32_16x16x32_bf16 v[40:43], v[136:139], v[192:195], v[40:43]
	v_mfma_f32_16x16x32_bf16 v[28:31], v[128:131], v[206:209], v[28:31]
	v_mfma_f32_16x16x32_bf16 v[24:27], v[136:139], v[206:209], v[24:27]
	v_mfma_f32_16x16x32_bf16 v[12:15], v[128:131], v[222:225], v[12:15]
	v_mfma_f32_16x16x32_bf16 v[8:11], v[136:139], v[222:225], v[8:11]
	v_mfma_f32_16x16x32_bf16 v[60:63], v[132:135], v[188:191], v[60:63]
	v_mfma_f32_16x16x32_bf16 v[56:59], v[140:143], v[188:191], v[56:59]
	v_mfma_f32_16x16x32_bf16 v[44:47], v[132:135], v[200:203], v[44:47]
	v_mfma_f32_16x16x32_bf16 v[40:43], v[140:143], v[200:203], v[40:43]
	v_mfma_f32_16x16x32_bf16 v[28:31], v[132:135], v[218:221], v[28:31]
	v_mfma_f32_16x16x32_bf16 v[24:27], v[140:143], v[218:221], v[24:27]
	v_mfma_f32_16x16x32_bf16 v[12:15], v[132:135], v[226:229], v[12:15]
	v_mfma_f32_16x16x32_bf16 v[8:11], v[140:143], v[226:229], v[8:11]
	s_setprio 0
	s_setprio 1
	v_mfma_f32_16x16x32_bf16 v[52:55], v[144:147], v[180:183], v[52:55]
	v_mfma_f32_16x16x32_bf16 v[48:51], v[152:155], v[180:183], v[48:51]
	v_mfma_f32_16x16x32_bf16 v[36:39], v[144:147], v[192:195], v[36:39]
	v_mfma_f32_16x16x32_bf16 v[32:35], v[152:155], v[192:195], v[32:35]
	v_mfma_f32_16x16x32_bf16 v[20:23], v[144:147], v[206:209], v[20:23]
	v_mfma_f32_16x16x32_bf16 v[16:19], v[152:155], v[206:209], v[16:19]
	v_mfma_f32_16x16x32_bf16 v[4:7], v[144:147], v[222:225], v[4:7]
	v_mfma_f32_16x16x32_bf16 v[0:3], v[152:155], v[222:225], v[0:3]
	v_mfma_f32_16x16x32_bf16 v[52:55], v[148:151], v[188:191], v[52:55]
	v_mfma_f32_16x16x32_bf16 v[48:51], v[156:159], v[188:191], v[48:51]
	v_mfma_f32_16x16x32_bf16 v[36:39], v[148:151], v[200:203], v[36:39]
	v_mfma_f32_16x16x32_bf16 v[32:35], v[156:159], v[200:203], v[32:35]
	v_mfma_f32_16x16x32_bf16 v[20:23], v[148:151], v[218:221], v[20:23]
	v_mfma_f32_16x16x32_bf16 v[16:19], v[156:159], v[218:221], v[16:19]
	v_mfma_f32_16x16x32_bf16 v[4:7], v[148:151], v[226:229], v[4:7]
	v_mfma_f32_16x16x32_bf16 v[0:3], v[156:159], v[226:229], v[0:3]
	s_setprio 0
	s_barrier
	s_add_i32 s75, 0, 0x18000
	s_add_i32 s76, 0, 0x1c000
	v_add_u32_e32 v140, s75, v171
	v_add_u32_e32 v156, s76, v171
	ds_read_b128 v[128:131], v140
	ds_read_b128 v[132:135], v140 offset:1024
	ds_read_b128 v[136:139], v140 offset:2048
	ds_read_b128 v[140:143], v140 offset:3072
	ds_read_b128 v[144:147], v156
	ds_read_b128 v[148:151], v156 offset:1024
	ds_read_b128 v[152:155], v156 offset:2048
	ds_read_b128 v[156:159], v156 offset:3072
	s_add_u32 s8, s8, 0x40000
	s_addc_u32 s9, s9, 0
	s_mov_b32 m0, s59
	v_lshl_add_u64 v[232:233], s[8:9], 0, v[166:167]
	ds_read_b128 v[180:183], v211 offset:32768
	ds_read_b128 v[188:191], v211 offset:33792
	ds_read_b128 v[192:195], v211 offset:34816
	ds_read_b128 v[200:203], v211 offset:35840
	ds_read_b128 v[206:209], v211 offset:36864
	ds_read_b128 v[218:221], v211 offset:37888
	ds_read_b128 v[222:225], v211 offset:38912
	ds_read_b128 v[226:229], v211 offset:39936
	global_load_lds_dwordx4 v[232:233], off
	v_lshl_add_u64 v[232:233], s[8:9], 0, v[162:163]
	s_mov_b32 m0, s60
	s_nop 0
	global_load_lds_dwordx4 v[232:233], off
	s_waitcnt vmcnt(8)
	s_waitcnt lgkmcnt(0)
	s_barrier
	s_setprio 1
	s_waitcnt lgkmcnt(0)
	v_mfma_f32_16x16x32_bf16 v[124:127], v[128:131], v[180:183], v[124:127]
	v_mfma_f32_16x16x32_bf16 v[120:123], v[136:139], v[180:183], v[120:123]
	v_mfma_f32_16x16x32_bf16 v[108:111], v[128:131], v[192:195], v[108:111]
	v_mfma_f32_16x16x32_bf16 v[104:107], v[136:139], v[192:195], v[104:107]
	v_mfma_f32_16x16x32_bf16 v[92:95], v[128:131], v[206:209], v[92:95]
	v_mfma_f32_16x16x32_bf16 v[88:91], v[136:139], v[206:209], v[88:91]
	v_mfma_f32_16x16x32_bf16 v[76:79], v[128:131], v[222:225], v[76:79]
	v_mfma_f32_16x16x32_bf16 v[72:75], v[136:139], v[222:225], v[72:75]
	v_mfma_f32_16x16x32_bf16 v[124:127], v[132:135], v[188:191], v[124:127]
	v_mfma_f32_16x16x32_bf16 v[120:123], v[140:143], v[188:191], v[120:123]
	v_mfma_f32_16x16x32_bf16 v[108:111], v[132:135], v[200:203], v[108:111]
	v_mfma_f32_16x16x32_bf16 v[104:107], v[140:143], v[200:203], v[104:107]
	v_mfma_f32_16x16x32_bf16 v[92:95], v[132:135], v[218:221], v[92:95]
	v_mfma_f32_16x16x32_bf16 v[88:91], v[140:143], v[218:221], v[88:91]
	v_mfma_f32_16x16x32_bf16 v[76:79], v[132:135], v[226:229], v[76:79]
	v_mfma_f32_16x16x32_bf16 v[72:75], v[140:143], v[226:229], v[72:75]
	s_setprio 0
	s_setprio 1
	v_mfma_f32_16x16x32_bf16 v[116:119], v[144:147], v[180:183], v[116:119]
	v_mfma_f32_16x16x32_bf16 v[112:115], v[152:155], v[180:183], v[112:115]
	v_mfma_f32_16x16x32_bf16 v[100:103], v[144:147], v[192:195], v[100:103]
	v_mfma_f32_16x16x32_bf16 v[96:99], v[152:155], v[192:195], v[96:99]
	v_mfma_f32_16x16x32_bf16 v[84:87], v[144:147], v[206:209], v[84:87]
	v_mfma_f32_16x16x32_bf16 v[80:83], v[152:155], v[206:209], v[80:83]
	v_mfma_f32_16x16x32_bf16 v[68:71], v[144:147], v[222:225], v[68:71]
	v_mfma_f32_16x16x32_bf16 v[64:67], v[152:155], v[222:225], v[64:67]
	v_mfma_f32_16x16x32_bf16 v[116:119], v[148:151], v[188:191], v[116:119]
	v_mfma_f32_16x16x32_bf16 v[112:115], v[156:159], v[188:191], v[112:115]
	v_mfma_f32_16x16x32_bf16 v[100:103], v[148:151], v[200:203], v[100:103]
	v_mfma_f32_16x16x32_bf16 v[96:99], v[156:159], v[200:203], v[96:99]
	v_mfma_f32_16x16x32_bf16 v[84:87], v[148:151], v[218:221], v[84:87]
	v_mfma_f32_16x16x32_bf16 v[80:83], v[156:159], v[218:221], v[80:83]
	v_mfma_f32_16x16x32_bf16 v[68:71], v[148:151], v[226:229], v[68:71]
	v_mfma_f32_16x16x32_bf16 v[64:67], v[156:159], v[226:229], v[64:67]
	s_setprio 0
	s_barrier
	s_add_i32 s8, s75, s56
	v_lshl_add_u64 v[184:185], v[184:185], 0, s[36:37]
	s_mov_b32 m0, s8
	ds_read_b128 v[180:183], v211 offset:49152
	ds_read_b128 v[188:191], v211 offset:50176
	ds_read_b128 v[192:195], v211 offset:51200
	ds_read_b128 v[200:203], v211 offset:52224
	ds_read_b128 v[206:209], v211 offset:53248
	ds_read_b128 v[218:221], v211 offset:54272
	ds_read_b128 v[222:225], v211 offset:55296
	ds_read_b128 v[226:229], v211 offset:56320
	global_load_lds_dwordx4 v[184:185], off
	s_add_i32 m0, s8, 0x2000
	s_add_u32 s2, s2, 0x40080
	v_lshl_add_u64 v[184:185], v[196:197], 0, s[36:37]
	s_addc_u32 s3, s3, 0
	s_add_i32 s8, s76, s56
	global_load_lds_dwordx4 v[184:185], off
	v_lshl_add_u64 v[184:185], s[2:3], 0, v[164:165]
	s_mov_b32 m0, s8
	s_nop 0
	global_load_lds_dwordx4 v[184:185], off
	v_lshl_add_u64 v[184:185], s[2:3], 0, v[160:161]
	s_add_i32 m0, s8, 0x2000
	s_nop 0
	global_load_lds_dwordx4 v[184:185], off
	v_lshl_add_u64 v[184:185], v[212:213], 0, s[36:37]
	s_mov_b32 m0, s62
	s_nop 0
	global_load_lds_dwordx4 v[184:185], off
	v_lshl_add_u64 v[184:185], v[230:231], 0, s[36:37]
	s_mov_b32 m0, s63
	s_nop 0
	global_load_lds_dwordx4 v[184:185], off
	s_waitcnt vmcnt(8)
	s_waitcnt lgkmcnt(0)
	s_barrier
	s_setprio 1
	s_waitcnt lgkmcnt(0)
	v_mfma_f32_16x16x32_bf16 v[60:63], v[128:131], v[180:183], v[60:63]
	v_mfma_f32_16x16x32_bf16 v[56:59], v[136:139], v[180:183], v[56:59]
	v_mfma_f32_16x16x32_bf16 v[44:47], v[128:131], v[192:195], v[44:47]
	v_mfma_f32_16x16x32_bf16 v[40:43], v[136:139], v[192:195], v[40:43]
	v_mfma_f32_16x16x32_bf16 v[28:31], v[128:131], v[206:209], v[28:31]
	v_mfma_f32_16x16x32_bf16 v[24:27], v[136:139], v[206:209], v[24:27]
	v_mfma_f32_16x16x32_bf16 v[12:15], v[128:131], v[222:225], v[12:15]
	v_mfma_f32_16x16x32_bf16 v[8:11], v[136:139], v[222:225], v[8:11]
	v_mfma_f32_16x16x32_bf16 v[60:63], v[132:135], v[188:191], v[60:63]
	v_mfma_f32_16x16x32_bf16 v[56:59], v[140:143], v[188:191], v[56:59]
	v_mfma_f32_16x16x32_bf16 v[44:47], v[132:135], v[200:203], v[44:47]
	v_mfma_f32_16x16x32_bf16 v[40:43], v[140:143], v[200:203], v[40:43]
	v_mfma_f32_16x16x32_bf16 v[28:31], v[132:135], v[218:221], v[28:31]
	v_mfma_f32_16x16x32_bf16 v[24:27], v[140:143], v[218:221], v[24:27]
	v_mfma_f32_16x16x32_bf16 v[12:15], v[132:135], v[226:229], v[12:15]
	v_mfma_f32_16x16x32_bf16 v[8:11], v[140:143], v[226:229], v[8:11]
	s_setprio 0
	s_setprio 1
	v_mfma_f32_16x16x32_bf16 v[52:55], v[144:147], v[180:183], v[52:55]
	v_mfma_f32_16x16x32_bf16 v[48:51], v[152:155], v[180:183], v[48:51]
	v_mfma_f32_16x16x32_bf16 v[36:39], v[144:147], v[192:195], v[36:39]
	v_mfma_f32_16x16x32_bf16 v[32:35], v[152:155], v[192:195], v[32:35]
	v_mfma_f32_16x16x32_bf16 v[20:23], v[144:147], v[206:209], v[20:23]
	v_mfma_f32_16x16x32_bf16 v[16:19], v[152:155], v[206:209], v[16:19]
	v_mfma_f32_16x16x32_bf16 v[4:7], v[144:147], v[222:225], v[4:7]
	v_mfma_f32_16x16x32_bf16 v[0:3], v[152:155], v[222:225], v[0:3]
	v_mfma_f32_16x16x32_bf16 v[52:55], v[148:151], v[188:191], v[52:55]
	v_mfma_f32_16x16x32_bf16 v[48:51], v[156:159], v[188:191], v[48:51]
	v_mfma_f32_16x16x32_bf16 v[36:39], v[148:151], v[200:203], v[36:39]
	v_mfma_f32_16x16x32_bf16 v[32:35], v[156:159], v[200:203], v[32:35]
	v_mfma_f32_16x16x32_bf16 v[20:23], v[148:151], v[218:221], v[20:23]
	v_mfma_f32_16x16x32_bf16 v[16:19], v[156:159], v[218:221], v[16:19]
	v_mfma_f32_16x16x32_bf16 v[4:7], v[148:151], v[226:229], v[4:7]
	v_mfma_f32_16x16x32_bf16 v[0:3], v[156:159], v[226:229], v[0:3]
	s_setprio 0
	s_barrier
	s_add_i32 s74, s74, 2
	s_add_u32 s6, s6, 0x100
	s_addc_u32 s7, s7, 0
	s_add_u32 s72, s72, 0x100
	s_addc_u32 s73, s73, 0
	s_cmp_gt_u32 s74, 13
	s_cbranch_scc0 .LBB0_1083
	s_mov_b32 s99, -2
	s_and_b64 vcc, exec, s[38:39]
	s_cbranch_vccz .LBB0_1086
	s_barrier

.LBB0_1146:
	v_readlane_b32 s60, v251, 1
	v_readlane_b32 s74, v251, 15
	v_readlane_b32 s75, v251, 16
	s_mov_b64 s[30:31], s[74:75]
	s_add_u32 s10, s30, 0x1000
	s_addc_u32 s11, s31, 0
	s_add_u32 s12, s12, 0x1000
	s_addc_u32 s13, s13, 0
	s_lshl_b32 s1, s7, 5
	s_mov_b64 s[30:31], 0x80
	s_and_b32 s38, s1, 0x60
	s_add_i32 m0, s52, 0x18000
	v_lshl_add_u64 v[6:7], v[6:7], 0, s[30:31]
	s_lshl_b32 s36, s6, 13
	s_lshl_b32 s7, s38, 7
	s_waitcnt vmcnt(2)
	s_barrier
	global_load_lds_dwordx4 v[6:7], off
	v_lshl_add_u64 v[4:5], v[4:5], 0, s[30:31]
	s_add_i32 m0, s52, 0x1a000
	s_add_i32 s57, s52, 0x8000
	s_add_i32 s58, s52, 0xa000
	global_load_lds_dwordx4 v[4:5], off
	v_lshl_add_u64 v[0:1], v[0:1], 0, s[30:31]
	s_mov_b32 m0, s57
	s_add_u32 s34, s2, 0x100080
	global_load_lds_dwordx4 v[0:1], off
	v_lshl_add_u64 v[0:1], v[2:3], 0, s[30:31]
	s_mov_b32 m0, s58
	s_addc_u32 s35, s3, 0
	global_load_lds_dwordx4 v[0:1], off
	s_add_i32 m0, s52, 0x1c000
	v_lshl_add_u64 v[0:1], s[34:35], 0, v[176:177]
	global_load_lds_dwordx4 v[0:1], off
	v_lshl_add_u64 v[0:1], s[34:35], 0, v[172:173]
	s_add_i32 m0, s52, 0x1e000
	v_bfe_u32 v2, v215, 4, 2
	global_load_lds_dwordx4 v[0:1], off
	v_and_b32_e32 v0, 15, v215
	v_lshlrev_b32_e32 v1, 4, v2
	v_lshl_or_b32 v169, s6, 6, v0
	v_lshl_or_b32 v0, v0, 6, v1
	v_lshlrev_b32_e32 v1, 2, v215
	v_and_b32_e32 v1, 32, v1
	v_bitop3_b32 v3, v0, s36, v1 bitop3:0xde
	v_bitop3_b32 v171, v0, s7, v1 bitop3:0xde
	v_cmp_lt_u32_e32 vcc, 1, v2
	v_mov_b32_e32 v1, 0x80
	v_mov_b32_e32 v4, 0x90
	v_bfe_u32 v0, v215, 4, 1
	v_cndmask_b32_e32 v187, v1, v4, vcc
	v_mov_b32_e32 v1, 0xa0
	v_mov_b32_e32 v4, 0xb0
	s_sext_i32_i8 s1, s4
	s_cmpk_lt_u32 s5, 0x100
	v_cmp_eq_u32_e64 s[4:5], 0, v0
	v_cndmask_b32_e32 v208, v1, v4, vcc
	v_lshlrev_b32_e32 v0, 2, v0
	v_mov_b32_e32 v1, v177
	v_lshl_add_u64 v[0:1], s[20:21], 0, v[0:1]
	s_mov_b64 s[6:7], 0x1c0000
	v_lshl_add_u64 v[188:189], v[0:1], 0, s[6:7]
	v_lshlrev_b32_e32 v0, 16, v12
	v_and_b32_e32 v0, 0xfffe0000, v0
	v_lshl_add_u32 v0, v11, 13, v0
	v_and_b32_e32 v1, 1, v12
	v_lshl_or_b32 v0, v1, 6, v0
	v_lshl_add_u32 v190, v13, 1, v0
	v_lshlrev_b32_e32 v0, 16, v8
	v_and_b32_e32 v0, 0xfffe0000, v0
	v_lshl_add_u32 v0, v9, 13, v0
	v_and_b32_e32 v1, 1, v8
	s_waitcnt vmcnt(6)
	s_mov_b32 s99, 0x7fff0000
	v_lshl_or_b32 v0, v1, 6, v0
	v_readlane_b32 s61, v251, 2
	s_cselect_b64 s[34:35], -1, 0
	v_lshl_add_u32 v192, v10, 1, v0
	s_add_i32 s59, 0, 0x10000
	s_add_i32 s60, 0, 0x14000
	v_mbcnt_lo_u32_b32 v0, -1, 0
	v_cndmask_b32_e64 v180, 0, 1, vcc
	v_mov_b32_e32 v181, s56
	v_cndmask_b32_e64 v182, 2, 3, vcc
	v_cndmask_b32_e64 v183, 0, 16, vcc
	v_cndmask_b32_e64 v184, 4, 5, vcc
	v_cndmask_b32_e64 v185, 32, 48, vcc
	v_cndmask_b32_e64 v186, 6, 7, vcc
	v_lshl_or_b32 v209, v2, 3, s38
	v_mov_b32_e32 v191, v177
	v_mov_b32_e32 v193, v177
	v_mov_b64_e32 v[194:195], 0x200
	v_mov_b64_e32 v[196:197], 0x1ff
	v_add_u32_e32 v210, s59, v171
	v_add_u32_e32 v211, s60, v171
	v_add_u32_e32 v212, 0, v3
	v_mbcnt_hi_u32_b32 v213, -1, v0
	s_mov_b32 s36, 0x3a800000
	s_mov_b32 s61, 0xf800000
	v_mov_b32_e32 v214, 0x260
	s_mov_b32 s38, 0x3fb504f3
	v_readlane_b32 s62, v251, 3
	v_readlane_b32 s63, v251, 4
	v_readlane_b32 s64, v251, 5
	v_readlane_b32 s65, v251, 6
	v_readlane_b32 s66, v251, 7
	v_readlane_b32 s67, v251, 8
	v_readlane_b32 s68, v251, 9
	v_readlane_b32 s69, v251, 10
	v_readlane_b32 s70, v251, 11
	v_readlane_b32 s71, v251, 12
	v_readlane_b32 s72, v251, 13
	v_readlane_b32 s73, v251, 14
	s_barrier
	s_branch .LBB0_1149

.LBB0_1155:
	s_ashr_i32 s43, s42, 31
	s_lshl_b64 s[44:45], s[42:43], 21
	s_add_u32 s44, s24, s44
	s_addc_u32 s45, s25, s45
	s_and_b64 s[46:47], s[6:7], exec
	s_cselect_b32 s43, s45, s49
	s_cselect_b32 s62, s44, s48
	s_ashr_i32 s41, s40, 31
	s_lshl_b64 s[46:47], s[40:41], 21
	s_add_u32 s46, s33, s46
	s_addc_u32 s47, s37, s47
	s_and_b64 s[50:51], s[6:7], exec
	s_cselect_b32 s41, s47, s3
	s_cselect_b32 s63, s46, s2
	s_add_u32 s48, s48, 0x100080
	s_addc_u32 s49, s49, 0
	s_add_u32 s64, s2, 0x100
	v_mov_b32_e32 v0, 0
	s_addc_u32 s65, s3, 0
	s_mov_b32 s66, -2
	v_mov_b32_e32 v1, v0
	v_mov_b32_e32 v2, v0
	v_mov_b32_e32 v3, v0
	v_mov_b32_e32 v4, v0
	v_mov_b32_e32 v5, v0
	v_mov_b32_e32 v6, v0
	v_mov_b32_e32 v7, v0
	v_mov_b32_e32 v16, v0
	v_mov_b32_e32 v17, v0
	v_mov_b32_e32 v18, v0
	v_mov_b32_e32 v19, v0
	v_mov_b32_e32 v20, v0
	v_mov_b32_e32 v21, v0
	v_mov_b32_e32 v22, v0
	v_mov_b32_e32 v23, v0
	v_mov_b32_e32 v32, v0
	v_mov_b32_e32 v33, v0
	v_mov_b32_e32 v34, v0
	v_mov_b32_e32 v35, v0
	v_mov_b32_e32 v36, v0
	v_mov_b32_e32 v37, v0
	v_mov_b32_e32 v38, v0
	v_mov_b32_e32 v39, v0
	v_mov_b32_e32 v48, v0
	v_mov_b32_e32 v49, v0
	v_mov_b32_e32 v50, v0
	v_mov_b32_e32 v51, v0
	v_mov_b32_e32 v52, v0
	v_mov_b32_e32 v53, v0
	v_mov_b32_e32 v54, v0
	v_mov_b32_e32 v55, v0
	v_mov_b32_e32 v8, v0
	v_mov_b32_e32 v9, v0
	v_mov_b32_e32 v10, v0
	v_mov_b32_e32 v11, v0
	v_mov_b32_e32 v12, v0
	v_mov_b32_e32 v13, v0
	v_mov_b32_e32 v14, v0
	v_mov_b32_e32 v15, v0
	v_mov_b32_e32 v24, v0
	v_mov_b32_e32 v25, v0
	v_mov_b32_e32 v26, v0
	v_mov_b32_e32 v27, v0
	v_mov_b32_e32 v28, v0
	v_mov_b32_e32 v29, v0
	v_mov_b32_e32 v30, v0
	v_mov_b32_e32 v31, v0
	v_mov_b32_e32 v40, v0
	v_mov_b32_e32 v41, v0
	v_mov_b32_e32 v42, v0
	v_mov_b32_e32 v43, v0
	v_mov_b32_e32 v44, v0
	v_mov_b32_e32 v45, v0
	v_mov_b32_e32 v46, v0
	v_mov_b32_e32 v47, v0
	v_mov_b32_e32 v56, v0
	v_mov_b32_e32 v57, v0
	v_mov_b32_e32 v58, v0
	v_mov_b32_e32 v59, v0
	v_mov_b32_e32 v60, v0
	v_mov_b32_e32 v61, v0
	v_mov_b32_e32 v62, v0
	v_mov_b32_e32 v63, v0
	v_mov_b32_e32 v80, v0
	v_mov_b32_e32 v81, v0
	v_mov_b32_e32 v82, v0
	v_mov_b32_e32 v83, v0
	v_mov_b32_e32 v84, v0
	v_mov_b32_e32 v85, v0
	v_mov_b32_e32 v86, v0
	v_mov_b32_e32 v87, v0
	v_mov_b32_e32 v112, v0
	v_mov_b32_e32 v113, v0
	v_mov_b32_e32 v114, v0
	v_mov_b32_e32 v115, v0
	v_mov_b32_e32 v116, v0
	v_mov_b32_e32 v117, v0
	v_mov_b32_e32 v118, v0
	v_mov_b32_e32 v119, v0
	v_mov_b32_e32 v128, v0
	v_mov_b32_e32 v129, v0
	v_mov_b32_e32 v130, v0
	v_mov_b32_e32 v131, v0
	v_mov_b32_e32 v132, v0
	v_mov_b32_e32 v133, v0
	v_mov_b32_e32 v134, v0
	v_mov_b32_e32 v135, v0
	v_mov_b32_e32 v144, v0
	v_mov_b32_e32 v145, v0
	v_mov_b32_e32 v146, v0
	v_mov_b32_e32 v147, v0
	v_mov_b32_e32 v148, v0
	v_mov_b32_e32 v149, v0
	v_mov_b32_e32 v150, v0
	v_mov_b32_e32 v151, v0
	v_mov_b32_e32 v104, v0
	v_mov_b32_e32 v105, v0
	v_mov_b32_e32 v106, v0
	v_mov_b32_e32 v107, v0
	v_mov_b32_e32 v108, v0
	v_mov_b32_e32 v109, v0
	v_mov_b32_e32 v110, v0
	v_mov_b32_e32 v111, v0
	v_mov_b32_e32 v120, v0
	v_mov_b32_e32 v121, v0
	v_mov_b32_e32 v122, v0
	v_mov_b32_e32 v123, v0
	v_mov_b32_e32 v124, v0
	v_mov_b32_e32 v125, v0
	v_mov_b32_e32 v126, v0
	v_mov_b32_e32 v127, v0
	v_mov_b32_e32 v136, v0
	v_mov_b32_e32 v137, v0
	v_mov_b32_e32 v138, v0
	v_mov_b32_e32 v139, v0
	v_mov_b32_e32 v140, v0
	v_mov_b32_e32 v141, v0
	v_mov_b32_e32 v142, v0
	v_mov_b32_e32 v143, v0
	v_mov_b32_e32 v152, v0
	v_mov_b32_e32 v153, v0
	v_mov_b32_e32 v154, v0
	v_mov_b32_e32 v155, v0
	v_mov_b32_e32 v156, v0
	v_mov_b32_e32 v157, v0
	v_mov_b32_e32 v158, v0
	v_mov_b32_e32 v159, v0
.LBB0_1156:
	ds_read_b128 v[64:67], v210
	ds_read_b128 v[68:71], v210 offset:1024
	ds_read_b128 v[72:75], v210 offset:2048
	ds_read_b128 v[76:79], v210 offset:3072
	ds_read_b128 v[88:91], v211
	ds_read_b128 v[92:95], v211 offset:1024
	ds_read_b128 v[96:99], v211 offset:2048
	ds_read_b128 v[100:103], v211 offset:3072
	s_add_u32 s2, s48, 0xfff00080
	s_addc_u32 s3, s49, -1
	s_cmp_eq_u32 s66, 60
	s_cselect_b32 s51, s43, s3
	s_cselect_b32 s50, s62, s2
	s_cselect_b32 s3, s41, s65
	s_cselect_b32 s2, s63, s64
	v_lshl_add_u64 v[206:207], s[48:49], 0, v[190:191]
	s_add_i32 m0, s52, 0xc000
	ds_read_b128 v[160:163], v212
	ds_read_b128 v[164:167], v212 offset:1024
	ds_read_b128 v[198:201], v212 offset:2048
	ds_read_b128 v[202:205], v212 offset:3072
	ds_read_b128 v[216:219], v212 offset:4096
	ds_read_b128 v[220:223], v212 offset:5120
	ds_read_b128 v[224:227], v212 offset:6144
	ds_read_b128 v[228:231], v212 offset:7168
	global_load_lds_dwordx4 v[206:207], off
	v_lshl_add_u64 v[206:207], s[48:49], 0, v[192:193]
	s_add_i32 m0, s52, 0xe000
	s_nop 0
	global_load_lds_dwordx4 v[206:207], off
	s_cmp_eq_u32 s66, s99
	s_cbranch_scc1 .Ls1a_P13_0
	s_waitcnt vmcnt(8)
	s_branch .Ls1b_P13_0

.Ls1b_P13_0:
	s_waitcnt lgkmcnt(0)
	s_barrier
	s_setprio 1
	s_waitcnt lgkmcnt(0)
	v_mfma_f32_16x16x32_bf16 v[156:159], v[64:67], v[160:163], v[156:159]
	v_mfma_f32_16x16x32_bf16 v[152:155], v[72:75], v[160:163], v[152:155]
	v_mfma_f32_16x16x32_bf16 v[140:143], v[64:67], v[198:201], v[140:143]
	v_mfma_f32_16x16x32_bf16 v[136:139], v[72:75], v[198:201], v[136:139]
	v_mfma_f32_16x16x32_bf16 v[124:127], v[64:67], v[216:219], v[124:127]
	v_mfma_f32_16x16x32_bf16 v[120:123], v[72:75], v[216:219], v[120:123]
	v_mfma_f32_16x16x32_bf16 v[108:111], v[64:67], v[224:227], v[108:111]
	v_mfma_f32_16x16x32_bf16 v[104:107], v[72:75], v[224:227], v[104:107]
	v_mfma_f32_16x16x32_bf16 v[156:159], v[68:71], v[164:167], v[156:159]
	v_mfma_f32_16x16x32_bf16 v[152:155], v[76:79], v[164:167], v[152:155]
	v_mfma_f32_16x16x32_bf16 v[140:143], v[68:71], v[202:205], v[140:143]
	v_mfma_f32_16x16x32_bf16 v[136:139], v[76:79], v[202:205], v[136:139]
	v_mfma_f32_16x16x32_bf16 v[124:127], v[68:71], v[220:223], v[124:127]
	v_mfma_f32_16x16x32_bf16 v[120:123], v[76:79], v[220:223], v[120:123]
	v_mfma_f32_16x16x32_bf16 v[108:111], v[68:71], v[228:231], v[108:111]
	v_mfma_f32_16x16x32_bf16 v[104:107], v[76:79], v[228:231], v[104:107]
	s_setprio 0
	s_setprio 1
	v_mfma_f32_16x16x32_bf16 v[148:151], v[88:91], v[160:163], v[148:151]
	v_mfma_f32_16x16x32_bf16 v[144:147], v[96:99], v[160:163], v[144:147]
	v_mfma_f32_16x16x32_bf16 v[132:135], v[88:91], v[198:201], v[132:135]
	v_mfma_f32_16x16x32_bf16 v[128:131], v[96:99], v[198:201], v[128:131]
	v_mfma_f32_16x16x32_bf16 v[116:119], v[88:91], v[216:219], v[116:119]
	v_mfma_f32_16x16x32_bf16 v[112:115], v[96:99], v[216:219], v[112:115]
	v_mfma_f32_16x16x32_bf16 v[84:87], v[88:91], v[224:227], v[84:87]
	v_mfma_f32_16x16x32_bf16 v[80:83], v[96:99], v[224:227], v[80:83]
	v_mfma_f32_16x16x32_bf16 v[148:151], v[92:95], v[164:167], v[148:151]
	v_mfma_f32_16x16x32_bf16 v[144:147], v[100:103], v[164:167], v[144:147]
	v_mfma_f32_16x16x32_bf16 v[132:135], v[92:95], v[202:205], v[132:135]
	v_mfma_f32_16x16x32_bf16 v[128:131], v[100:103], v[202:205], v[128:131]
	v_mfma_f32_16x16x32_bf16 v[116:119], v[92:95], v[220:223], v[116:119]
	v_mfma_f32_16x16x32_bf16 v[112:115], v[100:103], v[220:223], v[112:115]
	v_mfma_f32_16x16x32_bf16 v[84:87], v[92:95], v[228:231], v[84:87]
	v_mfma_f32_16x16x32_bf16 v[80:83], v[100:103], v[228:231], v[80:83]
	s_setprio 0
	s_barrier
	s_add_i32 s67, s59, s39
	v_lshl_add_u64 v[206:207], s[2:3], 0, v[176:177]
	s_mov_b32 m0, s67
	ds_read_b128 v[160:163], v212 offset:16384
	ds_read_b128 v[164:167], v212 offset:17408
	ds_read_b128 v[198:201], v212 offset:18432
	ds_read_b128 v[202:205], v212 offset:19456
	ds_read_b128 v[216:219], v212 offset:20480
	ds_read_b128 v[220:223], v212 offset:21504
	ds_read_b128 v[224:227], v212 offset:22528
	ds_read_b128 v[228:231], v212 offset:23552
	global_load_lds_dwordx4 v[206:207], off
	s_add_i32 m0, s67, 0x2000
	s_add_u32 s68, s2, 0x100000
	v_lshl_add_u64 v[232:233], s[2:3], 0, v[172:173]
	s_addc_u32 s69, s3, 0
	s_add_i32 s67, s60, s39
	global_load_lds_dwordx4 v[232:233], off
	v_lshl_add_u64 v[234:235], s[68:69], 0, v[176:177]
	s_mov_b32 m0, s67
	v_lshl_add_u64 v[236:237], s[50:51], 0, v[174:175]
	global_load_lds_dwordx4 v[234:235], off
	v_lshl_add_u64 v[234:235], s[68:69], 0, v[172:173]
	s_add_i32 m0, s67, 0x2000
	s_nop 0
	global_load_lds_dwordx4 v[234:235], off
	v_lshl_add_u64 v[234:235], s[50:51], 0, v[178:179]
	s_mov_b32 m0, s52
	s_nop 0
	global_load_lds_dwordx4 v[234:235], off
	s_mov_b32 m0, s53
	s_nop 0
	global_load_lds_dwordx4 v[236:237], off
	s_cmp_eq_u32 s66, s99
	s_cbranch_scc1 .Ls1a_P13_1
	s_waitcnt vmcnt(8)
	s_branch .Ls1b_P13_1

.Ls1b_P13_1:
	s_waitcnt lgkmcnt(0)
	s_barrier
	s_setprio 1
	s_waitcnt lgkmcnt(0)
	v_mfma_f32_16x16x32_bf16 v[60:63], v[64:67], v[160:163], v[60:63]
	v_mfma_f32_16x16x32_bf16 v[56:59], v[72:75], v[160:163], v[56:59]
	v_mfma_f32_16x16x32_bf16 v[44:47], v[64:67], v[198:201], v[44:47]
	v_mfma_f32_16x16x32_bf16 v[40:43], v[72:75], v[198:201], v[40:43]
	v_mfma_f32_16x16x32_bf16 v[28:31], v[64:67], v[216:219], v[28:31]
	v_mfma_f32_16x16x32_bf16 v[24:27], v[72:75], v[216:219], v[24:27]
	v_mfma_f32_16x16x32_bf16 v[12:15], v[64:67], v[224:227], v[12:15]
	v_mfma_f32_16x16x32_bf16 v[8:11], v[72:75], v[224:227], v[8:11]
	v_mfma_f32_16x16x32_bf16 v[60:63], v[68:71], v[164:167], v[60:63]
	v_mfma_f32_16x16x32_bf16 v[56:59], v[76:79], v[164:167], v[56:59]
	v_mfma_f32_16x16x32_bf16 v[44:47], v[68:71], v[202:205], v[44:47]
	v_mfma_f32_16x16x32_bf16 v[40:43], v[76:79], v[202:205], v[40:43]
	v_mfma_f32_16x16x32_bf16 v[28:31], v[68:71], v[220:223], v[28:31]
	v_mfma_f32_16x16x32_bf16 v[24:27], v[76:79], v[220:223], v[24:27]
	v_mfma_f32_16x16x32_bf16 v[12:15], v[68:71], v[228:231], v[12:15]
	v_mfma_f32_16x16x32_bf16 v[8:11], v[76:79], v[228:231], v[8:11]
	s_setprio 0
	s_setprio 1
	v_mfma_f32_16x16x32_bf16 v[52:55], v[88:91], v[160:163], v[52:55]
	v_mfma_f32_16x16x32_bf16 v[48:51], v[96:99], v[160:163], v[48:51]
	v_mfma_f32_16x16x32_bf16 v[36:39], v[88:91], v[198:201], v[36:39]
	v_mfma_f32_16x16x32_bf16 v[32:35], v[96:99], v[198:201], v[32:35]
	v_mfma_f32_16x16x32_bf16 v[20:23], v[88:91], v[216:219], v[20:23]
	v_mfma_f32_16x16x32_bf16 v[16:19], v[96:99], v[216:219], v[16:19]
	v_mfma_f32_16x16x32_bf16 v[4:7], v[88:91], v[224:227], v[4:7]
	v_mfma_f32_16x16x32_bf16 v[0:3], v[96:99], v[224:227], v[0:3]
	v_mfma_f32_16x16x32_bf16 v[52:55], v[92:95], v[164:167], v[52:55]
	v_mfma_f32_16x16x32_bf16 v[48:51], v[100:103], v[164:167], v[48:51]
	v_mfma_f32_16x16x32_bf16 v[36:39], v[92:95], v[202:205], v[36:39]
	v_mfma_f32_16x16x32_bf16 v[32:35], v[100:103], v[202:205], v[32:35]
	v_mfma_f32_16x16x32_bf16 v[20:23], v[92:95], v[220:223], v[20:23]
	v_mfma_f32_16x16x32_bf16 v[16:19], v[100:103], v[220:223], v[16:19]
	v_mfma_f32_16x16x32_bf16 v[4:7], v[92:95], v[228:231], v[4:7]
	v_mfma_f32_16x16x32_bf16 v[0:3], v[100:103], v[228:231], v[0:3]
	s_setprio 0
	s_barrier
	s_add_i32 s67, 0, 0x18000
	s_add_i32 s68, 0, 0x1c000
	v_add_u32_e32 v76, s67, v171
	v_add_u32_e32 v100, s68, v171
	ds_read_b128 v[64:67], v76
	ds_read_b128 v[68:71], v76 offset:1024
	ds_read_b128 v[72:75], v76 offset:2048
	ds_read_b128 v[76:79], v76 offset:3072
	ds_read_b128 v[88:91], v100
	ds_read_b128 v[92:95], v100 offset:1024
	ds_read_b128 v[96:99], v100 offset:2048
	ds_read_b128 v[100:103], v100 offset:3072
	s_add_u32 s50, s50, 0x100000
	s_addc_u32 s51, s51, 0
	s_mov_b32 m0, s54
	v_lshl_add_u64 v[238:239], s[50:51], 0, v[178:179]
	ds_read_b128 v[160:163], v212 offset:32768
	ds_read_b128 v[164:167], v212 offset:33792
	ds_read_b128 v[198:201], v212 offset:34816
	ds_read_b128 v[202:205], v212 offset:35840
	ds_read_b128 v[216:219], v212 offset:36864
	ds_read_b128 v[220:223], v212 offset:37888
	ds_read_b128 v[224:227], v212 offset:38912
	ds_read_b128 v[228:231], v212 offset:39936
	global_load_lds_dwordx4 v[238:239], off
	v_lshl_add_u64 v[238:239], s[50:51], 0, v[174:175]
	s_mov_b32 m0, s55
	s_nop 0
	global_load_lds_dwordx4 v[238:239], off
	s_waitcnt vmcnt(8)
	s_waitcnt lgkmcnt(0)
	s_barrier
	s_setprio 1
	s_waitcnt lgkmcnt(0)
	v_mfma_f32_16x16x32_bf16 v[156:159], v[64:67], v[160:163], v[156:159]
	v_mfma_f32_16x16x32_bf16 v[152:155], v[72:75], v[160:163], v[152:155]
	v_mfma_f32_16x16x32_bf16 v[140:143], v[64:67], v[198:201], v[140:143]
	v_mfma_f32_16x16x32_bf16 v[136:139], v[72:75], v[198:201], v[136:139]
	v_mfma_f32_16x16x32_bf16 v[124:127], v[64:67], v[216:219], v[124:127]
	v_mfma_f32_16x16x32_bf16 v[120:123], v[72:75], v[216:219], v[120:123]
	v_mfma_f32_16x16x32_bf16 v[108:111], v[64:67], v[224:227], v[108:111]
	v_mfma_f32_16x16x32_bf16 v[104:107], v[72:75], v[224:227], v[104:107]
	v_mfma_f32_16x16x32_bf16 v[156:159], v[68:71], v[164:167], v[156:159]
	v_mfma_f32_16x16x32_bf16 v[152:155], v[76:79], v[164:167], v[152:155]
	v_mfma_f32_16x16x32_bf16 v[140:143], v[68:71], v[202:205], v[140:143]
	v_mfma_f32_16x16x32_bf16 v[136:139], v[76:79], v[202:205], v[136:139]
	v_mfma_f32_16x16x32_bf16 v[124:127], v[68:71], v[220:223], v[124:127]
	v_mfma_f32_16x16x32_bf16 v[120:123], v[76:79], v[220:223], v[120:123]
	v_mfma_f32_16x16x32_bf16 v[108:111], v[68:71], v[228:231], v[108:111]
	v_mfma_f32_16x16x32_bf16 v[104:107], v[76:79], v[228:231], v[104:107]
	s_setprio 0
	s_setprio 1
	v_mfma_f32_16x16x32_bf16 v[148:151], v[88:91], v[160:163], v[148:151]
	v_mfma_f32_16x16x32_bf16 v[144:147], v[96:99], v[160:163], v[144:147]
	v_mfma_f32_16x16x32_bf16 v[132:135], v[88:91], v[198:201], v[132:135]
	v_mfma_f32_16x16x32_bf16 v[128:131], v[96:99], v[198:201], v[128:131]
	v_mfma_f32_16x16x32_bf16 v[116:119], v[88:91], v[216:219], v[116:119]
	v_mfma_f32_16x16x32_bf16 v[112:115], v[96:99], v[216:219], v[112:115]
	v_mfma_f32_16x16x32_bf16 v[84:87], v[88:91], v[224:227], v[84:87]
	v_mfma_f32_16x16x32_bf16 v[80:83], v[96:99], v[224:227], v[80:83]
	v_mfma_f32_16x16x32_bf16 v[148:151], v[92:95], v[164:167], v[148:151]
	v_mfma_f32_16x16x32_bf16 v[144:147], v[100:103], v[164:167], v[144:147]
	v_mfma_f32_16x16x32_bf16 v[132:135], v[92:95], v[202:205], v[132:135]
	v_mfma_f32_16x16x32_bf16 v[128:131], v[100:103], v[202:205], v[128:131]
	v_mfma_f32_16x16x32_bf16 v[116:119], v[92:95], v[220:223], v[116:119]
	v_mfma_f32_16x16x32_bf16 v[112:115], v[100:103], v[220:223], v[112:115]
	v_mfma_f32_16x16x32_bf16 v[84:87], v[92:95], v[228:231], v[84:87]
	v_mfma_f32_16x16x32_bf16 v[80:83], v[100:103], v[228:231], v[80:83]
	s_setprio 0
	s_barrier
	s_add_i32 s50, s67, s39
	v_lshl_add_u64 v[206:207], v[206:207], 0, s[30:31]
	s_mov_b32 m0, s50
	ds_read_b128 v[160:163], v212 offset:49152
	ds_read_b128 v[164:167], v212 offset:50176
	ds_read_b128 v[198:201], v212 offset:51200
	ds_read_b128 v[202:205], v212 offset:52224
	ds_read_b128 v[216:219], v212 offset:53248
	ds_read_b128 v[220:223], v212 offset:54272
	ds_read_b128 v[224:227], v212 offset:55296
	ds_read_b128 v[228:231], v212 offset:56320
	global_load_lds_dwordx4 v[206:207], off
	s_add_i32 m0, s50, 0x2000
	s_add_u32 s2, s2, 0x100080
	v_lshl_add_u64 v[206:207], v[232:233], 0, s[30:31]
	s_addc_u32 s3, s3, 0
	s_add_i32 s50, s68, s39
	global_load_lds_dwordx4 v[206:207], off
	v_lshl_add_u64 v[206:207], s[2:3], 0, v[176:177]
	s_mov_b32 m0, s50
	s_nop 0
	global_load_lds_dwordx4 v[206:207], off
	v_lshl_add_u64 v[206:207], s[2:3], 0, v[172:173]
	s_add_i32 m0, s50, 0x2000
	s_nop 0
	global_load_lds_dwordx4 v[206:207], off
	v_lshl_add_u64 v[206:207], v[234:235], 0, s[30:31]
	s_mov_b32 m0, s57
	s_nop 0
	global_load_lds_dwordx4 v[206:207], off
	v_lshl_add_u64 v[206:207], v[236:237], 0, s[30:31]
	s_mov_b32 m0, s58
	s_nop 0
	global_load_lds_dwordx4 v[206:207], off
	s_waitcnt vmcnt(8)
	s_waitcnt lgkmcnt(0)
	s_barrier
	s_setprio 1
	s_waitcnt lgkmcnt(0)
	v_mfma_f32_16x16x32_bf16 v[60:63], v[64:67], v[160:163], v[60:63]
	v_mfma_f32_16x16x32_bf16 v[56:59], v[72:75], v[160:163], v[56:59]
	v_mfma_f32_16x16x32_bf16 v[44:47], v[64:67], v[198:201], v[44:47]
	v_mfma_f32_16x16x32_bf16 v[40:43], v[72:75], v[198:201], v[40:43]
	v_mfma_f32_16x16x32_bf16 v[28:31], v[64:67], v[216:219], v[28:31]
	v_mfma_f32_16x16x32_bf16 v[24:27], v[72:75], v[216:219], v[24:27]
	v_mfma_f32_16x16x32_bf16 v[12:15], v[64:67], v[224:227], v[12:15]
	v_mfma_f32_16x16x32_bf16 v[8:11], v[72:75], v[224:227], v[8:11]
	v_mfma_f32_16x16x32_bf16 v[60:63], v[68:71], v[164:167], v[60:63]
	v_mfma_f32_16x16x32_bf16 v[56:59], v[76:79], v[164:167], v[56:59]
	v_mfma_f32_16x16x32_bf16 v[44:47], v[68:71], v[202:205], v[44:47]
	v_mfma_f32_16x16x32_bf16 v[40:43], v[76:79], v[202:205], v[40:43]
	v_mfma_f32_16x16x32_bf16 v[28:31], v[68:71], v[220:223], v[28:31]
	v_mfma_f32_16x16x32_bf16 v[24:27], v[76:79], v[220:223], v[24:27]
	v_mfma_f32_16x16x32_bf16 v[12:15], v[68:71], v[228:231], v[12:15]
	v_mfma_f32_16x16x32_bf16 v[8:11], v[76:79], v[228:231], v[8:11]
	s_setprio 0
	s_setprio 1
	v_mfma_f32_16x16x32_bf16 v[52:55], v[88:91], v[160:163], v[52:55]
	v_mfma_f32_16x16x32_bf16 v[48:51], v[96:99], v[160:163], v[48:51]
	v_mfma_f32_16x16x32_bf16 v[36:39], v[88:91], v[198:201], v[36:39]
	v_mfma_f32_16x16x32_bf16 v[32:35], v[96:99], v[198:201], v[32:35]
	v_mfma_f32_16x16x32_bf16 v[20:23], v[88:91], v[216:219], v[20:23]
	v_mfma_f32_16x16x32_bf16 v[16:19], v[96:99], v[216:219], v[16:19]
	v_mfma_f32_16x16x32_bf16 v[4:7], v[88:91], v[224:227], v[4:7]
	v_mfma_f32_16x16x32_bf16 v[0:3], v[96:99], v[224:227], v[0:3]
	v_mfma_f32_16x16x32_bf16 v[52:55], v[92:95], v[164:167], v[52:55]
	v_mfma_f32_16x16x32_bf16 v[48:51], v[100:103], v[164:167], v[48:51]
	v_mfma_f32_16x16x32_bf16 v[36:39], v[92:95], v[202:205], v[36:39]
	v_mfma_f32_16x16x32_bf16 v[32:35], v[100:103], v[202:205], v[32:35]
	v_mfma_f32_16x16x32_bf16 v[20:23], v[92:95], v[220:223], v[20:23]
	v_mfma_f32_16x16x32_bf16 v[16:19], v[100:103], v[220:223], v[16:19]
	v_mfma_f32_16x16x32_bf16 v[4:7], v[92:95], v[228:231], v[4:7]
	v_mfma_f32_16x16x32_bf16 v[0:3], v[100:103], v[228:231], v[0:3]
	s_setprio 0
	s_barrier
	s_add_i32 s66, s66, 2
	s_add_u32 s48, s48, 0x100
	s_addc_u32 s49, s49, 0
	s_add_u32 s64, s64, 0x100
	s_addc_u32 s65, s65, 0
	s_cmp_gt_u32 s66, 61
	s_cbranch_scc0 .LBB0_1156
	s_mov_b32 s99, -2
	s_and_b64 vcc, exec, s[34:35]
	s_cbranch_vccz .LBB0_1159
	s_barrier

	.amdhsa_kernel _Z10hybrid_fwd4Args
		.amdhsa_group_segment_fixed_size 0
		.amdhsa_private_segment_fixed_size 0
		.amdhsa_kernarg_size 368
		.amdhsa_user_sgpr_count 2
		.amdhsa_user_sgpr_dispatch_ptr 0
		.amdhsa_user_sgpr_queue_ptr 0
		.amdhsa_user_sgpr_kernarg_segment_ptr 1
		.amdhsa_user_sgpr_dispatch_id 0
		.amdhsa_user_sgpr_kernarg_preload_length 0
		.amdhsa_user_sgpr_kernarg_preload_offset 0
		.amdhsa_user_sgpr_private_segment_size 0
		.amdhsa_uses_dynamic_stack 0
		.amdhsa_enable_private_segment 0
		.amdhsa_system_sgpr_workgroup_id_x 1
		.amdhsa_system_sgpr_workgroup_id_y 0
		.amdhsa_system_sgpr_workgroup_id_z 0
		.amdhsa_system_sgpr_workgroup_info 0
		.amdhsa_system_vgpr_workitem_id 2
		.amdhsa_next_free_vgpr 252
		.amdhsa_next_free_sgpr 102
		.amdhsa_accum_offset 252
		.amdhsa_reserve_vcc 1
		.amdhsa_float_round_mode_32 0
		.amdhsa_float_round_mode_16_64 0
		.amdhsa_float_denorm_mode_32 3
		.amdhsa_float_denorm_mode_16_64 3
		.amdhsa_dx10_clamp 1
		.amdhsa_ieee_mode 1
		.amdhsa_fp16_overflow 0
		.amdhsa_tg_split 0
		.amdhsa_exception_fp_ieee_invalid_op 0
		.amdhsa_exception_fp_denorm_src 0
		.amdhsa_exception_fp_ieee_div_zero 0
		.amdhsa_exception_fp_ieee_overflow 0
		.amdhsa_exception_fp_ieee_underflow 0
		.amdhsa_exception_fp_ieee_inexact 0
		.amdhsa_exception_int_div_zero 0
	.end_amdhsa_kernel

amdhsa.kernels:
  - .agpr_count:     0
    .args:
      - .offset:         0
        .size:           112
        .value_kind:     by_value
      - .offset:         112
        .size:           4
        .value_kind:     hidden_block_count_x
      - .offset:         116
        .size:           4
        .value_kind:     hidden_block_count_y
      - .offset:         120
        .size:           4
        .value_kind:     hidden_block_count_z
      - .offset:         124
        .size:           2
        .value_kind:     hidden_group_size_x
      - .offset:         126
        .size:           2
        .value_kind:     hidden_group_size_y
      - .offset:         128
        .size:           2
        .value_kind:     hidden_group_size_z
      - .offset:         130
        .size:           2
        .value_kind:     hidden_remainder_x
      - .offset:         132
        .size:           2
        .value_kind:     hidden_remainder_y
      - .offset:         134
        .size:           2
        .value_kind:     hidden_remainder_z
      - .offset:         152
        .size:           8
        .value_kind:     hidden_global_offset_x
      - .offset:         160
        .size:           8
        .value_kind:     hidden_global_offset_y
      - .offset:         168
        .size:           8
        .value_kind:     hidden_global_offset_z
      - .offset:         176
        .size:           2
        .value_kind:     hidden_grid_dims
      - .offset:         200
        .size:           8
        .value_kind:     hidden_multigrid_sync_arg
      - .offset:         232
        .size:           4
        .value_kind:     hidden_dynamic_lds_size
    .group_segment_fixed_size: 0
    .kernarg_segment_align: 8
    .kernarg_segment_size: 368
    .language:       OpenCL C
    .language_version:
      - 2
      - 0
    .max_flat_workgroup_size: 512
    .name:           _Z10hybrid_fwd4Args
    .private_segment_fixed_size: 0
    .sgpr_count:     108
    .sgpr_spill_count: 196
    .symbol:         _Z10hybrid_fwd4Args.kd
    .uniform_work_group_size: 1
    .uses_dynamic_stack: false
    .vgpr_count:     252
    .vgpr_spill_count: 0
    .wavefront_size: 64
